# gemm K-loops: inverted priority flips (load segment prio 1, MFMA segment prio 0)
# baseline (speedup 1.0000x reference)
; #define PG8_STAGE(bufoff, gbase, voff) do { _Pragma("unroll") for (int _i = 0; _i < 2; ++_i) \
;         __builtin_amdgcn_global_load_lds((const unsigned*)((const char*)(gbase) + (voff)[_i]), (PG8_LAS unsigned*)(lds + (bufoff) + ldsw + _i * 8192), 16, 0, 0); } while (0)
; #define PG8_LDA(dst, b, h) do { _Pragma("unroll") for (int m = 0; m < 4; ++m) _Pragma("unroll") for (int k = 0; k < 2; ++k) dst[m][k] = *(const PG8_LAS bf16x8*)(lds + PG8_SA(b, h) + aoff + m * 2048 + k * 1024); } while (0)
; #define PG8_LDB(dst, b, h) do { _Pragma("unroll") for (int n = 0; n < 2; ++n) _Pragma("unroll") for (int k = 0; k < 2; ++k) dst[n][k] = *(const PG8_LAS bf16x8*)(lds + PG8_SB(b, h) + boff + n * 2048 + k * 1024); } while (0)
; #define PG8_MMA(ai, bj, At, Bt) do { __builtin_amdgcn_s_setprio(1); _Pragma("unroll") for (int m = 0; m < 4; ++m) _Pragma("unroll") for (int n = 0; n < 2; ++n) _Pragma("unroll") for (int k = 0; k < 2; ++k) \
;         acc[ai][bj][m][n] = __builtin_amdgcn_mfma_f32_16x16x32_bf16(Bt[n][k], At[m][k], acc[ai][bj][m][n], 0, 0, 0); __builtin_amdgcn_s_setprio(0); } while (0)
; template <class Epi, class Sched>
; __device__ __forceinline__ void gemm_phase(PG8_LAS unsigned char* lds, const Gemm g, const Sched& S, const Epi& E) {
;     ...
;         const char* nA = has_next ? (const char*)g.A + (size_t)nxt.pm * tstepA + (size_t)nxt.kc * cstep : cA; const char* nB = has_next ? (const char*)g.Bt + (size_t)nxt.pn * tstep + (size_t)nxt.kc * cstep : cB;
;         for (int t = 0; t < nt; t += 2) {
;             const bool last = (t == nt - 2);
;             const char* a1 = cA + (size_t)(t + 1) * kstep;
;             const char* a2 = last ? nA : cA + (size_t)(t + 2) * kstep; const char* b2 = last ? nB : cB + (size_t)(t + 2) * kstep;
;             const char* a3 = a2 + kstep; const char* b3 = b2 + kstep;
;             if (last && has_next) S.a_ready(nxt);
;             PG8_LDB(B0, 0, 0); PG8_SCHED; PG8_LDA(At, 0, 0); PG8_STAGE(PG8_SA(1, 1), a1 + hstep, voffA);
;             PG8_WAIT_L(8); PG8_BAR; PG8_WAIT_L(0); PG8_MMA(0, 0, At, B0); PG8_BAR; PG8_SCHED;
;             PG8_LDB(B1, 0, 1); PG8_STAGE(PG8_SB(0, 0), b2, voffB);
;             PG8_BAR; PG8_WAIT_L(0); PG8_MMA(0, 1, At, B1); PG8_BAR;
;             PG8_LDA(At, 0, 1); PG8_STAGE(PG8_SA(0, 0), a2, voffA);
;             PG8_BAR; PG8_WAIT_L(0); PG8_MMA(1, 0, At, B0); PG8_BAR; PG8_SCHED;
.LBB0_267:
	s_add_u32 s16, s16, 0x80
	s_addc_u32 s17, s17, 0
	s_add_u32 s24, s20, 0x100
	s_addc_u32 s25, s21, 0
	s_mov_b32 s20, 0
	s_add_i32 s42, s20, 2
	s_add_u32 s22, s16, 0x80
	s_addc_u32 s21, s17, 0
	s_add_i32 s43, 0, 0x10000
	v_add_u32_e32 v142, s43, v170
	ds_read_b128 v[130:133], v142
	ds_read_b128 v[134:137], v142 offset:1024
	ds_read_b128 v[138:141], v142 offset:2048
	ds_read_b128 v[142:145], v142 offset:3072
	s_cmp_eq_u32 s66, s20
	s_cselect_b32 s20, s2, s22
	s_cselect_b32 s21, s3, s21
	s_cselect_b32 s23, s13, s25
	s_cselect_b32 s22, s12, s24
	v_lshl_add_u64 v[168:169], s[16:17], 0, v[164:165]
	s_add_i32 m0, s36, 0xc000
	ds_read_b128 v[176:179], v172
	ds_read_b128 v[180:183], v172 offset:1024
	ds_read_b128 v[184:187], v172 offset:2048
	ds_read_b128 v[188:191], v172 offset:3072
	ds_read_b128 v[192:195], v172 offset:4096
	ds_read_b128 v[196:199], v172 offset:5120
	ds_read_b128 v[200:203], v172 offset:6144
	ds_read_b128 v[204:207], v172 offset:7168
	global_load_lds_dwordx4 v[168:169], off
	v_lshl_add_u64 v[168:169], s[16:17], 0, v[166:167]
	s_add_i32 m0, s36, 0xe000
	s_nop 0
	global_load_lds_dwordx4 v[168:169], off
	s_waitcnt lgkmcnt(8)
	s_barrier
	s_setprio 0
	s_waitcnt lgkmcnt(7)
	v_mfma_f32_16x16x32_bf16 v[126:129], v[130:133], v[176:179], 0
	v_mfma_f32_16x16x32_bf16 v[122:125], v[138:141], v[176:179], 0
	s_waitcnt lgkmcnt(5)
	v_mfma_f32_16x16x32_bf16 v[114:117], v[130:133], v[184:187], 0
	v_mfma_f32_16x16x32_bf16 v[110:113], v[138:141], v[184:187], 0
	s_waitcnt lgkmcnt(3)
	v_mfma_f32_16x16x32_bf16 v[98:101], v[130:133], v[192:195], 0
	v_mfma_f32_16x16x32_bf16 v[94:97], v[138:141], v[192:195], 0
	s_waitcnt lgkmcnt(1)
	v_mfma_f32_16x16x32_bf16 v[82:85], v[130:133], v[200:203], 0
	v_mfma_f32_16x16x32_bf16 v[78:81], v[138:141], v[200:203], 0
	v_mfma_f32_16x16x32_bf16 v[126:129], v[134:137], v[180:183], v[126:129]
	v_mfma_f32_16x16x32_bf16 v[122:125], v[142:145], v[180:183], v[122:125]
	v_mfma_f32_16x16x32_bf16 v[114:117], v[134:137], v[188:191], v[114:117]
	v_mfma_f32_16x16x32_bf16 v[110:113], v[142:145], v[188:191], v[110:113]
	v_mfma_f32_16x16x32_bf16 v[98:101], v[134:137], v[196:199], v[98:101]
	v_mfma_f32_16x16x32_bf16 v[94:97], v[142:145], v[196:199], v[94:97]
	s_waitcnt lgkmcnt(0)
	v_mfma_f32_16x16x32_bf16 v[82:85], v[134:137], v[204:207], v[82:85]
	v_mfma_f32_16x16x32_bf16 v[78:81], v[142:145], v[204:207], v[78:81]
	s_setprio 1
	s_barrier
	s_add_i32 s44, 0, 0x14000
	v_add_u32_e32 v168, s44, v170
	s_add_i32 s43, s43, s35
	ds_read_b128 v[208:211], v168
	ds_read_b128 v[212:215], v168 offset:1024
	ds_read_b128 v[216:219], v168 offset:2048
	ds_read_b128 v[234:237], v168 offset:3072
	v_lshl_add_u64 v[168:169], s[22:23], 0, v[48:49]
	s_mov_b32 m0, s43
	v_lshl_add_u64 v[224:225], s[22:23], 0, v[146:147]
	global_load_lds_dwordx4 v[168:169], off
	s_add_i32 m0, s43, 0x2000
	s_nop 0
	global_load_lds_dwordx4 v[224:225], off
	s_barrier
	s_setprio 0
	s_waitcnt lgkmcnt(3)
	v_mfma_f32_16x16x32_bf16 v[118:121], v[208:211], v[176:179], 0
	s_waitcnt lgkmcnt(1)
	v_mfma_f32_16x16x32_bf16 v[106:109], v[216:219], v[176:179], 0
	v_mfma_f32_16x16x32_bf16 v[102:105], v[208:211], v[184:187], 0
	v_mfma_f32_16x16x32_bf16 v[90:93], v[216:219], v[184:187], 0
	v_mfma_f32_16x16x32_bf16 v[86:89], v[208:211], v[192:195], 0
	v_mfma_f32_16x16x32_bf16 v[74:77], v[216:219], v[192:195], 0
	v_mfma_f32_16x16x32_bf16 v[70:73], v[208:211], v[200:203], 0
	v_mfma_f32_16x16x32_bf16 v[66:69], v[216:219], v[200:203], 0
	v_mfma_f32_16x16x32_bf16 v[118:121], v[212:215], v[180:183], v[118:121]
	s_waitcnt lgkmcnt(0)
	v_mfma_f32_16x16x32_bf16 v[106:109], v[234:237], v[180:183], v[106:109]
	v_mfma_f32_16x16x32_bf16 v[102:105], v[212:215], v[188:191], v[102:105]
	v_mfma_f32_16x16x32_bf16 v[90:93], v[234:237], v[188:191], v[90:93]
	v_mfma_f32_16x16x32_bf16 v[86:89], v[212:215], v[196:199], v[86:89]
	v_mfma_f32_16x16x32_bf16 v[74:77], v[234:237], v[196:199], v[74:77]
	v_mfma_f32_16x16x32_bf16 v[70:73], v[212:215], v[204:207], v[70:73]
	v_mfma_f32_16x16x32_bf16 v[66:69], v[234:237], v[204:207], v[66:69]
	s_setprio 1
	s_mov_b32 m0, s36
	v_lshl_add_u64 v[228:229], s[20:21], 0, v[48:49]
	s_barrier
	ds_read_b128 v[176:179], v172 offset:16384
	ds_read_b128 v[180:183], v172 offset:17408
	ds_read_b128 v[184:187], v172 offset:18432
	ds_read_b128 v[188:191], v172 offset:19456
	ds_read_b128 v[192:195], v172 offset:20480
	ds_read_b128 v[196:199], v172 offset:21504
	ds_read_b128 v[200:203], v172 offset:22528
	ds_read_b128 v[204:207], v172 offset:23552
	global_load_lds_dwordx4 v[228:229], off
	v_lshl_add_u64 v[238:239], s[20:21], 0, v[146:147]
	s_mov_b32 m0, s37
	s_nop 0
	global_load_lds_dwordx4 v[238:239], off
	s_barrier
	s_setprio 0
	s_waitcnt lgkmcnt(7)
	v_mfma_f32_16x16x32_bf16 v[62:65], v[130:133], v[176:179], 0
	v_mfma_f32_16x16x32_bf16 v[58:61], v[138:141], v[176:179], 0
	s_waitcnt lgkmcnt(5)
	v_mfma_f32_16x16x32_bf16 v[50:53], v[130:133], v[184:187], 0
	v_mfma_f32_16x16x32_bf16 v[44:47], v[138:141], v[184:187], 0
	s_waitcnt lgkmcnt(3)
	v_mfma_f32_16x16x32_bf16 v[32:35], v[130:133], v[192:195], 0
	v_mfma_f32_16x16x32_bf16 v[28:31], v[138:141], v[192:195], 0
	s_waitcnt lgkmcnt(1)
	v_mfma_f32_16x16x32_bf16 v[16:19], v[130:133], v[200:203], 0
	v_mfma_f32_16x16x32_bf16 v[12:15], v[138:141], v[200:203], 0
	v_mfma_f32_16x16x32_bf16 v[62:65], v[134:137], v[180:183], v[62:65]
	v_mfma_f32_16x16x32_bf16 v[58:61], v[142:145], v[180:183], v[58:61]
	v_mfma_f32_16x16x32_bf16 v[50:53], v[134:137], v[188:191], v[50:53]
	v_mfma_f32_16x16x32_bf16 v[44:47], v[142:145], v[188:191], v[44:47]
	v_mfma_f32_16x16x32_bf16 v[32:35], v[134:137], v[196:199], v[32:35]
	v_mfma_f32_16x16x32_bf16 v[28:31], v[142:145], v[196:199], v[28:31]
	s_waitcnt lgkmcnt(0)
	v_mfma_f32_16x16x32_bf16 v[16:19], v[134:137], v[204:207], v[16:19]
	v_mfma_f32_16x16x32_bf16 v[12:15], v[142:145], v[204:207], v[12:15]
	s_setprio 1
	s_barrier
; #define PG8_STAGE(bufoff, gbase, voff) do { _Pragma("unroll") for (int _i = 0; _i < 2; ++_i) \
;         __builtin_amdgcn_global_load_lds((const unsigned*)((const char*)(gbase) + (voff)[_i]), (PG8_LAS unsigned*)(lds + (bufoff) + ldsw + _i * 8192), 16, 0, 0); } while (0)
; #define PG8_LDA(dst, b, h) do { _Pragma("unroll") for (int m = 0; m < 4; ++m) _Pragma("unroll") for (int k = 0; k < 2; ++k) dst[m][k] = *(const PG8_LAS bf16x8*)(lds + PG8_SA(b, h) + aoff + m * 2048 + k * 1024); } while (0)
; #define PG8_LDB(dst, b, h) do { _Pragma("unroll") for (int n = 0; n < 2; ++n) _Pragma("unroll") for (int k = 0; k < 2; ++k) dst[n][k] = *(const PG8_LAS bf16x8*)(lds + PG8_SB(b, h) + boff + n * 2048 + k * 1024); } while (0)
; #define PG8_MMA(ai, bj, At, Bt) do { __builtin_amdgcn_s_setprio(1); _Pragma("unroll") for (int m = 0; m < 4; ++m) _Pragma("unroll") for (int n = 0; n < 2; ++n) _Pragma("unroll") for (int k = 0; k < 2; ++k) \
;         acc[ai][bj][m][n] = __builtin_amdgcn_mfma_f32_16x16x32_bf16(Bt[n][k], At[m][k], acc[ai][bj][m][n], 0, 0, 0); __builtin_amdgcn_s_setprio(0); } while (0)
; #define PG8_WAIT_V(n) asm volatile("s_waitcnt vmcnt(" #n ")" ::: "memory")
; #define PG8_WAIT_L(n) asm volatile("s_waitcnt lgkmcnt(" #n ")" ::: "memory")
; #define PG8_BAR __builtin_amdgcn_s_barrier()
; #define PG8_SCHED __builtin_amdgcn_sched_barrier(0)
; template <class Epi, class Sched>
; __device__ __forceinline__ void gemm_phase(PG8_LAS unsigned char* lds, const Gemm g, const Sched& S, const Epi& E) {
;     ...
;             PG8_STAGE(PG8_SB(0, 1), b2 + hstep, voffB);
;             PG8_WAIT_V(6); PG8_BAR; PG8_MMA(1, 1, At, B1); PG8_BAR;
;             PG8_LDB(B0, 1, 0); PG8_SCHED; PG8_LDA(At, 1, 0); PG8_STAGE(PG8_SA(0, 1), a2 + hstep, voffA);
;             PG8_WAIT_L(8); PG8_BAR; PG8_WAIT_L(0); PG8_MMA(0, 0, At, B0); PG8_BAR; PG8_SCHED;
;             PG8_LDB(B1, 1, 1); PG8_STAGE(PG8_SB(1, 0), b3, voffB);
;             PG8_BAR; PG8_WAIT_L(0); PG8_MMA(0, 1, At, B1); PG8_BAR;
;             PG8_LDA(At, 1, 1); PG8_STAGE(PG8_SA(1, 0), a3, voffA);
	s_add_u32 s22, s22, s10
	s_addc_u32 s23, s23, 0
	s_add_i32 s43, s44, s35
	v_lshl_add_u64 v[240:241], s[22:23], 0, v[48:49]
	s_mov_b32 m0, s43
	v_lshl_add_u64 v[242:243], s[22:23], 0, v[146:147]
	global_load_lds_dwordx4 v[240:241], off
	s_add_i32 m0, s43, 0x2000
	s_nop 0
	global_load_lds_dwordx4 v[242:243], off
	s_waitcnt vmcnt(6)
	s_barrier
	s_setprio 0
	v_mfma_f32_16x16x32_bf16 v[54:57], v[208:211], v[176:179], 0
	v_mfma_f32_16x16x32_bf16 v[40:43], v[216:219], v[176:179], 0
	v_mfma_f32_16x16x32_bf16 v[36:39], v[208:211], v[184:187], 0
	v_mfma_f32_16x16x32_bf16 v[24:27], v[216:219], v[184:187], 0
	v_mfma_f32_16x16x32_bf16 v[20:23], v[208:211], v[192:195], 0
	v_mfma_f32_16x16x32_bf16 v[8:11], v[216:219], v[192:195], 0
	v_mfma_f32_16x16x32_bf16 v[4:7], v[208:211], v[200:203], 0
	v_mfma_f32_16x16x32_bf16 v[0:3], v[216:219], v[200:203], 0
	v_mfma_f32_16x16x32_bf16 v[54:57], v[212:215], v[180:183], v[54:57]
	v_mfma_f32_16x16x32_bf16 v[40:43], v[234:237], v[180:183], v[40:43]
	v_mfma_f32_16x16x32_bf16 v[36:39], v[212:215], v[188:191], v[36:39]
	v_mfma_f32_16x16x32_bf16 v[24:27], v[234:237], v[188:191], v[24:27]
	v_mfma_f32_16x16x32_bf16 v[20:23], v[212:215], v[196:199], v[20:23]
	v_mfma_f32_16x16x32_bf16 v[8:11], v[234:237], v[196:199], v[8:11]
	v_mfma_f32_16x16x32_bf16 v[4:7], v[212:215], v[204:207], v[4:7]
	v_mfma_f32_16x16x32_bf16 v[0:3], v[234:237], v[204:207], v[0:3]
	s_setprio 1
	s_add_i32 s22, 0, 0x18000
	v_add_u32_e32 v142, s22, v170
	s_barrier
	ds_read_b128 v[130:133], v142
	ds_read_b128 v[134:137], v142 offset:1024
	ds_read_b128 v[138:141], v142 offset:2048
	ds_read_b128 v[142:145], v142 offset:3072
	s_add_u32 s20, s20, s10
	s_addc_u32 s21, s21, 0
	s_mov_b32 m0, s38
	v_lshl_add_u64 v[208:209], s[20:21], 0, v[48:49]
	ds_read_b128 v[176:179], v172 offset:32768
	ds_read_b128 v[180:183], v172 offset:33792
	ds_read_b128 v[184:187], v172 offset:34816
	ds_read_b128 v[188:191], v172 offset:35840
	ds_read_b128 v[192:195], v172 offset:36864
	ds_read_b128 v[196:199], v172 offset:37888
	ds_read_b128 v[200:203], v172 offset:38912
	ds_read_b128 v[204:207], v172 offset:39936
	global_load_lds_dwordx4 v[208:209], off
	v_lshl_add_u64 v[208:209], s[20:21], 0, v[146:147]
	s_mov_b32 m0, s39
	s_nop 0
	global_load_lds_dwordx4 v[208:209], off
	s_waitcnt lgkmcnt(8)
	s_barrier
	s_setprio 0
	s_waitcnt lgkmcnt(7)
	v_mfma_f32_16x16x32_bf16 v[126:129], v[130:133], v[176:179], v[126:129]
	v_mfma_f32_16x16x32_bf16 v[122:125], v[138:141], v[176:179], v[122:125]
	s_waitcnt lgkmcnt(5)
	v_mfma_f32_16x16x32_bf16 v[114:117], v[130:133], v[184:187], v[114:117]
	v_mfma_f32_16x16x32_bf16 v[110:113], v[138:141], v[184:187], v[110:113]
	s_waitcnt lgkmcnt(3)
	v_mfma_f32_16x16x32_bf16 v[98:101], v[130:133], v[192:195], v[98:101]
	v_mfma_f32_16x16x32_bf16 v[94:97], v[138:141], v[192:195], v[94:97]
	s_waitcnt lgkmcnt(1)
	v_mfma_f32_16x16x32_bf16 v[82:85], v[130:133], v[200:203], v[82:85]
	v_mfma_f32_16x16x32_bf16 v[78:81], v[138:141], v[200:203], v[78:81]
	v_mfma_f32_16x16x32_bf16 v[126:129], v[134:137], v[180:183], v[126:129]
	v_mfma_f32_16x16x32_bf16 v[122:125], v[142:145], v[180:183], v[122:125]
	v_mfma_f32_16x16x32_bf16 v[114:117], v[134:137], v[188:191], v[114:117]
	v_mfma_f32_16x16x32_bf16 v[110:113], v[142:145], v[188:191], v[110:113]
	v_mfma_f32_16x16x32_bf16 v[98:101], v[134:137], v[196:199], v[98:101]
	v_mfma_f32_16x16x32_bf16 v[94:97], v[142:145], v[196:199], v[94:97]
	s_waitcnt lgkmcnt(0)
	v_mfma_f32_16x16x32_bf16 v[82:85], v[134:137], v[204:207], v[82:85]
	v_mfma_f32_16x16x32_bf16 v[78:81], v[142:145], v[204:207], v[78:81]
	s_setprio 1
	s_barrier
	s_add_i32 s20, 0, 0x1c000
	s_add_i32 s21, s22, s35
	v_add_u32_e32 v173, s20, v170
	v_lshl_add_u64 v[168:169], v[168:169], 0, s[0:1]
	s_mov_b32 m0, s21
	ds_read_b128 v[208:211], v173
	ds_read_b128 v[212:215], v173 offset:1024
	ds_read_b128 v[216:219], v173 offset:2048
	ds_read_b128 v[234:237], v173 offset:3072
	global_load_lds_dwordx4 v[168:169], off
	v_lshl_add_u64 v[168:169], v[224:225], 0, s[0:1]
	s_add_i32 m0, s21, 0x2000
	s_nop 0
	global_load_lds_dwordx4 v[168:169], off
	s_barrier
	s_setprio 0
	s_waitcnt lgkmcnt(3)
	v_mfma_f32_16x16x32_bf16 v[118:121], v[208:211], v[176:179], v[118:121]
	s_waitcnt lgkmcnt(1)
	v_mfma_f32_16x16x32_bf16 v[106:109], v[216:219], v[176:179], v[106:109]
	v_mfma_f32_16x16x32_bf16 v[102:105], v[208:211], v[184:187], v[102:105]
	v_mfma_f32_16x16x32_bf16 v[90:93], v[216:219], v[184:187], v[90:93]
	v_mfma_f32_16x16x32_bf16 v[86:89], v[208:211], v[192:195], v[86:89]
	v_mfma_f32_16x16x32_bf16 v[74:77], v[216:219], v[192:195], v[74:77]
	v_mfma_f32_16x16x32_bf16 v[70:73], v[208:211], v[200:203], v[70:73]
	v_mfma_f32_16x16x32_bf16 v[66:69], v[216:219], v[200:203], v[66:69]
	v_mfma_f32_16x16x32_bf16 v[118:121], v[212:215], v[180:183], v[118:121]
	s_waitcnt lgkmcnt(0)
	v_mfma_f32_16x16x32_bf16 v[106:109], v[234:237], v[180:183], v[106:109]
	v_mfma_f32_16x16x32_bf16 v[102:105], v[212:215], v[188:191], v[102:105]
	v_mfma_f32_16x16x32_bf16 v[90:93], v[234:237], v[188:191], v[90:93]
	v_mfma_f32_16x16x32_bf16 v[86:89], v[212:215], v[196:199], v[86:89]
	v_mfma_f32_16x16x32_bf16 v[74:77], v[234:237], v[196:199], v[74:77]
	v_mfma_f32_16x16x32_bf16 v[70:73], v[212:215], v[204:207], v[70:73]
	v_mfma_f32_16x16x32_bf16 v[66:69], v[234:237], v[204:207], v[66:69]
	s_setprio 1
	s_mov_b32 m0, s64
	v_lshl_add_u64 v[168:169], v[228:229], 0, s[0:1]
	s_barrier
	ds_read_b128 v[176:179], v172 offset:49152
	ds_read_b128 v[180:183], v172 offset:50176
	ds_read_b128 v[184:187], v172 offset:51200
	ds_read_b128 v[188:191], v172 offset:52224
	ds_read_b128 v[192:195], v172 offset:53248
	ds_read_b128 v[196:199], v172 offset:54272
	ds_read_b128 v[200:203], v172 offset:55296
	ds_read_b128 v[204:207], v172 offset:56320
	global_load_lds_dwordx4 v[168:169], off
	v_lshl_add_u64 v[168:169], v[238:239], 0, s[0:1]
	s_mov_b32 m0, s65
	s_nop 0
	global_load_lds_dwordx4 v[168:169], off
	s_barrier
; #define PG8_STAGE(bufoff, gbase, voff) do { _Pragma("unroll") for (int _i = 0; _i < 2; ++_i) \
;         __builtin_amdgcn_global_load_lds((const unsigned*)((const char*)(gbase) + (voff)[_i]), (PG8_LAS unsigned*)(lds + (bufoff) + ldsw + _i * 8192), 16, 0, 0); } while (0)
; #define PG8_LDA(dst, b, h) do { _Pragma("unroll") for (int m = 0; m < 4; ++m) _Pragma("unroll") for (int k = 0; k < 2; ++k) dst[m][k] = *(const PG8_LAS bf16x8*)(lds + PG8_SA(b, h) + aoff + m * 2048 + k * 1024); } while (0)
; #define PG8_LDB(dst, b, h) do { _Pragma("unroll") for (int n = 0; n < 2; ++n) _Pragma("unroll") for (int k = 0; k < 2; ++k) dst[n][k] = *(const PG8_LAS bf16x8*)(lds + PG8_SB(b, h) + boff + n * 2048 + k * 1024); } while (0)
; #define PG8_MMA(ai, bj, At, Bt) do { __builtin_amdgcn_s_setprio(1); _Pragma("unroll") for (int m = 0; m < 4; ++m) _Pragma("unroll") for (int n = 0; n < 2; ++n) _Pragma("unroll") for (int k = 0; k < 2; ++k) \
;         acc[ai][bj][m][n] = __builtin_amdgcn_mfma_f32_16x16x32_bf16(Bt[n][k], At[m][k], acc[ai][bj][m][n], 0, 0, 0); __builtin_amdgcn_s_setprio(0); } while (0)
; #define PG8_WAIT_V(n) asm volatile("s_waitcnt vmcnt(" #n ")" ::: "memory")
; #define PG8_WAIT_L(n) asm volatile("s_waitcnt lgkmcnt(" #n ")" ::: "memory")
; #define PG8_BAR __builtin_amdgcn_s_barrier()
; #define PG8_SCHED __builtin_amdgcn_sched_barrier(0)
; template <class Epi, class Sched>
; __device__ __forceinline__ void gemm_phase(PG8_LAS unsigned char* lds, const Gemm g, const Sched& S, const Epi& E) {
;     ...
;             const char* a2 = last ? nA : cA + (size_t)(t + 2) * kstep; const char* b2 = last ? nB : cB + (size_t)(t + 2) * kstep;
;             const char* a3 = a2 + kstep; const char* b3 = b2 + kstep;
;             if (last && has_next) S.a_ready(nxt);
;             PG8_LDB(B0, 0, 0); PG8_SCHED; PG8_LDA(At, 0, 0); PG8_STAGE(PG8_SA(1, 1), a1 + hstep, voffA);
;             PG8_WAIT_L(8); PG8_BAR; PG8_WAIT_L(0); PG8_MMA(0, 0, At, B0); PG8_BAR; PG8_SCHED;
;             PG8_LDB(B1, 0, 1); PG8_STAGE(PG8_SB(0, 0), b2, voffB);
;     ...
;             PG8_BAR; PG8_WAIT_L(0); PG8_MMA(1, 0, At, B0); PG8_BAR; PG8_SCHED;
;             PG8_STAGE(PG8_SB(1, 1), b3 + hstep, voffB);
;             PG8_WAIT_V(6); PG8_BAR; PG8_MMA(1, 1, At, B1); PG8_BAR;
	s_setprio 0
	s_waitcnt lgkmcnt(7)
	v_mfma_f32_16x16x32_bf16 v[62:65], v[130:133], v[176:179], v[62:65]
	v_mfma_f32_16x16x32_bf16 v[58:61], v[138:141], v[176:179], v[58:61]
	s_waitcnt lgkmcnt(5)
	v_mfma_f32_16x16x32_bf16 v[50:53], v[130:133], v[184:187], v[50:53]
	v_mfma_f32_16x16x32_bf16 v[44:47], v[138:141], v[184:187], v[44:47]
	s_waitcnt lgkmcnt(3)
	v_mfma_f32_16x16x32_bf16 v[32:35], v[130:133], v[192:195], v[32:35]
	v_mfma_f32_16x16x32_bf16 v[28:31], v[138:141], v[192:195], v[28:31]
	s_waitcnt lgkmcnt(1)
	v_mfma_f32_16x16x32_bf16 v[16:19], v[130:133], v[200:203], v[16:19]
	v_mfma_f32_16x16x32_bf16 v[12:15], v[138:141], v[200:203], v[12:15]
	v_mfma_f32_16x16x32_bf16 v[62:65], v[134:137], v[180:183], v[62:65]
	v_mfma_f32_16x16x32_bf16 v[58:61], v[142:145], v[180:183], v[58:61]
	v_mfma_f32_16x16x32_bf16 v[50:53], v[134:137], v[188:191], v[50:53]
	v_mfma_f32_16x16x32_bf16 v[44:47], v[142:145], v[188:191], v[44:47]
	v_mfma_f32_16x16x32_bf16 v[32:35], v[134:137], v[196:199], v[32:35]
	v_mfma_f32_16x16x32_bf16 v[28:31], v[142:145], v[196:199], v[28:31]
	s_waitcnt lgkmcnt(0)
	v_mfma_f32_16x16x32_bf16 v[16:19], v[134:137], v[204:207], v[16:19]
	v_mfma_f32_16x16x32_bf16 v[12:15], v[142:145], v[204:207], v[12:15]
	s_setprio 1
	s_barrier
	s_add_i32 s20, s20, s35
	v_lshl_add_u64 v[130:131], v[240:241], 0, s[0:1]
	s_mov_b32 m0, s20
	s_nop 0
	global_load_lds_dwordx4 v[130:131], off
	v_lshl_add_u64 v[130:131], v[242:243], 0, s[0:1]
	s_add_i32 m0, s20, 0x2000
	s_nop 0
	global_load_lds_dwordx4 v[130:131], off
	s_waitcnt vmcnt(6)
	s_barrier
	s_setprio 0
	v_mfma_f32_16x16x32_bf16 v[54:57], v[208:211], v[176:179], v[54:57]
	v_mfma_f32_16x16x32_bf16 v[40:43], v[216:219], v[176:179], v[40:43]
	v_mfma_f32_16x16x32_bf16 v[36:39], v[208:211], v[184:187], v[36:39]
	v_mfma_f32_16x16x32_bf16 v[24:27], v[216:219], v[184:187], v[24:27]
	v_mfma_f32_16x16x32_bf16 v[20:23], v[208:211], v[192:195], v[20:23]
	v_mfma_f32_16x16x32_bf16 v[8:11], v[216:219], v[192:195], v[8:11]
	v_mfma_f32_16x16x32_bf16 v[4:7], v[208:211], v[200:203], v[4:7]
	v_mfma_f32_16x16x32_bf16 v[0:3], v[216:219], v[200:203], v[0:3]
	v_mfma_f32_16x16x32_bf16 v[54:57], v[212:215], v[180:183], v[54:57]
	v_mfma_f32_16x16x32_bf16 v[40:43], v[234:237], v[180:183], v[40:43]
	v_mfma_f32_16x16x32_bf16 v[36:39], v[212:215], v[188:191], v[36:39]
	v_mfma_f32_16x16x32_bf16 v[24:27], v[234:237], v[188:191], v[24:27]
	v_mfma_f32_16x16x32_bf16 v[20:23], v[212:215], v[196:199], v[20:23]
	v_mfma_f32_16x16x32_bf16 v[8:11], v[234:237], v[196:199], v[8:11]
	v_mfma_f32_16x16x32_bf16 v[4:7], v[212:215], v[204:207], v[4:7]
	v_mfma_f32_16x16x32_bf16 v[0:3], v[234:237], v[204:207], v[0:3]
	s_setprio 1
	s_add_u32 s16, s16, 0x100
	s_addc_u32 s17, s17, 0
	s_add_u32 s24, s24, 0x100
	s_addc_u32 s25, s25, 0
	s_cmp_ge_u32 s42, s54
	s_mov_b32 s20, s42
	s_barrier
	s_cbranch_scc1 .Lkpeel_exit_268
.LBB0_268:
	s_add_i32 s42, s20, 2
	s_add_u32 s22, s16, 0x80
	s_addc_u32 s21, s17, 0
	s_add_i32 s43, 0, 0x10000
	v_add_u32_e32 v142, s43, v170
	ds_read_b128 v[130:133], v142
	ds_read_b128 v[134:137], v142 offset:1024
	ds_read_b128 v[138:141], v142 offset:2048
	ds_read_b128 v[142:145], v142 offset:3072
	s_cmp_eq_u32 s66, s20
	s_cselect_b32 s20, s2, s22
	s_cselect_b32 s21, s3, s21
	s_cselect_b32 s23, s13, s25
	s_cselect_b32 s22, s12, s24
	v_lshl_add_u64 v[168:169], s[16:17], 0, v[164:165]
	s_add_i32 m0, s36, 0xc000
	ds_read_b128 v[176:179], v172
	ds_read_b128 v[180:183], v172 offset:1024
	ds_read_b128 v[184:187], v172 offset:2048
	ds_read_b128 v[188:191], v172 offset:3072
	ds_read_b128 v[192:195], v172 offset:4096
	ds_read_b128 v[196:199], v172 offset:5120
	ds_read_b128 v[200:203], v172 offset:6144
	ds_read_b128 v[204:207], v172 offset:7168
	global_load_lds_dwordx4 v[168:169], off
	v_lshl_add_u64 v[168:169], s[16:17], 0, v[166:167]
	s_add_i32 m0, s36, 0xe000
	s_nop 0
	global_load_lds_dwordx4 v[168:169], off
	s_waitcnt lgkmcnt(8)
	s_barrier
	s_setprio 0
	s_waitcnt lgkmcnt(7)
	v_mfma_f32_16x16x32_bf16 v[126:129], v[130:133], v[176:179], v[126:129]
	v_mfma_f32_16x16x32_bf16 v[122:125], v[138:141], v[176:179], v[122:125]
	s_waitcnt lgkmcnt(5)
	v_mfma_f32_16x16x32_bf16 v[114:117], v[130:133], v[184:187], v[114:117]
	v_mfma_f32_16x16x32_bf16 v[110:113], v[138:141], v[184:187], v[110:113]
	s_waitcnt lgkmcnt(3)
	v_mfma_f32_16x16x32_bf16 v[98:101], v[130:133], v[192:195], v[98:101]
	v_mfma_f32_16x16x32_bf16 v[94:97], v[138:141], v[192:195], v[94:97]
	s_waitcnt lgkmcnt(1)
	v_mfma_f32_16x16x32_bf16 v[82:85], v[130:133], v[200:203], v[82:85]
	v_mfma_f32_16x16x32_bf16 v[78:81], v[138:141], v[200:203], v[78:81]
	v_mfma_f32_16x16x32_bf16 v[126:129], v[134:137], v[180:183], v[126:129]
	v_mfma_f32_16x16x32_bf16 v[122:125], v[142:145], v[180:183], v[122:125]
	v_mfma_f32_16x16x32_bf16 v[114:117], v[134:137], v[188:191], v[114:117]
	v_mfma_f32_16x16x32_bf16 v[110:113], v[142:145], v[188:191], v[110:113]
	v_mfma_f32_16x16x32_bf16 v[98:101], v[134:137], v[196:199], v[98:101]
	v_mfma_f32_16x16x32_bf16 v[94:97], v[142:145], v[196:199], v[94:97]
	s_waitcnt lgkmcnt(0)
	v_mfma_f32_16x16x32_bf16 v[82:85], v[134:137], v[204:207], v[82:85]
	v_mfma_f32_16x16x32_bf16 v[78:81], v[142:145], v[204:207], v[78:81]
	s_setprio 1
	s_barrier
	s_add_i32 s44, 0, 0x14000
	v_add_u32_e32 v168, s44, v170
	s_add_i32 s43, s43, s35
	ds_read_b128 v[208:211], v168
	ds_read_b128 v[212:215], v168 offset:1024
	ds_read_b128 v[216:219], v168 offset:2048
	ds_read_b128 v[234:237], v168 offset:3072
	v_lshl_add_u64 v[168:169], s[22:23], 0, v[48:49]
	s_mov_b32 m0, s43
	v_lshl_add_u64 v[224:225], s[22:23], 0, v[146:147]
	global_load_lds_dwordx4 v[168:169], off
	s_add_i32 m0, s43, 0x2000
	s_nop 0
	global_load_lds_dwordx4 v[224:225], off
	s_barrier
; #define PG8_STAGE(bufoff, gbase, voff) do { _Pragma("unroll") for (int _i = 0; _i < 2; ++_i) \
;         __builtin_amdgcn_global_load_lds((const unsigned*)((const char*)(gbase) + (voff)[_i]), (PG8_LAS unsigned*)(lds + (bufoff) + ldsw + _i * 8192), 16, 0, 0); } while (0)
; #define PG8_LDA(dst, b, h) do { _Pragma("unroll") for (int m = 0; m < 4; ++m) _Pragma("unroll") for (int k = 0; k < 2; ++k) dst[m][k] = *(const PG8_LAS bf16x8*)(lds + PG8_SA(b, h) + aoff + m * 2048 + k * 1024); } while (0)
; #define PG8_LDB(dst, b, h) do { _Pragma("unroll") for (int n = 0; n < 2; ++n) _Pragma("unroll") for (int k = 0; k < 2; ++k) dst[n][k] = *(const PG8_LAS bf16x8*)(lds + PG8_SB(b, h) + boff + n * 2048 + k * 1024); } while (0)
; #define PG8_MMA(ai, bj, At, Bt) do { __builtin_amdgcn_s_setprio(1); _Pragma("unroll") for (int m = 0; m < 4; ++m) _Pragma("unroll") for (int n = 0; n < 2; ++n) _Pragma("unroll") for (int k = 0; k < 2; ++k) \
;         acc[ai][bj][m][n] = __builtin_amdgcn_mfma_f32_16x16x32_bf16(Bt[n][k], At[m][k], acc[ai][bj][m][n], 0, 0, 0); __builtin_amdgcn_s_setprio(0); } while (0)
; #define PG8_WAIT_V(n) asm volatile("s_waitcnt vmcnt(" #n ")" ::: "memory")
; #define PG8_WAIT_L(n) asm volatile("s_waitcnt lgkmcnt(" #n ")" ::: "memory")
; #define PG8_BAR __builtin_amdgcn_s_barrier()
; #define PG8_SCHED __builtin_amdgcn_sched_barrier(0)
; template <class Epi, class Sched>
; __device__ __forceinline__ void gemm_phase(PG8_LAS unsigned char* lds, const Gemm g, const Sched& S, const Epi& E) {
;     ...
;             PG8_BAR; PG8_WAIT_L(0); PG8_MMA(0, 1, At, B1); PG8_BAR;
;             PG8_LDA(At, 0, 1); PG8_STAGE(PG8_SA(0, 0), a2, voffA);
;             PG8_BAR; PG8_WAIT_L(0); PG8_MMA(1, 0, At, B0); PG8_BAR; PG8_SCHED;
;             PG8_STAGE(PG8_SB(0, 1), b2 + hstep, voffB);
;             PG8_WAIT_V(6); PG8_BAR; PG8_MMA(1, 1, At, B1); PG8_BAR;
;             PG8_LDB(B0, 1, 0); PG8_SCHED; PG8_LDA(At, 1, 0); PG8_STAGE(PG8_SA(0, 1), a2 + hstep, voffA);
;             PG8_WAIT_L(8); PG8_BAR; PG8_WAIT_L(0); PG8_MMA(0, 0, At, B0); PG8_BAR; PG8_SCHED;
	s_setprio 0
	s_waitcnt lgkmcnt(3)
	v_mfma_f32_16x16x32_bf16 v[118:121], v[208:211], v[176:179], v[118:121]
	s_waitcnt lgkmcnt(1)
	v_mfma_f32_16x16x32_bf16 v[106:109], v[216:219], v[176:179], v[106:109]
	v_mfma_f32_16x16x32_bf16 v[102:105], v[208:211], v[184:187], v[102:105]
	v_mfma_f32_16x16x32_bf16 v[90:93], v[216:219], v[184:187], v[90:93]
	v_mfma_f32_16x16x32_bf16 v[86:89], v[208:211], v[192:195], v[86:89]
	v_mfma_f32_16x16x32_bf16 v[74:77], v[216:219], v[192:195], v[74:77]
	v_mfma_f32_16x16x32_bf16 v[70:73], v[208:211], v[200:203], v[70:73]
	v_mfma_f32_16x16x32_bf16 v[66:69], v[216:219], v[200:203], v[66:69]
	v_mfma_f32_16x16x32_bf16 v[118:121], v[212:215], v[180:183], v[118:121]
	s_waitcnt lgkmcnt(0)
	v_mfma_f32_16x16x32_bf16 v[106:109], v[234:237], v[180:183], v[106:109]
	v_mfma_f32_16x16x32_bf16 v[102:105], v[212:215], v[188:191], v[102:105]
	v_mfma_f32_16x16x32_bf16 v[90:93], v[234:237], v[188:191], v[90:93]
	v_mfma_f32_16x16x32_bf16 v[86:89], v[212:215], v[196:199], v[86:89]
	v_mfma_f32_16x16x32_bf16 v[74:77], v[234:237], v[196:199], v[74:77]
	v_mfma_f32_16x16x32_bf16 v[70:73], v[212:215], v[204:207], v[70:73]
	v_mfma_f32_16x16x32_bf16 v[66:69], v[234:237], v[204:207], v[66:69]
	s_setprio 1
	s_mov_b32 m0, s36
	v_lshl_add_u64 v[228:229], s[20:21], 0, v[48:49]
	s_barrier
	ds_read_b128 v[176:179], v172 offset:16384
	ds_read_b128 v[180:183], v172 offset:17408
	ds_read_b128 v[184:187], v172 offset:18432
	ds_read_b128 v[188:191], v172 offset:19456
	ds_read_b128 v[192:195], v172 offset:20480
	ds_read_b128 v[196:199], v172 offset:21504
	ds_read_b128 v[200:203], v172 offset:22528
	ds_read_b128 v[204:207], v172 offset:23552
	global_load_lds_dwordx4 v[228:229], off
	v_lshl_add_u64 v[238:239], s[20:21], 0, v[146:147]
	s_mov_b32 m0, s37
	s_nop 0
	global_load_lds_dwordx4 v[238:239], off
	s_barrier
	s_setprio 0
	s_waitcnt lgkmcnt(7)
	v_mfma_f32_16x16x32_bf16 v[62:65], v[130:133], v[176:179], v[62:65]
	v_mfma_f32_16x16x32_bf16 v[58:61], v[138:141], v[176:179], v[58:61]
	s_waitcnt lgkmcnt(5)
	v_mfma_f32_16x16x32_bf16 v[50:53], v[130:133], v[184:187], v[50:53]
	v_mfma_f32_16x16x32_bf16 v[44:47], v[138:141], v[184:187], v[44:47]
	s_waitcnt lgkmcnt(3)
	v_mfma_f32_16x16x32_bf16 v[32:35], v[130:133], v[192:195], v[32:35]
	v_mfma_f32_16x16x32_bf16 v[28:31], v[138:141], v[192:195], v[28:31]
	s_waitcnt lgkmcnt(1)
	v_mfma_f32_16x16x32_bf16 v[16:19], v[130:133], v[200:203], v[16:19]
	v_mfma_f32_16x16x32_bf16 v[12:15], v[138:141], v[200:203], v[12:15]
	v_mfma_f32_16x16x32_bf16 v[62:65], v[134:137], v[180:183], v[62:65]
	v_mfma_f32_16x16x32_bf16 v[58:61], v[142:145], v[180:183], v[58:61]
	v_mfma_f32_16x16x32_bf16 v[50:53], v[134:137], v[188:191], v[50:53]
	v_mfma_f32_16x16x32_bf16 v[44:47], v[142:145], v[188:191], v[44:47]
	v_mfma_f32_16x16x32_bf16 v[32:35], v[134:137], v[196:199], v[32:35]
	v_mfma_f32_16x16x32_bf16 v[28:31], v[142:145], v[196:199], v[28:31]
	s_waitcnt lgkmcnt(0)
	v_mfma_f32_16x16x32_bf16 v[16:19], v[134:137], v[204:207], v[16:19]
	v_mfma_f32_16x16x32_bf16 v[12:15], v[142:145], v[204:207], v[12:15]
	s_setprio 1
	s_barrier
	s_add_u32 s22, s22, s10
	s_addc_u32 s23, s23, 0
	s_add_i32 s43, s44, s35
	v_lshl_add_u64 v[240:241], s[22:23], 0, v[48:49]
	s_mov_b32 m0, s43
	v_lshl_add_u64 v[242:243], s[22:23], 0, v[146:147]
	global_load_lds_dwordx4 v[240:241], off
	s_add_i32 m0, s43, 0x2000
	s_nop 0
	global_load_lds_dwordx4 v[242:243], off
	s_waitcnt vmcnt(6)
	s_barrier
	s_setprio 0
	v_mfma_f32_16x16x32_bf16 v[54:57], v[208:211], v[176:179], v[54:57]
	v_mfma_f32_16x16x32_bf16 v[40:43], v[216:219], v[176:179], v[40:43]
	v_mfma_f32_16x16x32_bf16 v[36:39], v[208:211], v[184:187], v[36:39]
	v_mfma_f32_16x16x32_bf16 v[24:27], v[216:219], v[184:187], v[24:27]
	v_mfma_f32_16x16x32_bf16 v[20:23], v[208:211], v[192:195], v[20:23]
	v_mfma_f32_16x16x32_bf16 v[8:11], v[216:219], v[192:195], v[8:11]
	v_mfma_f32_16x16x32_bf16 v[4:7], v[208:211], v[200:203], v[4:7]
	v_mfma_f32_16x16x32_bf16 v[0:3], v[216:219], v[200:203], v[0:3]
	v_mfma_f32_16x16x32_bf16 v[54:57], v[212:215], v[180:183], v[54:57]
	v_mfma_f32_16x16x32_bf16 v[40:43], v[234:237], v[180:183], v[40:43]
	v_mfma_f32_16x16x32_bf16 v[36:39], v[212:215], v[188:191], v[36:39]
	v_mfma_f32_16x16x32_bf16 v[24:27], v[234:237], v[188:191], v[24:27]
	v_mfma_f32_16x16x32_bf16 v[20:23], v[212:215], v[196:199], v[20:23]
	v_mfma_f32_16x16x32_bf16 v[8:11], v[234:237], v[196:199], v[8:11]
	v_mfma_f32_16x16x32_bf16 v[4:7], v[212:215], v[204:207], v[4:7]
	v_mfma_f32_16x16x32_bf16 v[0:3], v[234:237], v[204:207], v[0:3]
	s_setprio 1
	s_add_i32 s22, 0, 0x18000
	v_add_u32_e32 v142, s22, v170
	s_barrier
	ds_read_b128 v[130:133], v142
	ds_read_b128 v[134:137], v142 offset:1024
	ds_read_b128 v[138:141], v142 offset:2048
	ds_read_b128 v[142:145], v142 offset:3072
	s_add_u32 s20, s20, s10
	s_addc_u32 s21, s21, 0
	s_mov_b32 m0, s38
	v_lshl_add_u64 v[208:209], s[20:21], 0, v[48:49]
	ds_read_b128 v[176:179], v172 offset:32768
	ds_read_b128 v[180:183], v172 offset:33792
	ds_read_b128 v[184:187], v172 offset:34816
	ds_read_b128 v[188:191], v172 offset:35840
	ds_read_b128 v[192:195], v172 offset:36864
	ds_read_b128 v[196:199], v172 offset:37888
	ds_read_b128 v[200:203], v172 offset:38912
	ds_read_b128 v[204:207], v172 offset:39936
	global_load_lds_dwordx4 v[208:209], off
	v_lshl_add_u64 v[208:209], s[20:21], 0, v[146:147]
	s_mov_b32 m0, s39
	s_nop 0
	global_load_lds_dwordx4 v[208:209], off
	s_waitcnt lgkmcnt(8)
	s_barrier
; #define PG8_STAGE(bufoff, gbase, voff) do { _Pragma("unroll") for (int _i = 0; _i < 2; ++_i) \
;         __builtin_amdgcn_global_load_lds((const unsigned*)((const char*)(gbase) + (voff)[_i]), (PG8_LAS unsigned*)(lds + (bufoff) + ldsw + _i * 8192), 16, 0, 0); } while (0)
; #define PG8_LDA(dst, b, h) do { _Pragma("unroll") for (int m = 0; m < 4; ++m) _Pragma("unroll") for (int k = 0; k < 2; ++k) dst[m][k] = *(const PG8_LAS bf16x8*)(lds + PG8_SA(b, h) + aoff + m * 2048 + k * 1024); } while (0)
; #define PG8_LDB(dst, b, h) do { _Pragma("unroll") for (int n = 0; n < 2; ++n) _Pragma("unroll") for (int k = 0; k < 2; ++k) dst[n][k] = *(const PG8_LAS bf16x8*)(lds + PG8_SB(b, h) + boff + n * 2048 + k * 1024); } while (0)
; #define PG8_MMA(ai, bj, At, Bt) do { __builtin_amdgcn_s_setprio(1); _Pragma("unroll") for (int m = 0; m < 4; ++m) _Pragma("unroll") for (int n = 0; n < 2; ++n) _Pragma("unroll") for (int k = 0; k < 2; ++k) \
;         acc[ai][bj][m][n] = __builtin_amdgcn_mfma_f32_16x16x32_bf16(Bt[n][k], At[m][k], acc[ai][bj][m][n], 0, 0, 0); __builtin_amdgcn_s_setprio(0); } while (0)
; #define PG8_WAIT_V(n) asm volatile("s_waitcnt vmcnt(" #n ")" ::: "memory")
; #define PG8_WAIT_L(n) asm volatile("s_waitcnt lgkmcnt(" #n ")" ::: "memory")
; template <class Epi, class Sched>
; __device__ __forceinline__ void gemm_phase(PG8_LAS unsigned char* lds, const Gemm g, const Sched& S, const Epi& E) {
;     ...
;             PG8_WAIT_L(8); PG8_BAR; PG8_WAIT_L(0); PG8_MMA(0, 0, At, B0); PG8_BAR; PG8_SCHED;
;             PG8_LDB(B1, 1, 1); PG8_STAGE(PG8_SB(1, 0), b3, voffB);
;             PG8_BAR; PG8_WAIT_L(0); PG8_MMA(0, 1, At, B1); PG8_BAR;
;             PG8_LDA(At, 1, 1); PG8_STAGE(PG8_SA(1, 0), a3, voffA);
;             PG8_BAR; PG8_WAIT_L(0); PG8_MMA(1, 0, At, B0); PG8_BAR; PG8_SCHED;
;             PG8_STAGE(PG8_SB(1, 1), b3 + hstep, voffB);
;             PG8_WAIT_V(6); PG8_BAR; PG8_MMA(1, 1, At, B1); PG8_BAR;
;     __device__ __forceinline__ void operator()(const f32x4 (&acc)[2][2][4][2], const pg8::Unit& u, int wr, int wc, int fr, int fq) const {
;         const int R0 = row_off + u.pm * 256;
;         const float* inp; float* outp; int bidx;
;         if (R0 < ML) { bidx = R0 >> 12; inp = in_lat + (size_t)R0 * DM; outp = out_lat + (size_t)R0 * DM; }
;         else { bidx = 8; inp = in_ctx + (size_t)(R0 - ML) * DM; outp = out_ctx + (size_t)(R0 - ML) * DM; }
	s_setprio 0
	s_waitcnt lgkmcnt(7)
	v_mfma_f32_16x16x32_bf16 v[126:129], v[130:133], v[176:179], v[126:129]
	v_mfma_f32_16x16x32_bf16 v[122:125], v[138:141], v[176:179], v[122:125]
	s_waitcnt lgkmcnt(5)
	v_mfma_f32_16x16x32_bf16 v[114:117], v[130:133], v[184:187], v[114:117]
	v_mfma_f32_16x16x32_bf16 v[110:113], v[138:141], v[184:187], v[110:113]
	s_waitcnt lgkmcnt(3)
	v_mfma_f32_16x16x32_bf16 v[98:101], v[130:133], v[192:195], v[98:101]
	v_mfma_f32_16x16x32_bf16 v[94:97], v[138:141], v[192:195], v[94:97]
	s_waitcnt lgkmcnt(1)
	v_mfma_f32_16x16x32_bf16 v[82:85], v[130:133], v[200:203], v[82:85]
	v_mfma_f32_16x16x32_bf16 v[78:81], v[138:141], v[200:203], v[78:81]
	v_mfma_f32_16x16x32_bf16 v[126:129], v[134:137], v[180:183], v[126:129]
	v_mfma_f32_16x16x32_bf16 v[122:125], v[142:145], v[180:183], v[122:125]
	v_mfma_f32_16x16x32_bf16 v[114:117], v[134:137], v[188:191], v[114:117]
	v_mfma_f32_16x16x32_bf16 v[110:113], v[142:145], v[188:191], v[110:113]
	v_mfma_f32_16x16x32_bf16 v[98:101], v[134:137], v[196:199], v[98:101]
	v_mfma_f32_16x16x32_bf16 v[94:97], v[142:145], v[196:199], v[94:97]
	s_waitcnt lgkmcnt(0)
	v_mfma_f32_16x16x32_bf16 v[82:85], v[134:137], v[204:207], v[82:85]
	v_mfma_f32_16x16x32_bf16 v[78:81], v[142:145], v[204:207], v[78:81]
	s_setprio 1
	s_barrier
	s_add_i32 s20, 0, 0x1c000
	s_add_i32 s21, s22, s35
	v_add_u32_e32 v173, s20, v170
	v_lshl_add_u64 v[168:169], v[168:169], 0, s[0:1]
	s_mov_b32 m0, s21
	ds_read_b128 v[208:211], v173
	ds_read_b128 v[212:215], v173 offset:1024
	ds_read_b128 v[216:219], v173 offset:2048
	ds_read_b128 v[234:237], v173 offset:3072
	global_load_lds_dwordx4 v[168:169], off
	v_lshl_add_u64 v[168:169], v[224:225], 0, s[0:1]
	s_add_i32 m0, s21, 0x2000
	s_nop 0
	global_load_lds_dwordx4 v[168:169], off
	s_barrier
	s_setprio 0
	s_waitcnt lgkmcnt(3)
	v_mfma_f32_16x16x32_bf16 v[118:121], v[208:211], v[176:179], v[118:121]
	s_waitcnt lgkmcnt(1)
	v_mfma_f32_16x16x32_bf16 v[106:109], v[216:219], v[176:179], v[106:109]
	v_mfma_f32_16x16x32_bf16 v[102:105], v[208:211], v[184:187], v[102:105]
	v_mfma_f32_16x16x32_bf16 v[90:93], v[216:219], v[184:187], v[90:93]
	v_mfma_f32_16x16x32_bf16 v[86:89], v[208:211], v[192:195], v[86:89]
	v_mfma_f32_16x16x32_bf16 v[74:77], v[216:219], v[192:195], v[74:77]
	v_mfma_f32_16x16x32_bf16 v[70:73], v[208:211], v[200:203], v[70:73]
	v_mfma_f32_16x16x32_bf16 v[66:69], v[216:219], v[200:203], v[66:69]
	v_mfma_f32_16x16x32_bf16 v[118:121], v[212:215], v[180:183], v[118:121]
	s_waitcnt lgkmcnt(0)
	v_mfma_f32_16x16x32_bf16 v[106:109], v[234:237], v[180:183], v[106:109]
	v_mfma_f32_16x16x32_bf16 v[102:105], v[212:215], v[188:191], v[102:105]
	v_mfma_f32_16x16x32_bf16 v[90:93], v[234:237], v[188:191], v[90:93]
	v_mfma_f32_16x16x32_bf16 v[86:89], v[212:215], v[196:199], v[86:89]
	v_mfma_f32_16x16x32_bf16 v[74:77], v[234:237], v[196:199], v[74:77]
	v_mfma_f32_16x16x32_bf16 v[70:73], v[212:215], v[204:207], v[70:73]
	v_mfma_f32_16x16x32_bf16 v[66:69], v[234:237], v[204:207], v[66:69]
	s_setprio 1
	s_mov_b32 m0, s64
	v_lshl_add_u64 v[168:169], v[228:229], 0, s[0:1]
	s_barrier
	ds_read_b128 v[176:179], v172 offset:49152
	ds_read_b128 v[180:183], v172 offset:50176
	ds_read_b128 v[184:187], v172 offset:51200
	ds_read_b128 v[188:191], v172 offset:52224
	ds_read_b128 v[192:195], v172 offset:53248
	ds_read_b128 v[196:199], v172 offset:54272
	ds_read_b128 v[200:203], v172 offset:55296
	ds_read_b128 v[204:207], v172 offset:56320
	global_load_lds_dwordx4 v[168:169], off
	v_lshl_add_u64 v[168:169], v[238:239], 0, s[0:1]
	s_mov_b32 m0, s65
	s_nop 0
	global_load_lds_dwordx4 v[168:169], off
	s_barrier
	s_setprio 0
	s_waitcnt lgkmcnt(7)
	v_mfma_f32_16x16x32_bf16 v[62:65], v[130:133], v[176:179], v[62:65]
	v_mfma_f32_16x16x32_bf16 v[58:61], v[138:141], v[176:179], v[58:61]
	s_waitcnt lgkmcnt(5)
	v_mfma_f32_16x16x32_bf16 v[50:53], v[130:133], v[184:187], v[50:53]
	v_mfma_f32_16x16x32_bf16 v[44:47], v[138:141], v[184:187], v[44:47]
	s_waitcnt lgkmcnt(3)
	v_mfma_f32_16x16x32_bf16 v[32:35], v[130:133], v[192:195], v[32:35]
	v_mfma_f32_16x16x32_bf16 v[28:31], v[138:141], v[192:195], v[28:31]
	s_waitcnt lgkmcnt(1)
	v_mfma_f32_16x16x32_bf16 v[16:19], v[130:133], v[200:203], v[16:19]
	v_mfma_f32_16x16x32_bf16 v[12:15], v[138:141], v[200:203], v[12:15]
	v_mfma_f32_16x16x32_bf16 v[62:65], v[134:137], v[180:183], v[62:65]
	v_mfma_f32_16x16x32_bf16 v[58:61], v[142:145], v[180:183], v[58:61]
	v_mfma_f32_16x16x32_bf16 v[50:53], v[134:137], v[188:191], v[50:53]
	v_mfma_f32_16x16x32_bf16 v[44:47], v[142:145], v[188:191], v[44:47]
	v_mfma_f32_16x16x32_bf16 v[32:35], v[134:137], v[196:199], v[32:35]
	v_mfma_f32_16x16x32_bf16 v[28:31], v[142:145], v[196:199], v[28:31]
	s_waitcnt lgkmcnt(0)
	v_mfma_f32_16x16x32_bf16 v[16:19], v[134:137], v[204:207], v[16:19]
	v_mfma_f32_16x16x32_bf16 v[12:15], v[142:145], v[204:207], v[12:15]
	s_setprio 1
	s_barrier
	s_add_i32 s20, s20, s35
	v_lshl_add_u64 v[130:131], v[240:241], 0, s[0:1]
	s_mov_b32 m0, s20
	s_nop 0
	global_load_lds_dwordx4 v[130:131], off
	v_lshl_add_u64 v[130:131], v[242:243], 0, s[0:1]
	s_add_i32 m0, s20, 0x2000
	s_nop 0
	global_load_lds_dwordx4 v[130:131], off
	s_waitcnt vmcnt(6)
	s_barrier
	s_setprio 0
	v_mfma_f32_16x16x32_bf16 v[54:57], v[208:211], v[176:179], v[54:57]
	v_mfma_f32_16x16x32_bf16 v[40:43], v[216:219], v[176:179], v[40:43]
	v_mfma_f32_16x16x32_bf16 v[36:39], v[208:211], v[184:187], v[36:39]
	v_mfma_f32_16x16x32_bf16 v[24:27], v[216:219], v[184:187], v[24:27]
	v_mfma_f32_16x16x32_bf16 v[20:23], v[208:211], v[192:195], v[20:23]
	v_mfma_f32_16x16x32_bf16 v[8:11], v[216:219], v[192:195], v[8:11]
	v_mfma_f32_16x16x32_bf16 v[4:7], v[208:211], v[200:203], v[4:7]
	v_mfma_f32_16x16x32_bf16 v[0:3], v[216:219], v[200:203], v[0:3]
	v_mfma_f32_16x16x32_bf16 v[54:57], v[212:215], v[180:183], v[54:57]
	v_mfma_f32_16x16x32_bf16 v[40:43], v[234:237], v[180:183], v[40:43]
	v_mfma_f32_16x16x32_bf16 v[36:39], v[212:215], v[188:191], v[36:39]
	v_mfma_f32_16x16x32_bf16 v[24:27], v[234:237], v[188:191], v[24:27]
	v_mfma_f32_16x16x32_bf16 v[20:23], v[212:215], v[196:199], v[20:23]
	v_mfma_f32_16x16x32_bf16 v[8:11], v[234:237], v[196:199], v[8:11]
	v_mfma_f32_16x16x32_bf16 v[4:7], v[212:215], v[204:207], v[4:7]
	v_mfma_f32_16x16x32_bf16 v[0:3], v[234:237], v[204:207], v[0:3]
	s_setprio 1
	s_add_u32 s16, s16, 0x100
	s_addc_u32 s17, s17, 0
	s_add_u32 s24, s24, 0x100
	s_addc_u32 s25, s25, 0
	s_cmp_ge_u32 s42, s54
	s_mov_b32 s20, s42
	s_barrier
	s_cbranch_scc0 .LBB0_268
.Lkpeel_exit_268:
	s_setprio 0
	s_lshl_b32 s22, s69, 8
	s_cmpk_gt_i32 s69, 0x7f
	s_mov_b64 s[20:21], -1
	s_cbranch_scc0 .LBB0_271
	s_mov_b32 s17, s73
	s_add_i32 s16, s22, 0xffff8000
	s_lshl_b64 s[16:17], s[16:17], 12
	s_add_u32 s16, s55, s16
	s_addc_u32 s17, s56, s17
	s_mov_b64 s[20:21], 0

; #define PG8_STAGE(bufoff, gbase, voff) do { _Pragma("unroll") for (int _i = 0; _i < 2; ++_i) \
;         __builtin_amdgcn_global_load_lds((const unsigned*)((const char*)(gbase) + (voff)[_i]), (PG8_LAS unsigned*)(lds + (bufoff) + ldsw + _i * 8192), 16, 0, 0); } while (0)
; #define PG8_LDA(dst, b, h) do { _Pragma("unroll") for (int m = 0; m < 4; ++m) _Pragma("unroll") for (int k = 0; k < 2; ++k) dst[m][k] = *(const PG8_LAS bf16x8*)(lds + PG8_SA(b, h) + aoff + m * 2048 + k * 1024); } while (0)
; #define PG8_LDB(dst, b, h) do { _Pragma("unroll") for (int n = 0; n < 2; ++n) _Pragma("unroll") for (int k = 0; k < 2; ++k) dst[n][k] = *(const PG8_LAS bf16x8*)(lds + PG8_SB(b, h) + boff + n * 2048 + k * 1024); } while (0)
; #define PG8_MMA(ai, bj, At, Bt) do { __builtin_amdgcn_s_setprio(1); _Pragma("unroll") for (int m = 0; m < 4; ++m) _Pragma("unroll") for (int n = 0; n < 2; ++n) _Pragma("unroll") for (int k = 0; k < 2; ++k) \
;         acc[ai][bj][m][n] = __builtin_amdgcn_mfma_f32_16x16x32_bf16(Bt[n][k], At[m][k], acc[ai][bj][m][n], 0, 0, 0); __builtin_amdgcn_s_setprio(0); } while (0)
; #define PG8_WAIT_L(n) asm volatile("s_waitcnt lgkmcnt(" #n ")" ::: "memory")
; #define PG8_BAR __builtin_amdgcn_s_barrier()
; #define PG8_SCHED __builtin_amdgcn_sched_barrier(0)
; template <class Epi, class Sched>
; __device__ __forceinline__ void gemm_phase(PG8_LAS unsigned char* lds, const Gemm g, const Sched& S, const Epi& E) {
;     ...
;             PG8_LDB(B0, 0, 0); PG8_SCHED; PG8_LDA(At, 0, 0); PG8_STAGE(PG8_SA(1, 1), a1 + hstep, voffA);
;             PG8_WAIT_L(8); PG8_BAR; PG8_WAIT_L(0); PG8_MMA(0, 0, At, B0); PG8_BAR; PG8_SCHED;
;             PG8_LDB(B1, 0, 1); PG8_STAGE(PG8_SB(0, 0), b2, voffB);
;             PG8_BAR; PG8_WAIT_L(0); PG8_MMA(0, 1, At, B1); PG8_BAR;
;             PG8_LDA(At, 0, 1); PG8_STAGE(PG8_SA(0, 0), a2, voffA);
;             PG8_BAR; PG8_WAIT_L(0); PG8_MMA(1, 0, At, B0); PG8_BAR; PG8_SCHED;
.LBB0_287:
	s_add_u32 s20, s20, 0x80
	s_addc_u32 s21, s21, 0
	s_add_u32 s3, s22, 0x100
	s_addc_u32 s40, s23, 0
	s_mov_b32 s22, 0
	s_add_i32 s41, s22, 2
	s_add_u32 s24, s20, 0x80
	s_addc_u32 s23, s21, 0
	s_add_i32 s63, 0, 0x10000
	v_add_u32_e32 v155, s63, v152
	ds_read_b128 v[156:159], v155
	ds_read_b128 v[160:163], v155 offset:1024
	ds_read_b128 v[164:167], v155 offset:2048
	ds_read_b128 v[168:171], v155 offset:3072
	s_cmp_eq_u32 s55, s22
	s_cselect_b32 s22, s12, s24
	s_cselect_b32 s23, s13, s23
	s_cselect_b32 s25, s17, s40
	s_cselect_b32 s24, s16, s3
	v_lshl_add_u64 v[172:173], s[20:21], 0, v[148:149]
	s_add_i32 m0, s43, 0xc000
	ds_read_b128 v[176:179], v154
	ds_read_b128 v[180:183], v154 offset:1024
	ds_read_b128 v[184:187], v154 offset:2048
	ds_read_b128 v[188:191], v154 offset:3072
	ds_read_b128 v[192:195], v154 offset:4096
	ds_read_b128 v[196:199], v154 offset:5120
	ds_read_b128 v[200:203], v154 offset:6144
	ds_read_b128 v[204:207], v154 offset:7168
	global_load_lds_dwordx4 v[172:173], off
	v_lshl_add_u64 v[172:173], s[20:21], 0, v[150:151]
	s_add_i32 m0, s43, 0xe000
	s_nop 0
	global_load_lds_dwordx4 v[172:173], off
	s_waitcnt lgkmcnt(8)
	s_barrier
	s_setprio 0
	s_waitcnt lgkmcnt(7)
	v_mfma_f32_16x16x32_bf16 v[126:129], v[156:159], v[176:179], 0
	v_mfma_f32_16x16x32_bf16 v[122:125], v[164:167], v[176:179], 0
	s_waitcnt lgkmcnt(5)
	v_mfma_f32_16x16x32_bf16 v[118:121], v[156:159], v[184:187], 0
	v_mfma_f32_16x16x32_bf16 v[114:117], v[164:167], v[184:187], 0
	s_waitcnt lgkmcnt(3)
	v_mfma_f32_16x16x32_bf16 v[110:113], v[156:159], v[192:195], 0
	v_mfma_f32_16x16x32_bf16 v[106:109], v[164:167], v[192:195], 0
	s_waitcnt lgkmcnt(1)
	v_mfma_f32_16x16x32_bf16 v[98:101], v[156:159], v[200:203], 0
	v_mfma_f32_16x16x32_bf16 v[90:93], v[164:167], v[200:203], 0
	v_mfma_f32_16x16x32_bf16 v[126:129], v[160:163], v[180:183], v[126:129]
	v_mfma_f32_16x16x32_bf16 v[122:125], v[168:171], v[180:183], v[122:125]
	v_mfma_f32_16x16x32_bf16 v[118:121], v[160:163], v[188:191], v[118:121]
	v_mfma_f32_16x16x32_bf16 v[114:117], v[168:171], v[188:191], v[114:117]
	v_mfma_f32_16x16x32_bf16 v[110:113], v[160:163], v[196:199], v[110:113]
	v_mfma_f32_16x16x32_bf16 v[106:109], v[168:171], v[196:199], v[106:109]
	s_waitcnt lgkmcnt(0)
	v_mfma_f32_16x16x32_bf16 v[98:101], v[160:163], v[204:207], v[98:101]
	v_mfma_f32_16x16x32_bf16 v[90:93], v[168:171], v[204:207], v[90:93]
	s_setprio 1
	s_barrier
	s_add_i32 s64, 0, 0x14000
	s_add_i32 s63, s63, s37
	v_add_u32_e32 v155, s64, v152
	v_lshl_add_u64 v[172:173], s[24:25], 0, v[48:49]
	s_mov_b32 m0, s63
	ds_read_b128 v[208:211], v155
	ds_read_b128 v[212:215], v155 offset:1024
	ds_read_b128 v[216:219], v155 offset:2048
	ds_read_b128 v[234:237], v155 offset:3072
	global_load_lds_dwordx4 v[172:173], off
	v_lshl_add_u64 v[224:225], s[24:25], 0, v[130:131]
	s_add_i32 m0, s63, 0x2000
	s_nop 0
	global_load_lds_dwordx4 v[224:225], off
	s_barrier
	s_setprio 0
	s_waitcnt lgkmcnt(3)
	v_mfma_f32_16x16x32_bf16 v[102:105], v[208:211], v[176:179], 0
	s_waitcnt lgkmcnt(1)
	v_mfma_f32_16x16x32_bf16 v[94:97], v[216:219], v[176:179], 0
	v_mfma_f32_16x16x32_bf16 v[86:89], v[208:211], v[184:187], 0
	v_mfma_f32_16x16x32_bf16 v[82:85], v[216:219], v[184:187], 0
	v_mfma_f32_16x16x32_bf16 v[78:81], v[208:211], v[192:195], 0
	v_mfma_f32_16x16x32_bf16 v[74:77], v[216:219], v[192:195], 0
	v_mfma_f32_16x16x32_bf16 v[70:73], v[208:211], v[200:203], 0
	v_mfma_f32_16x16x32_bf16 v[66:69], v[216:219], v[200:203], 0
	v_mfma_f32_16x16x32_bf16 v[102:105], v[212:215], v[180:183], v[102:105]
	s_waitcnt lgkmcnt(0)
	v_mfma_f32_16x16x32_bf16 v[94:97], v[234:237], v[180:183], v[94:97]
	v_mfma_f32_16x16x32_bf16 v[86:89], v[212:215], v[188:191], v[86:89]
	v_mfma_f32_16x16x32_bf16 v[82:85], v[234:237], v[188:191], v[82:85]
	v_mfma_f32_16x16x32_bf16 v[78:81], v[212:215], v[196:199], v[78:81]
	v_mfma_f32_16x16x32_bf16 v[74:77], v[234:237], v[196:199], v[74:77]
	v_mfma_f32_16x16x32_bf16 v[70:73], v[212:215], v[204:207], v[70:73]
	v_mfma_f32_16x16x32_bf16 v[66:69], v[234:237], v[204:207], v[66:69]
	s_setprio 1
	s_mov_b32 m0, s43
	v_lshl_add_u64 v[228:229], s[22:23], 0, v[48:49]
	s_barrier
	ds_read_b128 v[176:179], v154 offset:16384
	ds_read_b128 v[180:183], v154 offset:17408
	ds_read_b128 v[184:187], v154 offset:18432
	ds_read_b128 v[188:191], v154 offset:19456
	ds_read_b128 v[192:195], v154 offset:20480
	ds_read_b128 v[196:199], v154 offset:21504
	ds_read_b128 v[200:203], v154 offset:22528
	ds_read_b128 v[204:207], v154 offset:23552
	global_load_lds_dwordx4 v[228:229], off
	v_lshl_add_u64 v[238:239], s[22:23], 0, v[130:131]
	s_mov_b32 m0, s44
	s_nop 0
	global_load_lds_dwordx4 v[238:239], off
	s_barrier
	s_setprio 0
	s_waitcnt lgkmcnt(7)
	v_mfma_f32_16x16x32_bf16 v[62:65], v[156:159], v[176:179], 0
	v_mfma_f32_16x16x32_bf16 v[58:61], v[164:167], v[176:179], 0
	s_waitcnt lgkmcnt(5)
	v_mfma_f32_16x16x32_bf16 v[54:57], v[156:159], v[184:187], 0
	v_mfma_f32_16x16x32_bf16 v[50:53], v[164:167], v[184:187], 0
	s_waitcnt lgkmcnt(3)
	v_mfma_f32_16x16x32_bf16 v[44:47], v[156:159], v[192:195], 0
	v_mfma_f32_16x16x32_bf16 v[40:43], v[164:167], v[192:195], 0
	s_waitcnt lgkmcnt(1)
	v_mfma_f32_16x16x32_bf16 v[32:35], v[156:159], v[200:203], 0
	v_mfma_f32_16x16x32_bf16 v[24:27], v[164:167], v[200:203], 0
	v_mfma_f32_16x16x32_bf16 v[62:65], v[160:163], v[180:183], v[62:65]
	v_mfma_f32_16x16x32_bf16 v[58:61], v[168:171], v[180:183], v[58:61]
	v_mfma_f32_16x16x32_bf16 v[54:57], v[160:163], v[188:191], v[54:57]
	v_mfma_f32_16x16x32_bf16 v[50:53], v[168:171], v[188:191], v[50:53]
	v_mfma_f32_16x16x32_bf16 v[44:47], v[160:163], v[196:199], v[44:47]
	v_mfma_f32_16x16x32_bf16 v[40:43], v[168:171], v[196:199], v[40:43]
	s_waitcnt lgkmcnt(0)
	v_mfma_f32_16x16x32_bf16 v[32:35], v[160:163], v[204:207], v[32:35]
	v_mfma_f32_16x16x32_bf16 v[24:27], v[168:171], v[204:207], v[24:27]
	s_setprio 1
	s_barrier
; #define PG8_STAGE(bufoff, gbase, voff) do { _Pragma("unroll") for (int _i = 0; _i < 2; ++_i) \
;         __builtin_amdgcn_global_load_lds((const unsigned*)((const char*)(gbase) + (voff)[_i]), (PG8_LAS unsigned*)(lds + (bufoff) + ldsw + _i * 8192), 16, 0, 0); } while (0)
; #define PG8_LDA(dst, b, h) do { _Pragma("unroll") for (int m = 0; m < 4; ++m) _Pragma("unroll") for (int k = 0; k < 2; ++k) dst[m][k] = *(const PG8_LAS bf16x8*)(lds + PG8_SA(b, h) + aoff + m * 2048 + k * 1024); } while (0)
; #define PG8_LDB(dst, b, h) do { _Pragma("unroll") for (int n = 0; n < 2; ++n) _Pragma("unroll") for (int k = 0; k < 2; ++k) dst[n][k] = *(const PG8_LAS bf16x8*)(lds + PG8_SB(b, h) + boff + n * 2048 + k * 1024); } while (0)
; #define PG8_MMA(ai, bj, At, Bt) do { __builtin_amdgcn_s_setprio(1); _Pragma("unroll") for (int m = 0; m < 4; ++m) _Pragma("unroll") for (int n = 0; n < 2; ++n) _Pragma("unroll") for (int k = 0; k < 2; ++k) \
;         acc[ai][bj][m][n] = __builtin_amdgcn_mfma_f32_16x16x32_bf16(Bt[n][k], At[m][k], acc[ai][bj][m][n], 0, 0, 0); __builtin_amdgcn_s_setprio(0); } while (0)
; #define PG8_WAIT_V(n) asm volatile("s_waitcnt vmcnt(" #n ")" ::: "memory")
; #define PG8_WAIT_L(n) asm volatile("s_waitcnt lgkmcnt(" #n ")" ::: "memory")
; #define PG8_BAR __builtin_amdgcn_s_barrier()
; #define PG8_SCHED __builtin_amdgcn_sched_barrier(0)
; template <class Epi, class Sched>
; __device__ __forceinline__ void gemm_phase(PG8_LAS unsigned char* lds, const Gemm g, const Sched& S, const Epi& E) {
;     ...
;             PG8_STAGE(PG8_SB(0, 1), b2 + hstep, voffB);
;             PG8_WAIT_V(6); PG8_BAR; PG8_MMA(1, 1, At, B1); PG8_BAR;
;             PG8_LDB(B0, 1, 0); PG8_SCHED; PG8_LDA(At, 1, 0); PG8_STAGE(PG8_SA(0, 1), a2 + hstep, voffA);
;             PG8_WAIT_L(8); PG8_BAR; PG8_WAIT_L(0); PG8_MMA(0, 0, At, B0); PG8_BAR; PG8_SCHED;
;             PG8_LDB(B1, 1, 1); PG8_STAGE(PG8_SB(1, 0), b3, voffB);
;             PG8_BAR; PG8_WAIT_L(0); PG8_MMA(0, 1, At, B1); PG8_BAR;
;             PG8_LDA(At, 1, 1); PG8_STAGE(PG8_SA(1, 0), a3, voffA);
	s_add_u32 s24, s24, s10
	s_addc_u32 s25, s25, 0
	s_add_i32 s63, s64, s37
	v_lshl_add_u64 v[240:241], s[24:25], 0, v[48:49]
	s_mov_b32 m0, s63
	v_lshl_add_u64 v[242:243], s[24:25], 0, v[130:131]
	global_load_lds_dwordx4 v[240:241], off
	s_add_i32 m0, s63, 0x2000
	s_nop 0
	global_load_lds_dwordx4 v[242:243], off
	s_waitcnt vmcnt(6)
	s_barrier
	s_setprio 0
	v_mfma_f32_16x16x32_bf16 v[36:39], v[208:211], v[176:179], 0
	v_mfma_f32_16x16x32_bf16 v[28:31], v[216:219], v[176:179], 0
	v_mfma_f32_16x16x32_bf16 v[20:23], v[208:211], v[184:187], 0
	v_mfma_f32_16x16x32_bf16 v[16:19], v[216:219], v[184:187], 0
	v_mfma_f32_16x16x32_bf16 v[12:15], v[208:211], v[192:195], 0
	v_mfma_f32_16x16x32_bf16 v[8:11], v[216:219], v[192:195], 0
	v_mfma_f32_16x16x32_bf16 v[4:7], v[208:211], v[200:203], 0
	v_mfma_f32_16x16x32_bf16 v[0:3], v[216:219], v[200:203], 0
	v_mfma_f32_16x16x32_bf16 v[36:39], v[212:215], v[180:183], v[36:39]
	v_mfma_f32_16x16x32_bf16 v[28:31], v[234:237], v[180:183], v[28:31]
	v_mfma_f32_16x16x32_bf16 v[20:23], v[212:215], v[188:191], v[20:23]
	v_mfma_f32_16x16x32_bf16 v[16:19], v[234:237], v[188:191], v[16:19]
	v_mfma_f32_16x16x32_bf16 v[12:15], v[212:215], v[196:199], v[12:15]
	v_mfma_f32_16x16x32_bf16 v[8:11], v[234:237], v[196:199], v[8:11]
	v_mfma_f32_16x16x32_bf16 v[4:7], v[212:215], v[204:207], v[4:7]
	v_mfma_f32_16x16x32_bf16 v[0:3], v[234:237], v[204:207], v[0:3]
	s_setprio 1
	s_add_i32 s24, 0, 0x18000
	v_add_u32_e32 v155, s24, v152
	s_barrier
	ds_read_b128 v[156:159], v155
	ds_read_b128 v[160:163], v155 offset:1024
	ds_read_b128 v[164:167], v155 offset:2048
	ds_read_b128 v[168:171], v155 offset:3072
	s_add_u32 s22, s22, s10
	s_addc_u32 s23, s23, 0
	s_mov_b32 m0, s46
	v_lshl_add_u64 v[208:209], s[22:23], 0, v[48:49]
	ds_read_b128 v[176:179], v154 offset:32768
	ds_read_b128 v[180:183], v154 offset:33792
	ds_read_b128 v[184:187], v154 offset:34816
	ds_read_b128 v[188:191], v154 offset:35840
	ds_read_b128 v[192:195], v154 offset:36864
	ds_read_b128 v[196:199], v154 offset:37888
	ds_read_b128 v[200:203], v154 offset:38912
	ds_read_b128 v[204:207], v154 offset:39936
	global_load_lds_dwordx4 v[208:209], off
	v_lshl_add_u64 v[208:209], s[22:23], 0, v[130:131]
	s_mov_b32 m0, s47
	s_nop 0
	global_load_lds_dwordx4 v[208:209], off
	s_waitcnt lgkmcnt(8)
	s_barrier
	s_setprio 0
	s_waitcnt lgkmcnt(7)
	v_mfma_f32_16x16x32_bf16 v[126:129], v[156:159], v[176:179], v[126:129]
	v_mfma_f32_16x16x32_bf16 v[122:125], v[164:167], v[176:179], v[122:125]
	s_waitcnt lgkmcnt(5)
	v_mfma_f32_16x16x32_bf16 v[118:121], v[156:159], v[184:187], v[118:121]
	v_mfma_f32_16x16x32_bf16 v[114:117], v[164:167], v[184:187], v[114:117]
	s_waitcnt lgkmcnt(3)
	v_mfma_f32_16x16x32_bf16 v[110:113], v[156:159], v[192:195], v[110:113]
	v_mfma_f32_16x16x32_bf16 v[106:109], v[164:167], v[192:195], v[106:109]
	s_waitcnt lgkmcnt(1)
	v_mfma_f32_16x16x32_bf16 v[98:101], v[156:159], v[200:203], v[98:101]
	v_mfma_f32_16x16x32_bf16 v[90:93], v[164:167], v[200:203], v[90:93]
	v_mfma_f32_16x16x32_bf16 v[126:129], v[160:163], v[180:183], v[126:129]
	v_mfma_f32_16x16x32_bf16 v[122:125], v[168:171], v[180:183], v[122:125]
	v_mfma_f32_16x16x32_bf16 v[118:121], v[160:163], v[188:191], v[118:121]
	v_mfma_f32_16x16x32_bf16 v[114:117], v[168:171], v[188:191], v[114:117]
	v_mfma_f32_16x16x32_bf16 v[110:113], v[160:163], v[196:199], v[110:113]
	v_mfma_f32_16x16x32_bf16 v[106:109], v[168:171], v[196:199], v[106:109]
	s_waitcnt lgkmcnt(0)
	v_mfma_f32_16x16x32_bf16 v[98:101], v[160:163], v[204:207], v[98:101]
	v_mfma_f32_16x16x32_bf16 v[90:93], v[168:171], v[204:207], v[90:93]
	s_setprio 1
	s_barrier
	s_add_i32 s22, 0, 0x1c000
	s_add_i32 s23, s24, s37
	v_add_u32_e32 v155, s22, v152
	v_lshl_add_u64 v[172:173], v[172:173], 0, s[0:1]
	s_mov_b32 m0, s23
	ds_read_b128 v[208:211], v155
	ds_read_b128 v[212:215], v155 offset:1024
	ds_read_b128 v[216:219], v155 offset:2048
	ds_read_b128 v[234:237], v155 offset:3072
	global_load_lds_dwordx4 v[172:173], off
	v_lshl_add_u64 v[172:173], v[224:225], 0, s[0:1]
	s_add_i32 m0, s23, 0x2000
	s_nop 0
	global_load_lds_dwordx4 v[172:173], off
	s_barrier
	s_setprio 0
	s_waitcnt lgkmcnt(3)
	v_mfma_f32_16x16x32_bf16 v[102:105], v[208:211], v[176:179], v[102:105]
	s_waitcnt lgkmcnt(1)
	v_mfma_f32_16x16x32_bf16 v[94:97], v[216:219], v[176:179], v[94:97]
	v_mfma_f32_16x16x32_bf16 v[86:89], v[208:211], v[184:187], v[86:89]
	v_mfma_f32_16x16x32_bf16 v[82:85], v[216:219], v[184:187], v[82:85]
	v_mfma_f32_16x16x32_bf16 v[78:81], v[208:211], v[192:195], v[78:81]
	v_mfma_f32_16x16x32_bf16 v[74:77], v[216:219], v[192:195], v[74:77]
	v_mfma_f32_16x16x32_bf16 v[70:73], v[208:211], v[200:203], v[70:73]
	v_mfma_f32_16x16x32_bf16 v[66:69], v[216:219], v[200:203], v[66:69]
	v_mfma_f32_16x16x32_bf16 v[102:105], v[212:215], v[180:183], v[102:105]
	s_waitcnt lgkmcnt(0)
	v_mfma_f32_16x16x32_bf16 v[94:97], v[234:237], v[180:183], v[94:97]
	v_mfma_f32_16x16x32_bf16 v[86:89], v[212:215], v[188:191], v[86:89]
	v_mfma_f32_16x16x32_bf16 v[82:85], v[234:237], v[188:191], v[82:85]
	v_mfma_f32_16x16x32_bf16 v[78:81], v[212:215], v[196:199], v[78:81]
	v_mfma_f32_16x16x32_bf16 v[74:77], v[234:237], v[196:199], v[74:77]
	v_mfma_f32_16x16x32_bf16 v[70:73], v[212:215], v[204:207], v[70:73]
	v_mfma_f32_16x16x32_bf16 v[66:69], v[234:237], v[204:207], v[66:69]
	s_setprio 1
	s_mov_b32 m0, s50
	v_lshl_add_u64 v[172:173], v[228:229], 0, s[0:1]
	s_barrier
	ds_read_b128 v[176:179], v154 offset:49152
	ds_read_b128 v[180:183], v154 offset:50176
	ds_read_b128 v[184:187], v154 offset:51200
	ds_read_b128 v[188:191], v154 offset:52224
	ds_read_b128 v[192:195], v154 offset:53248
	ds_read_b128 v[196:199], v154 offset:54272
	ds_read_b128 v[200:203], v154 offset:55296
	ds_read_b128 v[204:207], v154 offset:56320
	global_load_lds_dwordx4 v[172:173], off
	v_lshl_add_u64 v[172:173], v[238:239], 0, s[0:1]
	s_mov_b32 m0, s51
	s_nop 0
	global_load_lds_dwordx4 v[172:173], off
	s_barrier
; #define PG8_STAGE(bufoff, gbase, voff) do { _Pragma("unroll") for (int _i = 0; _i < 2; ++_i) \
;         __builtin_amdgcn_global_load_lds((const unsigned*)((const char*)(gbase) + (voff)[_i]), (PG8_LAS unsigned*)(lds + (bufoff) + ldsw + _i * 8192), 16, 0, 0); } while (0)
; #define PG8_LDA(dst, b, h) do { _Pragma("unroll") for (int m = 0; m < 4; ++m) _Pragma("unroll") for (int k = 0; k < 2; ++k) dst[m][k] = *(const PG8_LAS bf16x8*)(lds + PG8_SA(b, h) + aoff + m * 2048 + k * 1024); } while (0)
; #define PG8_LDB(dst, b, h) do { _Pragma("unroll") for (int n = 0; n < 2; ++n) _Pragma("unroll") for (int k = 0; k < 2; ++k) dst[n][k] = *(const PG8_LAS bf16x8*)(lds + PG8_SB(b, h) + boff + n * 2048 + k * 1024); } while (0)
; #define PG8_WAIT_V(n) asm volatile("s_waitcnt vmcnt(" #n ")" ::: "memory")
; #define PG8_WAIT_L(n) asm volatile("s_waitcnt lgkmcnt(" #n ")" ::: "memory")
; #define PG8_BAR __builtin_amdgcn_s_barrier()
; #define PG8_SCHED __builtin_amdgcn_sched_barrier(0)
; template <class Epi, class Sched>
; __device__ __forceinline__ void gemm_phase(PG8_LAS unsigned char* lds, const Gemm g, const Sched& S, const Epi& E) {
;     ...
;             PG8_LDB(B0, 0, 0); PG8_SCHED; PG8_LDA(At, 0, 0); PG8_STAGE(PG8_SA(1, 1), a1 + hstep, voffA);
;             PG8_WAIT_L(8); PG8_BAR; PG8_WAIT_L(0); PG8_MMA(0, 0, At, B0); PG8_BAR; PG8_SCHED;
;             PG8_LDB(B1, 0, 1); PG8_STAGE(PG8_SB(0, 0), b2, voffB);
;             PG8_BAR; PG8_WAIT_L(0); PG8_MMA(0, 1, At, B1); PG8_BAR;
;             PG8_LDA(At, 0, 1); PG8_STAGE(PG8_SA(0, 0), a2, voffA);
;             PG8_BAR; PG8_WAIT_L(0); PG8_MMA(1, 0, At, B0); PG8_BAR; PG8_SCHED;
;             PG8_STAGE(PG8_SB(0, 1), b2 + hstep, voffB);
;             PG8_WAIT_V(6); PG8_BAR; PG8_MMA(1, 1, At, B1); PG8_BAR;
;             PG8_LDB(B0, 1, 0); PG8_SCHED; PG8_LDA(At, 1, 0); PG8_STAGE(PG8_SA(0, 1), a2 + hstep, voffA);
;             PG8_WAIT_L(8); PG8_BAR; PG8_WAIT_L(0); PG8_MMA(0, 0, At, B0); PG8_BAR; PG8_SCHED;
;             PG8_LDB(B1, 1, 1); PG8_STAGE(PG8_SB(1, 0), b3, voffB);
;             PG8_BAR; PG8_WAIT_L(0); PG8_MMA(0, 1, At, B1); PG8_BAR;
;             PG8_LDA(At, 1, 1); PG8_STAGE(PG8_SA(1, 0), a3, voffA);
;             PG8_BAR; PG8_WAIT_L(0); PG8_MMA(1, 0, At, B0); PG8_BAR; PG8_SCHED;
;             PG8_STAGE(PG8_SB(1, 1), b3 + hstep, voffB);
;             PG8_WAIT_V(6); PG8_BAR; PG8_MMA(1, 1, At, B1); PG8_BAR;
	s_setprio 0
	s_waitcnt lgkmcnt(7)
	v_mfma_f32_16x16x32_bf16 v[62:65], v[156:159], v[176:179], v[62:65]
	v_mfma_f32_16x16x32_bf16 v[58:61], v[164:167], v[176:179], v[58:61]
	s_waitcnt lgkmcnt(5)
	v_mfma_f32_16x16x32_bf16 v[54:57], v[156:159], v[184:187], v[54:57]
	v_mfma_f32_16x16x32_bf16 v[50:53], v[164:167], v[184:187], v[50:53]
	s_waitcnt lgkmcnt(3)
	v_mfma_f32_16x16x32_bf16 v[44:47], v[156:159], v[192:195], v[44:47]
	v_mfma_f32_16x16x32_bf16 v[40:43], v[164:167], v[192:195], v[40:43]
	s_waitcnt lgkmcnt(1)
	v_mfma_f32_16x16x32_bf16 v[32:35], v[156:159], v[200:203], v[32:35]
	v_mfma_f32_16x16x32_bf16 v[24:27], v[164:167], v[200:203], v[24:27]
	v_mfma_f32_16x16x32_bf16 v[62:65], v[160:163], v[180:183], v[62:65]
	v_mfma_f32_16x16x32_bf16 v[58:61], v[168:171], v[180:183], v[58:61]
	v_mfma_f32_16x16x32_bf16 v[54:57], v[160:163], v[188:191], v[54:57]
	v_mfma_f32_16x16x32_bf16 v[50:53], v[168:171], v[188:191], v[50:53]
	v_mfma_f32_16x16x32_bf16 v[44:47], v[160:163], v[196:199], v[44:47]
	v_mfma_f32_16x16x32_bf16 v[40:43], v[168:171], v[196:199], v[40:43]
	s_waitcnt lgkmcnt(0)
	v_mfma_f32_16x16x32_bf16 v[32:35], v[160:163], v[204:207], v[32:35]
	v_mfma_f32_16x16x32_bf16 v[24:27], v[168:171], v[204:207], v[24:27]
	s_setprio 1
	s_barrier
	s_add_i32 s22, s22, s37
	v_lshl_add_u64 v[156:157], v[240:241], 0, s[0:1]
	s_mov_b32 m0, s22
	s_nop 0
	global_load_lds_dwordx4 v[156:157], off
	v_lshl_add_u64 v[156:157], v[242:243], 0, s[0:1]
	s_add_i32 m0, s22, 0x2000
	s_nop 0
	global_load_lds_dwordx4 v[156:157], off
	s_waitcnt vmcnt(6)
	s_barrier
	s_setprio 0
	v_mfma_f32_16x16x32_bf16 v[36:39], v[208:211], v[176:179], v[36:39]
	v_mfma_f32_16x16x32_bf16 v[28:31], v[216:219], v[176:179], v[28:31]
	v_mfma_f32_16x16x32_bf16 v[20:23], v[208:211], v[184:187], v[20:23]
	v_mfma_f32_16x16x32_bf16 v[16:19], v[216:219], v[184:187], v[16:19]
	v_mfma_f32_16x16x32_bf16 v[12:15], v[208:211], v[192:195], v[12:15]
	v_mfma_f32_16x16x32_bf16 v[8:11], v[216:219], v[192:195], v[8:11]
	v_mfma_f32_16x16x32_bf16 v[4:7], v[208:211], v[200:203], v[4:7]
	v_mfma_f32_16x16x32_bf16 v[0:3], v[216:219], v[200:203], v[0:3]
	v_mfma_f32_16x16x32_bf16 v[36:39], v[212:215], v[180:183], v[36:39]
	v_mfma_f32_16x16x32_bf16 v[28:31], v[234:237], v[180:183], v[28:31]
	v_mfma_f32_16x16x32_bf16 v[20:23], v[212:215], v[188:191], v[20:23]
	v_mfma_f32_16x16x32_bf16 v[16:19], v[234:237], v[188:191], v[16:19]
	v_mfma_f32_16x16x32_bf16 v[12:15], v[212:215], v[196:199], v[12:15]
	v_mfma_f32_16x16x32_bf16 v[8:11], v[234:237], v[196:199], v[8:11]
	v_mfma_f32_16x16x32_bf16 v[4:7], v[212:215], v[204:207], v[4:7]
	v_mfma_f32_16x16x32_bf16 v[0:3], v[234:237], v[204:207], v[0:3]
	s_setprio 1
	s_add_u32 s20, s20, 0x100
	s_addc_u32 s21, s21, 0
	s_add_u32 s3, s3, 0x100
	s_addc_u32 s40, s40, 0
	s_cmp_ge_u32 s41, s54
	s_mov_b32 s22, s41
	s_barrier
	s_cbranch_scc1 .Lkpeel_exit_288
.LBB0_288:
	s_add_i32 s41, s22, 2
	s_add_u32 s24, s20, 0x80
	s_addc_u32 s23, s21, 0
	s_add_i32 s63, 0, 0x10000
	v_add_u32_e32 v155, s63, v152
	ds_read_b128 v[156:159], v155
	ds_read_b128 v[160:163], v155 offset:1024
	ds_read_b128 v[164:167], v155 offset:2048
	ds_read_b128 v[168:171], v155 offset:3072
	s_cmp_eq_u32 s55, s22
	s_cselect_b32 s22, s12, s24
	s_cselect_b32 s23, s13, s23
	s_cselect_b32 s25, s17, s40
	s_cselect_b32 s24, s16, s3
	v_lshl_add_u64 v[172:173], s[20:21], 0, v[148:149]
	s_add_i32 m0, s43, 0xc000
	ds_read_b128 v[176:179], v154
	ds_read_b128 v[180:183], v154 offset:1024
	ds_read_b128 v[184:187], v154 offset:2048
	ds_read_b128 v[188:191], v154 offset:3072
	ds_read_b128 v[192:195], v154 offset:4096
	ds_read_b128 v[196:199], v154 offset:5120
	ds_read_b128 v[200:203], v154 offset:6144
	ds_read_b128 v[204:207], v154 offset:7168
	global_load_lds_dwordx4 v[172:173], off
	v_lshl_add_u64 v[172:173], s[20:21], 0, v[150:151]
	s_add_i32 m0, s43, 0xe000
	s_nop 0
	global_load_lds_dwordx4 v[172:173], off
	s_waitcnt lgkmcnt(8)
	s_barrier
	s_setprio 0
	s_waitcnt lgkmcnt(7)
	v_mfma_f32_16x16x32_bf16 v[126:129], v[156:159], v[176:179], v[126:129]
	v_mfma_f32_16x16x32_bf16 v[122:125], v[164:167], v[176:179], v[122:125]
	s_waitcnt lgkmcnt(5)
	v_mfma_f32_16x16x32_bf16 v[118:121], v[156:159], v[184:187], v[118:121]
	v_mfma_f32_16x16x32_bf16 v[114:117], v[164:167], v[184:187], v[114:117]
	s_waitcnt lgkmcnt(3)
	v_mfma_f32_16x16x32_bf16 v[110:113], v[156:159], v[192:195], v[110:113]
	v_mfma_f32_16x16x32_bf16 v[106:109], v[164:167], v[192:195], v[106:109]
	s_waitcnt lgkmcnt(1)
	v_mfma_f32_16x16x32_bf16 v[98:101], v[156:159], v[200:203], v[98:101]
	v_mfma_f32_16x16x32_bf16 v[90:93], v[164:167], v[200:203], v[90:93]
	v_mfma_f32_16x16x32_bf16 v[126:129], v[160:163], v[180:183], v[126:129]
	v_mfma_f32_16x16x32_bf16 v[122:125], v[168:171], v[180:183], v[122:125]
	v_mfma_f32_16x16x32_bf16 v[118:121], v[160:163], v[188:191], v[118:121]
	v_mfma_f32_16x16x32_bf16 v[114:117], v[168:171], v[188:191], v[114:117]
	v_mfma_f32_16x16x32_bf16 v[110:113], v[160:163], v[196:199], v[110:113]
	v_mfma_f32_16x16x32_bf16 v[106:109], v[168:171], v[196:199], v[106:109]
	s_waitcnt lgkmcnt(0)
	v_mfma_f32_16x16x32_bf16 v[98:101], v[160:163], v[204:207], v[98:101]
	v_mfma_f32_16x16x32_bf16 v[90:93], v[168:171], v[204:207], v[90:93]
	s_setprio 1
	s_barrier
	s_add_i32 s64, 0, 0x14000
	s_add_i32 s63, s63, s37
	v_add_u32_e32 v155, s64, v152
	v_lshl_add_u64 v[172:173], s[24:25], 0, v[48:49]
	s_mov_b32 m0, s63
	ds_read_b128 v[208:211], v155
	ds_read_b128 v[212:215], v155 offset:1024
	ds_read_b128 v[216:219], v155 offset:2048
	ds_read_b128 v[234:237], v155 offset:3072
	global_load_lds_dwordx4 v[172:173], off
	v_lshl_add_u64 v[224:225], s[24:25], 0, v[130:131]
	s_add_i32 m0, s63, 0x2000
	s_nop 0
	global_load_lds_dwordx4 v[224:225], off
	s_barrier
; #define PG8_STAGE(bufoff, gbase, voff) do { _Pragma("unroll") for (int _i = 0; _i < 2; ++_i) \
;         __builtin_amdgcn_global_load_lds((const unsigned*)((const char*)(gbase) + (voff)[_i]), (PG8_LAS unsigned*)(lds + (bufoff) + ldsw + _i * 8192), 16, 0, 0); } while (0)
; #define PG8_LDA(dst, b, h) do { _Pragma("unroll") for (int m = 0; m < 4; ++m) _Pragma("unroll") for (int k = 0; k < 2; ++k) dst[m][k] = *(const PG8_LAS bf16x8*)(lds + PG8_SA(b, h) + aoff + m * 2048 + k * 1024); } while (0)
; #define PG8_LDB(dst, b, h) do { _Pragma("unroll") for (int n = 0; n < 2; ++n) _Pragma("unroll") for (int k = 0; k < 2; ++k) dst[n][k] = *(const PG8_LAS bf16x8*)(lds + PG8_SB(b, h) + boff + n * 2048 + k * 1024); } while (0)
; #define PG8_MMA(ai, bj, At, Bt) do { __builtin_amdgcn_s_setprio(1); _Pragma("unroll") for (int m = 0; m < 4; ++m) _Pragma("unroll") for (int n = 0; n < 2; ++n) _Pragma("unroll") for (int k = 0; k < 2; ++k) \
;         acc[ai][bj][m][n] = __builtin_amdgcn_mfma_f32_16x16x32_bf16(Bt[n][k], At[m][k], acc[ai][bj][m][n], 0, 0, 0); __builtin_amdgcn_s_setprio(0); } while (0)
; #define PG8_WAIT_V(n) asm volatile("s_waitcnt vmcnt(" #n ")" ::: "memory")
; #define PG8_WAIT_L(n) asm volatile("s_waitcnt lgkmcnt(" #n ")" ::: "memory")
; #define PG8_BAR __builtin_amdgcn_s_barrier()
; #define PG8_SCHED __builtin_amdgcn_sched_barrier(0)
; template <class Epi, class Sched>
; __device__ __forceinline__ void gemm_phase(PG8_LAS unsigned char* lds, const Gemm g, const Sched& S, const Epi& E) {
;     ...
;             PG8_BAR; PG8_WAIT_L(0); PG8_MMA(0, 1, At, B1); PG8_BAR;
;             PG8_LDA(At, 0, 1); PG8_STAGE(PG8_SA(0, 0), a2, voffA);
;             PG8_BAR; PG8_WAIT_L(0); PG8_MMA(1, 0, At, B0); PG8_BAR; PG8_SCHED;
;             PG8_STAGE(PG8_SB(0, 1), b2 + hstep, voffB);
;             PG8_WAIT_V(6); PG8_BAR; PG8_MMA(1, 1, At, B1); PG8_BAR;
;             PG8_LDB(B0, 1, 0); PG8_SCHED; PG8_LDA(At, 1, 0); PG8_STAGE(PG8_SA(0, 1), a2 + hstep, voffA);
;             PG8_WAIT_L(8); PG8_BAR; PG8_WAIT_L(0); PG8_MMA(0, 0, At, B0); PG8_BAR; PG8_SCHED;
	s_setprio 0
	s_waitcnt lgkmcnt(3)
	v_mfma_f32_16x16x32_bf16 v[102:105], v[208:211], v[176:179], v[102:105]
	s_waitcnt lgkmcnt(1)
	v_mfma_f32_16x16x32_bf16 v[94:97], v[216:219], v[176:179], v[94:97]
	v_mfma_f32_16x16x32_bf16 v[86:89], v[208:211], v[184:187], v[86:89]
	v_mfma_f32_16x16x32_bf16 v[82:85], v[216:219], v[184:187], v[82:85]
	v_mfma_f32_16x16x32_bf16 v[78:81], v[208:211], v[192:195], v[78:81]
	v_mfma_f32_16x16x32_bf16 v[74:77], v[216:219], v[192:195], v[74:77]
	v_mfma_f32_16x16x32_bf16 v[70:73], v[208:211], v[200:203], v[70:73]
	v_mfma_f32_16x16x32_bf16 v[66:69], v[216:219], v[200:203], v[66:69]
	v_mfma_f32_16x16x32_bf16 v[102:105], v[212:215], v[180:183], v[102:105]
	s_waitcnt lgkmcnt(0)
	v_mfma_f32_16x16x32_bf16 v[94:97], v[234:237], v[180:183], v[94:97]
	v_mfma_f32_16x16x32_bf16 v[86:89], v[212:215], v[188:191], v[86:89]
	v_mfma_f32_16x16x32_bf16 v[82:85], v[234:237], v[188:191], v[82:85]
	v_mfma_f32_16x16x32_bf16 v[78:81], v[212:215], v[196:199], v[78:81]
	v_mfma_f32_16x16x32_bf16 v[74:77], v[234:237], v[196:199], v[74:77]
	v_mfma_f32_16x16x32_bf16 v[70:73], v[212:215], v[204:207], v[70:73]
	v_mfma_f32_16x16x32_bf16 v[66:69], v[234:237], v[204:207], v[66:69]
	s_setprio 1
	s_mov_b32 m0, s43
	v_lshl_add_u64 v[228:229], s[22:23], 0, v[48:49]
	s_barrier
	ds_read_b128 v[176:179], v154 offset:16384
	ds_read_b128 v[180:183], v154 offset:17408
	ds_read_b128 v[184:187], v154 offset:18432
	ds_read_b128 v[188:191], v154 offset:19456
	ds_read_b128 v[192:195], v154 offset:20480
	ds_read_b128 v[196:199], v154 offset:21504
	ds_read_b128 v[200:203], v154 offset:22528
	ds_read_b128 v[204:207], v154 offset:23552
	global_load_lds_dwordx4 v[228:229], off
	v_lshl_add_u64 v[238:239], s[22:23], 0, v[130:131]
	s_mov_b32 m0, s44
	s_nop 0
	global_load_lds_dwordx4 v[238:239], off
	s_barrier
	s_setprio 0
	s_waitcnt lgkmcnt(7)
	v_mfma_f32_16x16x32_bf16 v[62:65], v[156:159], v[176:179], v[62:65]
	v_mfma_f32_16x16x32_bf16 v[58:61], v[164:167], v[176:179], v[58:61]
	s_waitcnt lgkmcnt(5)
	v_mfma_f32_16x16x32_bf16 v[54:57], v[156:159], v[184:187], v[54:57]
	v_mfma_f32_16x16x32_bf16 v[50:53], v[164:167], v[184:187], v[50:53]
	s_waitcnt lgkmcnt(3)
	v_mfma_f32_16x16x32_bf16 v[44:47], v[156:159], v[192:195], v[44:47]
	v_mfma_f32_16x16x32_bf16 v[40:43], v[164:167], v[192:195], v[40:43]
	s_waitcnt lgkmcnt(1)
	v_mfma_f32_16x16x32_bf16 v[32:35], v[156:159], v[200:203], v[32:35]
	v_mfma_f32_16x16x32_bf16 v[24:27], v[164:167], v[200:203], v[24:27]
	v_mfma_f32_16x16x32_bf16 v[62:65], v[160:163], v[180:183], v[62:65]
	v_mfma_f32_16x16x32_bf16 v[58:61], v[168:171], v[180:183], v[58:61]
	v_mfma_f32_16x16x32_bf16 v[54:57], v[160:163], v[188:191], v[54:57]
	v_mfma_f32_16x16x32_bf16 v[50:53], v[168:171], v[188:191], v[50:53]
	v_mfma_f32_16x16x32_bf16 v[44:47], v[160:163], v[196:199], v[44:47]
	v_mfma_f32_16x16x32_bf16 v[40:43], v[168:171], v[196:199], v[40:43]
	s_waitcnt lgkmcnt(0)
	v_mfma_f32_16x16x32_bf16 v[32:35], v[160:163], v[204:207], v[32:35]
	v_mfma_f32_16x16x32_bf16 v[24:27], v[168:171], v[204:207], v[24:27]
	s_setprio 1
	s_barrier
	s_add_u32 s24, s24, s10
	s_addc_u32 s25, s25, 0
	s_add_i32 s63, s64, s37
	v_lshl_add_u64 v[240:241], s[24:25], 0, v[48:49]
	s_mov_b32 m0, s63
	v_lshl_add_u64 v[242:243], s[24:25], 0, v[130:131]
	global_load_lds_dwordx4 v[240:241], off
	s_add_i32 m0, s63, 0x2000
	s_nop 0
	global_load_lds_dwordx4 v[242:243], off
	s_waitcnt vmcnt(6)
	s_barrier
	s_setprio 0
	v_mfma_f32_16x16x32_bf16 v[36:39], v[208:211], v[176:179], v[36:39]
	v_mfma_f32_16x16x32_bf16 v[28:31], v[216:219], v[176:179], v[28:31]
	v_mfma_f32_16x16x32_bf16 v[20:23], v[208:211], v[184:187], v[20:23]
	v_mfma_f32_16x16x32_bf16 v[16:19], v[216:219], v[184:187], v[16:19]
	v_mfma_f32_16x16x32_bf16 v[12:15], v[208:211], v[192:195], v[12:15]
	v_mfma_f32_16x16x32_bf16 v[8:11], v[216:219], v[192:195], v[8:11]
	v_mfma_f32_16x16x32_bf16 v[4:7], v[208:211], v[200:203], v[4:7]
	v_mfma_f32_16x16x32_bf16 v[0:3], v[216:219], v[200:203], v[0:3]
	v_mfma_f32_16x16x32_bf16 v[36:39], v[212:215], v[180:183], v[36:39]
	v_mfma_f32_16x16x32_bf16 v[28:31], v[234:237], v[180:183], v[28:31]
	v_mfma_f32_16x16x32_bf16 v[20:23], v[212:215], v[188:191], v[20:23]
	v_mfma_f32_16x16x32_bf16 v[16:19], v[234:237], v[188:191], v[16:19]
	v_mfma_f32_16x16x32_bf16 v[12:15], v[212:215], v[196:199], v[12:15]
	v_mfma_f32_16x16x32_bf16 v[8:11], v[234:237], v[196:199], v[8:11]
	v_mfma_f32_16x16x32_bf16 v[4:7], v[212:215], v[204:207], v[4:7]
	v_mfma_f32_16x16x32_bf16 v[0:3], v[234:237], v[204:207], v[0:3]
	s_setprio 1
	s_add_i32 s24, 0, 0x18000
	v_add_u32_e32 v155, s24, v152
	s_barrier
	ds_read_b128 v[156:159], v155
	ds_read_b128 v[160:163], v155 offset:1024
	ds_read_b128 v[164:167], v155 offset:2048
	ds_read_b128 v[168:171], v155 offset:3072
	s_add_u32 s22, s22, s10
	s_addc_u32 s23, s23, 0
	s_mov_b32 m0, s46
	v_lshl_add_u64 v[208:209], s[22:23], 0, v[48:49]
	ds_read_b128 v[176:179], v154 offset:32768
	ds_read_b128 v[180:183], v154 offset:33792
	ds_read_b128 v[184:187], v154 offset:34816
	ds_read_b128 v[188:191], v154 offset:35840
	ds_read_b128 v[192:195], v154 offset:36864
	ds_read_b128 v[196:199], v154 offset:37888
	ds_read_b128 v[200:203], v154 offset:38912
	ds_read_b128 v[204:207], v154 offset:39936
	global_load_lds_dwordx4 v[208:209], off
	v_lshl_add_u64 v[208:209], s[22:23], 0, v[130:131]
	s_mov_b32 m0, s47
	s_nop 0
	global_load_lds_dwordx4 v[208:209], off
	s_waitcnt lgkmcnt(8)
	s_barrier
; #define PG8_STAGE(bufoff, gbase, voff) do { _Pragma("unroll") for (int _i = 0; _i < 2; ++_i) \
;         __builtin_amdgcn_global_load_lds((const unsigned*)((const char*)(gbase) + (voff)[_i]), (PG8_LAS unsigned*)(lds + (bufoff) + ldsw + _i * 8192), 16, 0, 0); } while (0)
; #define PG8_LDA(dst, b, h) do { _Pragma("unroll") for (int m = 0; m < 4; ++m) _Pragma("unroll") for (int k = 0; k < 2; ++k) dst[m][k] = *(const PG8_LAS bf16x8*)(lds + PG8_SA(b, h) + aoff + m * 2048 + k * 1024); } while (0)
; #define PG8_LDB(dst, b, h) do { _Pragma("unroll") for (int n = 0; n < 2; ++n) _Pragma("unroll") for (int k = 0; k < 2; ++k) dst[n][k] = *(const PG8_LAS bf16x8*)(lds + PG8_SB(b, h) + boff + n * 2048 + k * 1024); } while (0)
; #define PG8_MMA(ai, bj, At, Bt) do { __builtin_amdgcn_s_setprio(1); _Pragma("unroll") for (int m = 0; m < 4; ++m) _Pragma("unroll") for (int n = 0; n < 2; ++n) _Pragma("unroll") for (int k = 0; k < 2; ++k) \
;         acc[ai][bj][m][n] = __builtin_amdgcn_mfma_f32_16x16x32_bf16(Bt[n][k], At[m][k], acc[ai][bj][m][n], 0, 0, 0); __builtin_amdgcn_s_setprio(0); } while (0)
; #define PG8_WAIT_V(n) asm volatile("s_waitcnt vmcnt(" #n ")" ::: "memory")
; #define PG8_WAIT_L(n) asm volatile("s_waitcnt lgkmcnt(" #n ")" ::: "memory")
; #define PG8_BAR __builtin_amdgcn_s_barrier()
; #define PG8_SCHED __builtin_amdgcn_sched_barrier(0)
; template <class Epi, class Sched>
; __device__ __forceinline__ void gemm_phase(PG8_LAS unsigned char* lds, const Gemm g, const Sched& S, const Epi& E) {
;     ...
;             PG8_WAIT_L(8); PG8_BAR; PG8_WAIT_L(0); PG8_MMA(0, 0, At, B0); PG8_BAR; PG8_SCHED;
;             PG8_LDB(B1, 1, 1); PG8_STAGE(PG8_SB(1, 0), b3, voffB);
;             PG8_BAR; PG8_WAIT_L(0); PG8_MMA(0, 1, At, B1); PG8_BAR;
;             PG8_LDA(At, 1, 1); PG8_STAGE(PG8_SA(1, 0), a3, voffA);
;             PG8_BAR; PG8_WAIT_L(0); PG8_MMA(1, 0, At, B0); PG8_BAR; PG8_SCHED;
;             PG8_STAGE(PG8_SB(1, 1), b3 + hstep, voffB);
;             PG8_WAIT_V(6); PG8_BAR; PG8_MMA(1, 1, At, B1); PG8_BAR;
	s_setprio 0
	s_waitcnt lgkmcnt(7)
	v_mfma_f32_16x16x32_bf16 v[126:129], v[156:159], v[176:179], v[126:129]
	v_mfma_f32_16x16x32_bf16 v[122:125], v[164:167], v[176:179], v[122:125]
	s_waitcnt lgkmcnt(5)
	v_mfma_f32_16x16x32_bf16 v[118:121], v[156:159], v[184:187], v[118:121]
	v_mfma_f32_16x16x32_bf16 v[114:117], v[164:167], v[184:187], v[114:117]
	s_waitcnt lgkmcnt(3)
	v_mfma_f32_16x16x32_bf16 v[110:113], v[156:159], v[192:195], v[110:113]
	v_mfma_f32_16x16x32_bf16 v[106:109], v[164:167], v[192:195], v[106:109]
	s_waitcnt lgkmcnt(1)
	v_mfma_f32_16x16x32_bf16 v[98:101], v[156:159], v[200:203], v[98:101]
	v_mfma_f32_16x16x32_bf16 v[90:93], v[164:167], v[200:203], v[90:93]
	v_mfma_f32_16x16x32_bf16 v[126:129], v[160:163], v[180:183], v[126:129]
	v_mfma_f32_16x16x32_bf16 v[122:125], v[168:171], v[180:183], v[122:125]
	v_mfma_f32_16x16x32_bf16 v[118:121], v[160:163], v[188:191], v[118:121]
	v_mfma_f32_16x16x32_bf16 v[114:117], v[168:171], v[188:191], v[114:117]
	v_mfma_f32_16x16x32_bf16 v[110:113], v[160:163], v[196:199], v[110:113]
	v_mfma_f32_16x16x32_bf16 v[106:109], v[168:171], v[196:199], v[106:109]
	s_waitcnt lgkmcnt(0)
	v_mfma_f32_16x16x32_bf16 v[98:101], v[160:163], v[204:207], v[98:101]
	v_mfma_f32_16x16x32_bf16 v[90:93], v[168:171], v[204:207], v[90:93]
	s_setprio 1
	s_barrier
	s_add_i32 s22, 0, 0x1c000
	s_add_i32 s23, s24, s37
	v_add_u32_e32 v155, s22, v152
	v_lshl_add_u64 v[172:173], v[172:173], 0, s[0:1]
	s_mov_b32 m0, s23
	ds_read_b128 v[208:211], v155
	ds_read_b128 v[212:215], v155 offset:1024
	ds_read_b128 v[216:219], v155 offset:2048
	ds_read_b128 v[234:237], v155 offset:3072
	global_load_lds_dwordx4 v[172:173], off
	v_lshl_add_u64 v[172:173], v[224:225], 0, s[0:1]
	s_add_i32 m0, s23, 0x2000
	s_nop 0
	global_load_lds_dwordx4 v[172:173], off
	s_barrier
	s_setprio 0
	s_waitcnt lgkmcnt(3)
	v_mfma_f32_16x16x32_bf16 v[102:105], v[208:211], v[176:179], v[102:105]
	s_waitcnt lgkmcnt(1)
	v_mfma_f32_16x16x32_bf16 v[94:97], v[216:219], v[176:179], v[94:97]
	v_mfma_f32_16x16x32_bf16 v[86:89], v[208:211], v[184:187], v[86:89]
	v_mfma_f32_16x16x32_bf16 v[82:85], v[216:219], v[184:187], v[82:85]
	v_mfma_f32_16x16x32_bf16 v[78:81], v[208:211], v[192:195], v[78:81]
	v_mfma_f32_16x16x32_bf16 v[74:77], v[216:219], v[192:195], v[74:77]
	v_mfma_f32_16x16x32_bf16 v[70:73], v[208:211], v[200:203], v[70:73]
	v_mfma_f32_16x16x32_bf16 v[66:69], v[216:219], v[200:203], v[66:69]
	v_mfma_f32_16x16x32_bf16 v[102:105], v[212:215], v[180:183], v[102:105]
	s_waitcnt lgkmcnt(0)
	v_mfma_f32_16x16x32_bf16 v[94:97], v[234:237], v[180:183], v[94:97]
	v_mfma_f32_16x16x32_bf16 v[86:89], v[212:215], v[188:191], v[86:89]
	v_mfma_f32_16x16x32_bf16 v[82:85], v[234:237], v[188:191], v[82:85]
	v_mfma_f32_16x16x32_bf16 v[78:81], v[212:215], v[196:199], v[78:81]
	v_mfma_f32_16x16x32_bf16 v[74:77], v[234:237], v[196:199], v[74:77]
	v_mfma_f32_16x16x32_bf16 v[70:73], v[212:215], v[204:207], v[70:73]
	v_mfma_f32_16x16x32_bf16 v[66:69], v[234:237], v[204:207], v[66:69]
	s_setprio 1
	s_mov_b32 m0, s50
	v_lshl_add_u64 v[172:173], v[228:229], 0, s[0:1]
	s_barrier
	ds_read_b128 v[176:179], v154 offset:49152
	ds_read_b128 v[180:183], v154 offset:50176
	ds_read_b128 v[184:187], v154 offset:51200
	ds_read_b128 v[188:191], v154 offset:52224
	ds_read_b128 v[192:195], v154 offset:53248
	ds_read_b128 v[196:199], v154 offset:54272
	ds_read_b128 v[200:203], v154 offset:55296
	ds_read_b128 v[204:207], v154 offset:56320
	global_load_lds_dwordx4 v[172:173], off
	v_lshl_add_u64 v[172:173], v[238:239], 0, s[0:1]
	s_mov_b32 m0, s51
	s_nop 0
	global_load_lds_dwordx4 v[172:173], off
	s_barrier
	s_setprio 0
	s_waitcnt lgkmcnt(7)
	v_mfma_f32_16x16x32_bf16 v[62:65], v[156:159], v[176:179], v[62:65]
	v_mfma_f32_16x16x32_bf16 v[58:61], v[164:167], v[176:179], v[58:61]
	s_waitcnt lgkmcnt(5)
	v_mfma_f32_16x16x32_bf16 v[54:57], v[156:159], v[184:187], v[54:57]
	v_mfma_f32_16x16x32_bf16 v[50:53], v[164:167], v[184:187], v[50:53]
	s_waitcnt lgkmcnt(3)
	v_mfma_f32_16x16x32_bf16 v[44:47], v[156:159], v[192:195], v[44:47]
	v_mfma_f32_16x16x32_bf16 v[40:43], v[164:167], v[192:195], v[40:43]
	s_waitcnt lgkmcnt(1)
	v_mfma_f32_16x16x32_bf16 v[32:35], v[156:159], v[200:203], v[32:35]
	v_mfma_f32_16x16x32_bf16 v[24:27], v[164:167], v[200:203], v[24:27]
	v_mfma_f32_16x16x32_bf16 v[62:65], v[160:163], v[180:183], v[62:65]
	v_mfma_f32_16x16x32_bf16 v[58:61], v[168:171], v[180:183], v[58:61]
	v_mfma_f32_16x16x32_bf16 v[54:57], v[160:163], v[188:191], v[54:57]
	v_mfma_f32_16x16x32_bf16 v[50:53], v[168:171], v[188:191], v[50:53]
	v_mfma_f32_16x16x32_bf16 v[44:47], v[160:163], v[196:199], v[44:47]
	v_mfma_f32_16x16x32_bf16 v[40:43], v[168:171], v[196:199], v[40:43]
	s_waitcnt lgkmcnt(0)
	v_mfma_f32_16x16x32_bf16 v[32:35], v[160:163], v[204:207], v[32:35]
	v_mfma_f32_16x16x32_bf16 v[24:27], v[168:171], v[204:207], v[24:27]
	s_setprio 1
	s_barrier
	s_add_i32 s22, s22, s37
	v_lshl_add_u64 v[156:157], v[240:241], 0, s[0:1]
	s_mov_b32 m0, s22
	s_nop 0
	global_load_lds_dwordx4 v[156:157], off
	v_lshl_add_u64 v[156:157], v[242:243], 0, s[0:1]
	s_add_i32 m0, s22, 0x2000
	s_nop 0
	global_load_lds_dwordx4 v[156:157], off
	s_waitcnt vmcnt(6)
	s_barrier
	s_setprio 0
	v_mfma_f32_16x16x32_bf16 v[36:39], v[208:211], v[176:179], v[36:39]
	v_mfma_f32_16x16x32_bf16 v[28:31], v[216:219], v[176:179], v[28:31]
	v_mfma_f32_16x16x32_bf16 v[20:23], v[208:211], v[184:187], v[20:23]
	v_mfma_f32_16x16x32_bf16 v[16:19], v[216:219], v[184:187], v[16:19]
	v_mfma_f32_16x16x32_bf16 v[12:15], v[208:211], v[192:195], v[12:15]
	v_mfma_f32_16x16x32_bf16 v[8:11], v[216:219], v[192:195], v[8:11]
	v_mfma_f32_16x16x32_bf16 v[4:7], v[208:211], v[200:203], v[4:7]
	v_mfma_f32_16x16x32_bf16 v[0:3], v[216:219], v[200:203], v[0:3]
	v_mfma_f32_16x16x32_bf16 v[36:39], v[212:215], v[180:183], v[36:39]
	v_mfma_f32_16x16x32_bf16 v[28:31], v[234:237], v[180:183], v[28:31]
	v_mfma_f32_16x16x32_bf16 v[20:23], v[212:215], v[188:191], v[20:23]
	v_mfma_f32_16x16x32_bf16 v[16:19], v[234:237], v[188:191], v[16:19]
	v_mfma_f32_16x16x32_bf16 v[12:15], v[212:215], v[196:199], v[12:15]
	v_mfma_f32_16x16x32_bf16 v[8:11], v[234:237], v[196:199], v[8:11]
	v_mfma_f32_16x16x32_bf16 v[4:7], v[212:215], v[204:207], v[4:7]
	v_mfma_f32_16x16x32_bf16 v[0:3], v[234:237], v[204:207], v[0:3]
	s_setprio 1
	s_add_u32 s20, s20, 0x100
	s_addc_u32 s21, s21, 0
	s_add_u32 s3, s3, 0x100
	s_addc_u32 s40, s40, 0
	s_cmp_ge_u32 s41, s54
	s_mov_b32 s22, s41
	s_barrier
	s_cbranch_scc0 .LBB0_288
;     __device__ __forceinline__ void operator()(const f32x4 (&acc)[2][2][4][2], const pg8::Unit& u, int wr, int wc, int fr, int fq) const {
;         float* outp = part + ((size_t)u.kc * MC + (size_t)(u.pm * 256 - ML)) * DM;
;         const int col0 = u.pn * 256 + wc * 32 + 4 * fq;
; #pragma unroll
;         for (int ai = 0; ai < 2; ++ai)
; #pragma unroll
;             for (int m = 0; m < 4; ++m) { float* rp = outp + (size_t)(wr * 64 + fr + ai * 128 + m * 16) * DM + col0;
; #pragma unroll
;                 for (int bj = 0; bj < 2; ++bj)
; #pragma unroll
;                     for (int n = 0; n < 2; ++n) *(f32x4*)(rp + bj * 128 + n * 16) = acc[ai][bj][m][n]; }
.Lkpeel_exit_288:
	s_setprio 0
	s_lshl_b32 s20, s45, 8
	s_ashr_i32 s3, s2, 31
	s_ashr_i32 s21, s20, 31
	s_lshl_b64 s[20:21], s[20:21], 12
	s_lshl_b64 s[2:3], s[2:3], 23
	s_add_u32 s2, s48, s2
	s_addc_u32 s3, s49, s3
	s_add_u32 s2, s2, s20
	v_lshl_or_b32 v156, s42, 8, v153
	s_addc_u32 s3, s3, s21
	v_ashrrev_i32_e32 v157, 31, v156
	v_lshl_add_u64 v[156:157], v[156:157], 2, s[2:3]
	s_brev_b32 s2, 31
	s_mov_b32 s3, -1
	v_lshl_add_u64 v[156:157], v[156:157], 0, s[2:3]
	v_and_b32_e32 v166, 8, v220
	v_mul_i32_i24_e32 v166, 0xfffff008, v166
	v_mov_b32_e32 v168, 0x8000
	v_mov_b32_e32 v169, 0
	v_ashrrev_i32_e32 v167, 31, v166
	v_lshl_add_u64 v[156:157], v[156:157], 0, v[166:167]
	v_mov_b32_dpp v160, v126 row_ror:8 row_mask:0xf bank_mask:0x3
	v_mov_b32_dpp v161, v127 row_ror:8 row_mask:0xf bank_mask:0x3
	v_mov_b32_dpp v162, v128 row_ror:8 row_mask:0xf bank_mask:0x3
	v_mov_b32_dpp v163, v129 row_ror:8 row_mask:0xf bank_mask:0x3
	v_mov_b32_dpp v126, v122 row_ror:8 row_mask:0xf bank_mask:0xc
	v_mov_b32_dpp v127, v123 row_ror:8 row_mask:0xf bank_mask:0xc
	v_mov_b32_dpp v128, v124 row_ror:8 row_mask:0xf bank_mask:0xc
	v_mov_b32_dpp v129, v125 row_ror:8 row_mask:0xf bank_mask:0xc
	v_mov_b32_dpp v122, v160 quad_perm:[0,1,2,3] row_mask:0xf bank_mask:0x3
	v_mov_b32_dpp v123, v161 quad_perm:[0,1,2,3] row_mask:0xf bank_mask:0x3
	v_mov_b32_dpp v124, v162 quad_perm:[0,1,2,3] row_mask:0xf bank_mask:0x3
	v_mov_b32_dpp v125, v163 quad_perm:[0,1,2,3] row_mask:0xf bank_mask:0x3
	v_mov_b32_dpp v160, v102 row_ror:8 row_mask:0xf bank_mask:0x3
	v_mov_b32_dpp v161, v103 row_ror:8 row_mask:0xf bank_mask:0x3
	v_mov_b32_dpp v162, v104 row_ror:8 row_mask:0xf bank_mask:0x3
	v_mov_b32_dpp v163, v105 row_ror:8 row_mask:0xf bank_mask:0x3
	v_mov_b32_dpp v102, v94 row_ror:8 row_mask:0xf bank_mask:0xc
	v_mov_b32_dpp v103, v95 row_ror:8 row_mask:0xf bank_mask:0xc
	v_mov_b32_dpp v104, v96 row_ror:8 row_mask:0xf bank_mask:0xc
	v_mov_b32_dpp v105, v97 row_ror:8 row_mask:0xf bank_mask:0xc
	v_mov_b32_dpp v94, v160 quad_perm:[0,1,2,3] row_mask:0xf bank_mask:0x3
	v_mov_b32_dpp v95, v161 quad_perm:[0,1,2,3] row_mask:0xf bank_mask:0x3
	v_mov_b32_dpp v96, v162 quad_perm:[0,1,2,3] row_mask:0xf bank_mask:0x3
	v_mov_b32_dpp v97, v163 quad_perm:[0,1,2,3] row_mask:0xf bank_mask:0x3
	v_lshl_add_u64 v[158:159], v[156:157], 0, v[132:133]
	v_lshl_add_u64 v[164:165], v[158:159], 0, v[168:169]
	global_store_dwordx4 v[158:159], v[126:129], off
	global_store_dwordx4 v[164:165], v[122:125], off
	global_store_dwordx4 v[158:159], v[102:105], off offset:512
	global_store_dwordx4 v[164:165], v[94:97], off offset:512
	s_and_b64 vcc, exec, s[6:7]
	s_mov_b32 s2, s56
	v_mov_b32_dpp v160, v118 row_ror:8 row_mask:0xf bank_mask:0x3
	v_mov_b32_dpp v161, v119 row_ror:8 row_mask:0xf bank_mask:0x3
	v_mov_b32_dpp v162, v120 row_ror:8 row_mask:0xf bank_mask:0x3
	v_mov_b32_dpp v163, v121 row_ror:8 row_mask:0xf bank_mask:0x3
	v_mov_b32_dpp v118, v114 row_ror:8 row_mask:0xf bank_mask:0xc
	v_mov_b32_dpp v119, v115 row_ror:8 row_mask:0xf bank_mask:0xc
	v_mov_b32_dpp v120, v116 row_ror:8 row_mask:0xf bank_mask:0xc
	v_mov_b32_dpp v121, v117 row_ror:8 row_mask:0xf bank_mask:0xc
	v_mov_b32_dpp v114, v160 quad_perm:[0,1,2,3] row_mask:0xf bank_mask:0x3
	v_mov_b32_dpp v115, v161 quad_perm:[0,1,2,3] row_mask:0xf bank_mask:0x3
	v_mov_b32_dpp v116, v162 quad_perm:[0,1,2,3] row_mask:0xf bank_mask:0x3
	v_mov_b32_dpp v117, v163 quad_perm:[0,1,2,3] row_mask:0xf bank_mask:0x3
	v_mov_b32_dpp v160, v86 row_ror:8 row_mask:0xf bank_mask:0x3
	v_mov_b32_dpp v161, v87 row_ror:8 row_mask:0xf bank_mask:0x3
	v_mov_b32_dpp v162, v88 row_ror:8 row_mask:0xf bank_mask:0x3
	v_mov_b32_dpp v163, v89 row_ror:8 row_mask:0xf bank_mask:0x3
	v_mov_b32_dpp v86, v82 row_ror:8 row_mask:0xf bank_mask:0xc
	v_mov_b32_dpp v87, v83 row_ror:8 row_mask:0xf bank_mask:0xc
	v_mov_b32_dpp v88, v84 row_ror:8 row_mask:0xf bank_mask:0xc
	v_mov_b32_dpp v89, v85 row_ror:8 row_mask:0xf bank_mask:0xc
	v_mov_b32_dpp v82, v160 quad_perm:[0,1,2,3] row_mask:0xf bank_mask:0x3
	v_mov_b32_dpp v83, v161 quad_perm:[0,1,2,3] row_mask:0xf bank_mask:0x3
	v_mov_b32_dpp v84, v162 quad_perm:[0,1,2,3] row_mask:0xf bank_mask:0x3
	v_mov_b32_dpp v85, v163 quad_perm:[0,1,2,3] row_mask:0xf bank_mask:0x3
	v_lshl_add_u64 v[94:95], v[156:157], 0, v[134:135]
	v_lshl_add_u64 v[96:97], v[94:95], 0, v[168:169]
	global_store_dwordx4 v[94:95], v[118:121], off
	global_store_dwordx4 v[96:97], v[114:117], off
	global_store_dwordx4 v[94:95], v[86:89], off offset:512
	global_store_dwordx4 v[96:97], v[82:85], off offset:512
	s_mov_b32 s42, s57
	s_mov_b32 s45, s59
	v_mov_b32_dpp v160, v110 row_ror:8 row_mask:0xf bank_mask:0x3
	v_mov_b32_dpp v161, v111 row_ror:8 row_mask:0xf bank_mask:0x3
	v_mov_b32_dpp v162, v112 row_ror:8 row_mask:0xf bank_mask:0x3
	v_mov_b32_dpp v163, v113 row_ror:8 row_mask:0xf bank_mask:0x3
	v_mov_b32_dpp v110, v106 row_ror:8 row_mask:0xf bank_mask:0xc
	v_mov_b32_dpp v111, v107 row_ror:8 row_mask:0xf bank_mask:0xc
	v_mov_b32_dpp v112, v108 row_ror:8 row_mask:0xf bank_mask:0xc
	v_mov_b32_dpp v113, v109 row_ror:8 row_mask:0xf bank_mask:0xc
	v_mov_b32_dpp v106, v160 quad_perm:[0,1,2,3] row_mask:0xf bank_mask:0x3
	v_mov_b32_dpp v107, v161 quad_perm:[0,1,2,3] row_mask:0xf bank_mask:0x3
	v_mov_b32_dpp v108, v162 quad_perm:[0,1,2,3] row_mask:0xf bank_mask:0x3
	v_mov_b32_dpp v109, v163 quad_perm:[0,1,2,3] row_mask:0xf bank_mask:0x3
	v_mov_b32_dpp v160, v78 row_ror:8 row_mask:0xf bank_mask:0x3
	v_mov_b32_dpp v161, v79 row_ror:8 row_mask:0xf bank_mask:0x3
	v_mov_b32_dpp v162, v80 row_ror:8 row_mask:0xf bank_mask:0x3
	v_mov_b32_dpp v163, v81 row_ror:8 row_mask:0xf bank_mask:0x3
;     __device__ __forceinline__ void operator()(const f32x4 (&acc)[2][2][4][2], const pg8::Unit& u, int wr, int wc, int fr, int fq) const {
;     ...
; #pragma unroll
;         for (int ai = 0; ai < 2; ++ai)
; #pragma unroll
;             for (int m = 0; m < 4; ++m) { float* rp = outp + (size_t)(wr * 64 + fr + ai * 128 + m * 16) * DM + col0;
; #pragma unroll
;                 for (int bj = 0; bj < 2; ++bj)
; #pragma unroll
;                     for (int n = 0; n < 2; ++n) *(f32x4*)(rp + bj * 128 + n * 16) = acc[ai][bj][m][n]; }
	v_mov_b32_dpp v78, v74 row_ror:8 row_mask:0xf bank_mask:0xc
	v_mov_b32_dpp v79, v75 row_ror:8 row_mask:0xf bank_mask:0xc
	v_mov_b32_dpp v80, v76 row_ror:8 row_mask:0xf bank_mask:0xc
	v_mov_b32_dpp v81, v77 row_ror:8 row_mask:0xf bank_mask:0xc
	v_mov_b32_dpp v74, v160 quad_perm:[0,1,2,3] row_mask:0xf bank_mask:0x3
	v_mov_b32_dpp v75, v161 quad_perm:[0,1,2,3] row_mask:0xf bank_mask:0x3
	v_mov_b32_dpp v76, v162 quad_perm:[0,1,2,3] row_mask:0xf bank_mask:0x3
	v_mov_b32_dpp v77, v163 quad_perm:[0,1,2,3] row_mask:0xf bank_mask:0x3
	v_lshl_add_u64 v[82:83], v[156:157], 0, v[136:137]
	v_lshl_add_u64 v[84:85], v[82:83], 0, v[168:169]
	global_store_dwordx4 v[82:83], v[110:113], off
	global_store_dwordx4 v[84:85], v[106:109], off
	global_store_dwordx4 v[82:83], v[78:81], off offset:512
	global_store_dwordx4 v[84:85], v[74:77], off offset:512
	s_mov_b64 s[22:23], s[16:17]
	s_mov_b64 s[20:21], s[12:13]
	v_mov_b32_dpp v160, v98 row_ror:8 row_mask:0xf bank_mask:0x3
	v_mov_b32_dpp v161, v99 row_ror:8 row_mask:0xf bank_mask:0x3
	v_mov_b32_dpp v162, v100 row_ror:8 row_mask:0xf bank_mask:0x3
	v_mov_b32_dpp v163, v101 row_ror:8 row_mask:0xf bank_mask:0x3
	v_mov_b32_dpp v98, v90 row_ror:8 row_mask:0xf bank_mask:0xc
	v_mov_b32_dpp v99, v91 row_ror:8 row_mask:0xf bank_mask:0xc
	v_mov_b32_dpp v100, v92 row_ror:8 row_mask:0xf bank_mask:0xc
	v_mov_b32_dpp v101, v93 row_ror:8 row_mask:0xf bank_mask:0xc
	v_mov_b32_dpp v90, v160 quad_perm:[0,1,2,3] row_mask:0xf bank_mask:0x3
	v_mov_b32_dpp v91, v161 quad_perm:[0,1,2,3] row_mask:0xf bank_mask:0x3
	v_mov_b32_dpp v92, v162 quad_perm:[0,1,2,3] row_mask:0xf bank_mask:0x3
	v_mov_b32_dpp v93, v163 quad_perm:[0,1,2,3] row_mask:0xf bank_mask:0x3
	v_mov_b32_dpp v160, v70 row_ror:8 row_mask:0xf bank_mask:0x3
	v_mov_b32_dpp v161, v71 row_ror:8 row_mask:0xf bank_mask:0x3
	v_mov_b32_dpp v162, v72 row_ror:8 row_mask:0xf bank_mask:0x3
	v_mov_b32_dpp v163, v73 row_ror:8 row_mask:0xf bank_mask:0x3
	v_mov_b32_dpp v70, v66 row_ror:8 row_mask:0xf bank_mask:0xc
	v_mov_b32_dpp v71, v67 row_ror:8 row_mask:0xf bank_mask:0xc
	v_mov_b32_dpp v72, v68 row_ror:8 row_mask:0xf bank_mask:0xc
	v_mov_b32_dpp v73, v69 row_ror:8 row_mask:0xf bank_mask:0xc
	v_mov_b32_dpp v66, v160 quad_perm:[0,1,2,3] row_mask:0xf bank_mask:0x3
	v_mov_b32_dpp v67, v161 quad_perm:[0,1,2,3] row_mask:0xf bank_mask:0x3
	v_mov_b32_dpp v68, v162 quad_perm:[0,1,2,3] row_mask:0xf bank_mask:0x3
	v_mov_b32_dpp v69, v163 quad_perm:[0,1,2,3] row_mask:0xf bank_mask:0x3
	v_lshl_add_u64 v[74:75], v[156:157], 0, v[138:139]
	v_lshl_add_u64 v[76:77], v[74:75], 0, v[168:169]
	global_store_dwordx4 v[74:75], v[98:101], off
	global_store_dwordx4 v[76:77], v[90:93], off
	global_store_dwordx4 v[74:75], v[70:73], off offset:512
	global_store_dwordx4 v[76:77], v[66:69], off offset:512
	s_nop 1
	v_mov_b32_dpp v160, v62 row_ror:8 row_mask:0xf bank_mask:0x3
	v_mov_b32_dpp v161, v63 row_ror:8 row_mask:0xf bank_mask:0x3
	v_mov_b32_dpp v162, v64 row_ror:8 row_mask:0xf bank_mask:0x3
	v_mov_b32_dpp v163, v65 row_ror:8 row_mask:0xf bank_mask:0x3
	v_mov_b32_dpp v62, v58 row_ror:8 row_mask:0xf bank_mask:0xc
	v_mov_b32_dpp v63, v59 row_ror:8 row_mask:0xf bank_mask:0xc
	v_mov_b32_dpp v64, v60 row_ror:8 row_mask:0xf bank_mask:0xc
	v_mov_b32_dpp v65, v61 row_ror:8 row_mask:0xf bank_mask:0xc
	v_mov_b32_dpp v58, v160 quad_perm:[0,1,2,3] row_mask:0xf bank_mask:0x3
	v_mov_b32_dpp v59, v161 quad_perm:[0,1,2,3] row_mask:0xf bank_mask:0x3
	v_mov_b32_dpp v60, v162 quad_perm:[0,1,2,3] row_mask:0xf bank_mask:0x3
	v_mov_b32_dpp v61, v163 quad_perm:[0,1,2,3] row_mask:0xf bank_mask:0x3
	v_mov_b32_dpp v160, v36 row_ror:8 row_mask:0xf bank_mask:0x3
	v_mov_b32_dpp v161, v37 row_ror:8 row_mask:0xf bank_mask:0x3
	v_mov_b32_dpp v162, v38 row_ror:8 row_mask:0xf bank_mask:0x3
	v_mov_b32_dpp v163, v39 row_ror:8 row_mask:0xf bank_mask:0x3
	v_mov_b32_dpp v36, v28 row_ror:8 row_mask:0xf bank_mask:0xc
	v_mov_b32_dpp v37, v29 row_ror:8 row_mask:0xf bank_mask:0xc
	v_mov_b32_dpp v38, v30 row_ror:8 row_mask:0xf bank_mask:0xc
	v_mov_b32_dpp v39, v31 row_ror:8 row_mask:0xf bank_mask:0xc
	v_mov_b32_dpp v28, v160 quad_perm:[0,1,2,3] row_mask:0xf bank_mask:0x3
	v_mov_b32_dpp v29, v161 quad_perm:[0,1,2,3] row_mask:0xf bank_mask:0x3
	v_mov_b32_dpp v30, v162 quad_perm:[0,1,2,3] row_mask:0xf bank_mask:0x3
	v_mov_b32_dpp v31, v163 quad_perm:[0,1,2,3] row_mask:0xf bank_mask:0x3
	v_lshl_add_u64 v[66:67], v[156:157], 0, v[140:141]
	v_lshl_add_u64 v[68:69], v[66:67], 0, v[168:169]
	global_store_dwordx4 v[66:67], v[62:65], off
	global_store_dwordx4 v[68:69], v[58:61], off
	global_store_dwordx4 v[66:67], v[36:39], off offset:512
	global_store_dwordx4 v[68:69], v[28:31], off offset:512
	s_nop 1
	v_mov_b32_dpp v160, v54 row_ror:8 row_mask:0xf bank_mask:0x3
	v_mov_b32_dpp v161, v55 row_ror:8 row_mask:0xf bank_mask:0x3
	v_mov_b32_dpp v162, v56 row_ror:8 row_mask:0xf bank_mask:0x3
	v_mov_b32_dpp v163, v57 row_ror:8 row_mask:0xf bank_mask:0x3
	v_mov_b32_dpp v54, v50 row_ror:8 row_mask:0xf bank_mask:0xc
	v_mov_b32_dpp v55, v51 row_ror:8 row_mask:0xf bank_mask:0xc
	v_mov_b32_dpp v56, v52 row_ror:8 row_mask:0xf bank_mask:0xc
	v_mov_b32_dpp v57, v53 row_ror:8 row_mask:0xf bank_mask:0xc
	v_mov_b32_dpp v50, v160 quad_perm:[0,1,2,3] row_mask:0xf bank_mask:0x3
	v_mov_b32_dpp v51, v161 quad_perm:[0,1,2,3] row_mask:0xf bank_mask:0x3
; template <class Epi, class Sched>
; __device__ __forceinline__ void gemm_phase(PG8_LAS unsigned char* lds, const Gemm g, const Sched& S, const Epi& E) {
;     ...
;         if (!has_next) break;
; #pragma unroll
;         for (int a = 0; a < 2; ++a)
; #pragma unroll
;             for (int b = 0; b < 2; ++b)
; #pragma unroll
;                 for (int m = 0; m < 4; ++m)
; #pragma unroll
;                     for (int n = 0; n < 2; ++n) acc[a][b][m][n] = (f32x4){0.f, 0.f, 0.f, 0.f};
;         cur = nxt; cA = nA; cB = nB; ++ui;
;     __device__ __forceinline__ void operator()(const f32x4 (&acc)[2][2][4][2], const pg8::Unit& u, int wr, int wc, int fr, int fq) const {
;     ...
; #pragma unroll
;         for (int ai = 0; ai < 2; ++ai)
; #pragma unroll
;             for (int m = 0; m < 4; ++m) { float* rp = outp + (size_t)(wr * 64 + fr + ai * 128 + m * 16) * DM + col0;
; #pragma unroll
;                 for (int bj = 0; bj < 2; ++bj)
; #pragma unroll
;                     for (int n = 0; n < 2; ++n) *(f32x4*)(rp + bj * 128 + n * 16) = acc[ai][bj][m][n]; }
	v_mov_b32_dpp v52, v162 quad_perm:[0,1,2,3] row_mask:0xf bank_mask:0x3
	v_mov_b32_dpp v53, v163 quad_perm:[0,1,2,3] row_mask:0xf bank_mask:0x3
	v_mov_b32_dpp v160, v20 row_ror:8 row_mask:0xf bank_mask:0x3
	v_mov_b32_dpp v161, v21 row_ror:8 row_mask:0xf bank_mask:0x3
	v_mov_b32_dpp v162, v22 row_ror:8 row_mask:0xf bank_mask:0x3
	v_mov_b32_dpp v163, v23 row_ror:8 row_mask:0xf bank_mask:0x3
	v_mov_b32_dpp v20, v16 row_ror:8 row_mask:0xf bank_mask:0xc
	v_mov_b32_dpp v21, v17 row_ror:8 row_mask:0xf bank_mask:0xc
	v_mov_b32_dpp v22, v18 row_ror:8 row_mask:0xf bank_mask:0xc
	v_mov_b32_dpp v23, v19 row_ror:8 row_mask:0xf bank_mask:0xc
	v_mov_b32_dpp v16, v160 quad_perm:[0,1,2,3] row_mask:0xf bank_mask:0x3
	v_mov_b32_dpp v17, v161 quad_perm:[0,1,2,3] row_mask:0xf bank_mask:0x3
	v_mov_b32_dpp v18, v162 quad_perm:[0,1,2,3] row_mask:0xf bank_mask:0x3
	v_mov_b32_dpp v19, v163 quad_perm:[0,1,2,3] row_mask:0xf bank_mask:0x3
	v_lshl_add_u64 v[28:29], v[156:157], 0, v[142:143]
	v_lshl_add_u64 v[30:31], v[28:29], 0, v[168:169]
	global_store_dwordx4 v[28:29], v[54:57], off
	global_store_dwordx4 v[30:31], v[50:53], off
	global_store_dwordx4 v[28:29], v[20:23], off offset:512
	global_store_dwordx4 v[30:31], v[16:19], off offset:512
	s_nop 1
	v_mov_b32_dpp v160, v44 row_ror:8 row_mask:0xf bank_mask:0x3
	v_mov_b32_dpp v161, v45 row_ror:8 row_mask:0xf bank_mask:0x3
	v_mov_b32_dpp v162, v46 row_ror:8 row_mask:0xf bank_mask:0x3
	v_mov_b32_dpp v163, v47 row_ror:8 row_mask:0xf bank_mask:0x3
	v_mov_b32_dpp v44, v40 row_ror:8 row_mask:0xf bank_mask:0xc
	v_mov_b32_dpp v45, v41 row_ror:8 row_mask:0xf bank_mask:0xc
	v_mov_b32_dpp v46, v42 row_ror:8 row_mask:0xf bank_mask:0xc
	v_mov_b32_dpp v47, v43 row_ror:8 row_mask:0xf bank_mask:0xc
	v_mov_b32_dpp v40, v160 quad_perm:[0,1,2,3] row_mask:0xf bank_mask:0x3
	v_mov_b32_dpp v41, v161 quad_perm:[0,1,2,3] row_mask:0xf bank_mask:0x3
	v_mov_b32_dpp v42, v162 quad_perm:[0,1,2,3] row_mask:0xf bank_mask:0x3
	v_mov_b32_dpp v43, v163 quad_perm:[0,1,2,3] row_mask:0xf bank_mask:0x3
	v_mov_b32_dpp v160, v12 row_ror:8 row_mask:0xf bank_mask:0x3
	v_mov_b32_dpp v161, v13 row_ror:8 row_mask:0xf bank_mask:0x3
	v_mov_b32_dpp v162, v14 row_ror:8 row_mask:0xf bank_mask:0x3
	v_mov_b32_dpp v163, v15 row_ror:8 row_mask:0xf bank_mask:0x3
	v_mov_b32_dpp v12, v8 row_ror:8 row_mask:0xf bank_mask:0xc
	v_mov_b32_dpp v13, v9 row_ror:8 row_mask:0xf bank_mask:0xc
	v_mov_b32_dpp v14, v10 row_ror:8 row_mask:0xf bank_mask:0xc
	v_mov_b32_dpp v15, v11 row_ror:8 row_mask:0xf bank_mask:0xc
	v_mov_b32_dpp v8, v160 quad_perm:[0,1,2,3] row_mask:0xf bank_mask:0x3
	v_mov_b32_dpp v9, v161 quad_perm:[0,1,2,3] row_mask:0xf bank_mask:0x3
	v_mov_b32_dpp v10, v162 quad_perm:[0,1,2,3] row_mask:0xf bank_mask:0x3
	v_mov_b32_dpp v11, v163 quad_perm:[0,1,2,3] row_mask:0xf bank_mask:0x3
	v_lshl_add_u64 v[16:17], v[156:157], 0, v[144:145]
	v_lshl_add_u64 v[18:19], v[16:17], 0, v[168:169]
	global_store_dwordx4 v[16:17], v[44:47], off
	global_store_dwordx4 v[18:19], v[40:43], off
	global_store_dwordx4 v[16:17], v[12:15], off offset:512
	global_store_dwordx4 v[18:19], v[8:11], off offset:512
	s_nop 1
	v_mov_b32_dpp v160, v32 row_ror:8 row_mask:0xf bank_mask:0x3
	v_mov_b32_dpp v161, v33 row_ror:8 row_mask:0xf bank_mask:0x3
	v_mov_b32_dpp v162, v34 row_ror:8 row_mask:0xf bank_mask:0x3
	v_mov_b32_dpp v163, v35 row_ror:8 row_mask:0xf bank_mask:0x3
	v_mov_b32_dpp v32, v24 row_ror:8 row_mask:0xf bank_mask:0xc
	v_mov_b32_dpp v33, v25 row_ror:8 row_mask:0xf bank_mask:0xc
	v_mov_b32_dpp v34, v26 row_ror:8 row_mask:0xf bank_mask:0xc
	v_mov_b32_dpp v35, v27 row_ror:8 row_mask:0xf bank_mask:0xc
	v_mov_b32_dpp v24, v160 quad_perm:[0,1,2,3] row_mask:0xf bank_mask:0x3
	v_mov_b32_dpp v25, v161 quad_perm:[0,1,2,3] row_mask:0xf bank_mask:0x3
	v_mov_b32_dpp v26, v162 quad_perm:[0,1,2,3] row_mask:0xf bank_mask:0x3
	v_mov_b32_dpp v27, v163 quad_perm:[0,1,2,3] row_mask:0xf bank_mask:0x3
	v_mov_b32_dpp v160, v4 row_ror:8 row_mask:0xf bank_mask:0x3
	v_mov_b32_dpp v161, v5 row_ror:8 row_mask:0xf bank_mask:0x3
	v_mov_b32_dpp v162, v6 row_ror:8 row_mask:0xf bank_mask:0x3
	v_mov_b32_dpp v163, v7 row_ror:8 row_mask:0xf bank_mask:0x3
	v_mov_b32_dpp v4, v0 row_ror:8 row_mask:0xf bank_mask:0xc
	v_mov_b32_dpp v5, v1 row_ror:8 row_mask:0xf bank_mask:0xc
	v_mov_b32_dpp v6, v2 row_ror:8 row_mask:0xf bank_mask:0xc
	v_mov_b32_dpp v7, v3 row_ror:8 row_mask:0xf bank_mask:0xc
	v_mov_b32_dpp v0, v160 quad_perm:[0,1,2,3] row_mask:0xf bank_mask:0x3
	v_mov_b32_dpp v1, v161 quad_perm:[0,1,2,3] row_mask:0xf bank_mask:0x3
	v_mov_b32_dpp v2, v162 quad_perm:[0,1,2,3] row_mask:0xf bank_mask:0x3
	v_mov_b32_dpp v3, v163 quad_perm:[0,1,2,3] row_mask:0xf bank_mask:0x3
	v_lshl_add_u64 v[8:9], v[156:157], 0, v[146:147]
	v_lshl_add_u64 v[10:11], v[8:9], 0, v[168:169]
	global_store_dwordx4 v[8:9], v[32:35], off
	global_store_dwordx4 v[10:11], v[24:27], off
	global_store_dwordx4 v[8:9], v[4:7], off offset:512
	global_store_dwordx4 v[10:11], v[0:3], off offset:512
	s_cbranch_vccz .LBB0_281
	s_waitcnt vmcnt(0)
	v_readlane_b32 s46, v254, 33
	v_readlane_b32 s48, v254, 35
	s_cmpk_gt_u32 s34, 0xff
	v_readlane_b32 s54, v254, 31
	v_readlane_b32 s47, v254, 34
	v_readlane_b32 s49, v254, 36
	v_readlane_b32 s55, v254, 39
	s_mov_b32 s57, s65
	s_cbranch_scc1 .LBB0_292
	s_barrier

; #define PG8_STAGE(bufoff, gbase, voff) do { _Pragma("unroll") for (int _i = 0; _i < 2; ++_i) \
;         __builtin_amdgcn_global_load_lds((const unsigned*)((const char*)(gbase) + (voff)[_i]), (PG8_LAS unsigned*)(lds + (bufoff) + ldsw + _i * 8192), 16, 0, 0); } while (0)
; #define PG8_LDA(dst, b, h) do { _Pragma("unroll") for (int m = 0; m < 4; ++m) _Pragma("unroll") for (int k = 0; k < 2; ++k) dst[m][k] = *(const PG8_LAS bf16x8*)(lds + PG8_SA(b, h) + aoff + m * 2048 + k * 1024); } while (0)
; #define PG8_LDB(dst, b, h) do { _Pragma("unroll") for (int n = 0; n < 2; ++n) _Pragma("unroll") for (int k = 0; k < 2; ++k) dst[n][k] = *(const PG8_LAS bf16x8*)(lds + PG8_SB(b, h) + boff + n * 2048 + k * 1024); } while (0)
; #define PG8_MMA(ai, bj, At, Bt) do { __builtin_amdgcn_s_setprio(1); _Pragma("unroll") for (int m = 0; m < 4; ++m) _Pragma("unroll") for (int n = 0; n < 2; ++n) _Pragma("unroll") for (int k = 0; k < 2; ++k) \
;         acc[ai][bj][m][n] = __builtin_amdgcn_mfma_f32_16x16x32_bf16(Bt[n][k], At[m][k], acc[ai][bj][m][n], 0, 0, 0); __builtin_amdgcn_s_setprio(0); } while (0)
; #define PG8_BAR __builtin_amdgcn_s_barrier()
; template <class Epi, class Sched>
; __device__ __forceinline__ void gemm_phase(PG8_LAS unsigned char* lds, const Gemm g, const Sched& S, const Epi& E) {
;     ...
;         const bool has_next = S.next(ui + 1, nxt);
;         const char* nA = has_next ? (const char*)g.A + (size_t)nxt.pm * tstepA + (size_t)nxt.kc * cstep : cA; const char* nB = has_next ? (const char*)g.Bt + (size_t)nxt.pn * tstep + (size_t)nxt.kc * cstep : cB;
;         for (int t = 0; t < nt; t += 2) {
;             const bool last = (t == nt - 2);
;             const char* a1 = cA + (size_t)(t + 1) * kstep;
;             const char* a2 = last ? nA : cA + (size_t)(t + 2) * kstep; const char* b2 = last ? nB : cB + (size_t)(t + 2) * kstep;
;             const char* a3 = a2 + kstep; const char* b3 = b2 + kstep;
;             if (last && has_next) S.a_ready(nxt);
;             PG8_LDB(B0, 0, 0); PG8_SCHED; PG8_LDA(At, 0, 0); PG8_STAGE(PG8_SA(1, 1), a1 + hstep, voffA);
;             PG8_WAIT_L(8); PG8_BAR; PG8_WAIT_L(0); PG8_MMA(0, 0, At, B0); PG8_BAR; PG8_SCHED;
;             PG8_LDB(B1, 0, 1); PG8_STAGE(PG8_SB(0, 0), b2, voffB);
;             PG8_BAR; PG8_WAIT_L(0); PG8_MMA(0, 1, At, B1); PG8_BAR;
;             PG8_LDA(At, 0, 1); PG8_STAGE(PG8_SA(0, 0), a2, voffA);
.LBB0_319:
	v_mov_b64_e32 v[0:1], s[56:57]
	s_ashr_i32 s25, s24, 31
	v_cmp_lt_i64_e32 vcc, s[26:27], v[0:1]
	s_lshl_b64 s[26:27], s[24:25], 19
	s_add_u32 s26, s8, s26
	s_addc_u32 s27, s9, s27
	s_and_b64 s[28:29], vcc, exec
	s_cselect_b32 s25, s27, s31
	s_cselect_b32 s56, s26, s30
	s_ashr_i32 s23, s22, 31
	s_lshl_b64 s[28:29], s[22:23], 19
	s_add_u32 s28, s6, s28
	s_addc_u32 s29, s7, s29
	s_and_b64 s[36:37], vcc, exec
	s_cselect_b32 s23, s29, s35
	s_cselect_b32 s57, s28, s34
	s_add_u32 s30, s30, 0x40080
	s_addc_u32 s31, s31, 0
	s_add_u32 s59, s34, 0x100
	s_addc_u32 s63, s35, 0
	s_mov_b32 s64, -2
	s_add_u32 s34, s30, 0xfffc0080
	s_addc_u32 s35, s31, -1
	s_add_i32 s65, 0, 0x10000
	v_add_u32_e32 v140, s65, v143
	ds_read_b128 v[146:149], v140
	ds_read_b128 v[150:153], v140 offset:1024
	ds_read_b128 v[154:157], v140 offset:2048
	ds_read_b128 v[158:161], v140 offset:3072
	s_cmp_eq_u32 s64, 12
	s_cselect_b32 s37, s25, s35
	s_cselect_b32 s36, s56, s34
	s_cselect_b32 s35, s23, s63
	s_cselect_b32 s34, s57, s59
	v_lshl_add_u64 v[140:141], s[30:31], 0, v[136:137]
	s_add_i32 m0, s21, 0xc000
	ds_read_b128 v[162:165], v145
	ds_read_b128 v[166:169], v145 offset:1024
	ds_read_b128 v[170:173], v145 offset:2048
	ds_read_b128 v[176:179], v145 offset:3072
	ds_read_b128 v[180:183], v145 offset:4096
	ds_read_b128 v[184:187], v145 offset:5120
	ds_read_b128 v[188:191], v145 offset:6144
	ds_read_b128 v[192:195], v145 offset:7168
	global_load_lds_dwordx4 v[140:141], off
	v_lshl_add_u64 v[140:141], s[30:31], 0, v[138:139]
	s_add_i32 m0, s21, 0xe000
	s_nop 0
	global_load_lds_dwordx4 v[140:141], off
	s_waitcnt lgkmcnt(8)
	s_barrier
	s_setprio 0
	s_waitcnt lgkmcnt(7)
	v_mfma_f32_16x16x32_bf16 v[126:129], v[146:149], v[162:165], 0
	v_mfma_f32_16x16x32_bf16 v[122:125], v[154:157], v[162:165], 0
	s_waitcnt lgkmcnt(5)
	v_mfma_f32_16x16x32_bf16 v[118:121], v[146:149], v[170:173], 0
	v_mfma_f32_16x16x32_bf16 v[110:113], v[154:157], v[170:173], 0
	s_waitcnt lgkmcnt(3)
	v_mfma_f32_16x16x32_bf16 v[102:105], v[146:149], v[180:183], 0
	v_mfma_f32_16x16x32_bf16 v[94:97], v[154:157], v[180:183], 0
	s_waitcnt lgkmcnt(1)
	v_mfma_f32_16x16x32_bf16 v[86:89], v[146:149], v[188:191], 0
	v_mfma_f32_16x16x32_bf16 v[78:81], v[154:157], v[188:191], 0
	v_mfma_f32_16x16x32_bf16 v[126:129], v[150:153], v[166:169], v[126:129]
	v_mfma_f32_16x16x32_bf16 v[122:125], v[158:161], v[166:169], v[122:125]
	v_mfma_f32_16x16x32_bf16 v[118:121], v[150:153], v[176:179], v[118:121]
	v_mfma_f32_16x16x32_bf16 v[110:113], v[158:161], v[176:179], v[110:113]
	v_mfma_f32_16x16x32_bf16 v[102:105], v[150:153], v[184:187], v[102:105]
	v_mfma_f32_16x16x32_bf16 v[94:97], v[158:161], v[184:187], v[94:97]
	s_waitcnt lgkmcnt(0)
	v_mfma_f32_16x16x32_bf16 v[86:89], v[150:153], v[192:195], v[86:89]
	v_mfma_f32_16x16x32_bf16 v[78:81], v[158:161], v[192:195], v[78:81]
	s_setprio 1
	s_barrier
	s_add_i32 s68, 0, 0x14000
	v_add_u32_e32 v140, s68, v143
	s_add_i32 s65, s65, s13
	ds_read_b128 v[196:199], v140
	ds_read_b128 v[200:203], v140 offset:1024
	ds_read_b128 v[204:207], v140 offset:2048
	ds_read_b128 v[208:211], v140 offset:3072
	v_lshl_add_u64 v[140:141], s[34:35], 0, v[48:49]
	s_mov_b32 m0, s65
	v_lshl_add_u64 v[212:213], s[34:35], 0, v[130:131]
	global_load_lds_dwordx4 v[140:141], off
	s_add_i32 m0, s65, 0x2000
	s_nop 0
	global_load_lds_dwordx4 v[212:213], off
	s_barrier
	s_setprio 0
	s_waitcnt lgkmcnt(3)
	v_mfma_f32_16x16x32_bf16 v[114:117], v[196:199], v[162:165], 0
	s_waitcnt lgkmcnt(1)
	v_mfma_f32_16x16x32_bf16 v[106:109], v[204:207], v[162:165], 0
	v_mfma_f32_16x16x32_bf16 v[98:101], v[196:199], v[170:173], 0
	v_mfma_f32_16x16x32_bf16 v[90:93], v[204:207], v[170:173], 0
	v_mfma_f32_16x16x32_bf16 v[82:85], v[196:199], v[180:183], 0
	v_mfma_f32_16x16x32_bf16 v[74:77], v[204:207], v[180:183], 0
	v_mfma_f32_16x16x32_bf16 v[70:73], v[196:199], v[188:191], 0
	v_mfma_f32_16x16x32_bf16 v[66:69], v[204:207], v[188:191], 0
	v_mfma_f32_16x16x32_bf16 v[114:117], v[200:203], v[166:169], v[114:117]
	s_waitcnt lgkmcnt(0)
	v_mfma_f32_16x16x32_bf16 v[106:109], v[208:211], v[166:169], v[106:109]
	v_mfma_f32_16x16x32_bf16 v[98:101], v[200:203], v[176:179], v[98:101]
	v_mfma_f32_16x16x32_bf16 v[90:93], v[208:211], v[176:179], v[90:93]
	v_mfma_f32_16x16x32_bf16 v[82:85], v[200:203], v[184:187], v[82:85]
	v_mfma_f32_16x16x32_bf16 v[74:77], v[208:211], v[184:187], v[74:77]
	v_mfma_f32_16x16x32_bf16 v[70:73], v[200:203], v[192:195], v[70:73]
	v_mfma_f32_16x16x32_bf16 v[66:69], v[208:211], v[192:195], v[66:69]
	s_setprio 1
	s_mov_b32 m0, s21
	v_lshl_add_u64 v[214:215], s[36:37], 0, v[134:135]
	s_barrier
	ds_read_b128 v[162:165], v145 offset:16384
	ds_read_b128 v[166:169], v145 offset:17408
	ds_read_b128 v[170:173], v145 offset:18432
	ds_read_b128 v[176:179], v145 offset:19456
	ds_read_b128 v[180:183], v145 offset:20480
	ds_read_b128 v[184:187], v145 offset:21504
	ds_read_b128 v[188:191], v145 offset:22528
	ds_read_b128 v[192:195], v145 offset:23552
	global_load_lds_dwordx4 v[214:215], off
	v_lshl_add_u64 v[216:217], s[36:37], 0, v[132:133]
	s_mov_b32 m0, s46
	s_nop 0
	global_load_lds_dwordx4 v[216:217], off
	s_barrier
; #define PG8_STAGE(bufoff, gbase, voff) do { _Pragma("unroll") for (int _i = 0; _i < 2; ++_i) \
;         __builtin_amdgcn_global_load_lds((const unsigned*)((const char*)(gbase) + (voff)[_i]), (PG8_LAS unsigned*)(lds + (bufoff) + ldsw + _i * 8192), 16, 0, 0); } while (0)
; #define PG8_LDA(dst, b, h) do { _Pragma("unroll") for (int m = 0; m < 4; ++m) _Pragma("unroll") for (int k = 0; k < 2; ++k) dst[m][k] = *(const PG8_LAS bf16x8*)(lds + PG8_SA(b, h) + aoff + m * 2048 + k * 1024); } while (0)
; #define PG8_LDB(dst, b, h) do { _Pragma("unroll") for (int n = 0; n < 2; ++n) _Pragma("unroll") for (int k = 0; k < 2; ++k) dst[n][k] = *(const PG8_LAS bf16x8*)(lds + PG8_SB(b, h) + boff + n * 2048 + k * 1024); } while (0)
; #define PG8_MMA(ai, bj, At, Bt) do { __builtin_amdgcn_s_setprio(1); _Pragma("unroll") for (int m = 0; m < 4; ++m) _Pragma("unroll") for (int n = 0; n < 2; ++n) _Pragma("unroll") for (int k = 0; k < 2; ++k) \
;         acc[ai][bj][m][n] = __builtin_amdgcn_mfma_f32_16x16x32_bf16(Bt[n][k], At[m][k], acc[ai][bj][m][n], 0, 0, 0); __builtin_amdgcn_s_setprio(0); } while (0)
; #define PG8_WAIT_V(n) asm volatile("s_waitcnt vmcnt(" #n ")" ::: "memory")
; #define PG8_WAIT_L(n) asm volatile("s_waitcnt lgkmcnt(" #n ")" ::: "memory")
; #define PG8_BAR __builtin_amdgcn_s_barrier()
; #define PG8_SCHED __builtin_amdgcn_sched_barrier(0)
; template <class Epi, class Sched>
; __device__ __forceinline__ void gemm_phase(PG8_LAS unsigned char* lds, const Gemm g, const Sched& S, const Epi& E) {
;     ...
;             PG8_BAR; PG8_WAIT_L(0); PG8_MMA(1, 0, At, B0); PG8_BAR; PG8_SCHED;
;             PG8_STAGE(PG8_SB(0, 1), b2 + hstep, voffB);
;             PG8_WAIT_V(6); PG8_BAR; PG8_MMA(1, 1, At, B1); PG8_BAR;
;             PG8_LDB(B0, 1, 0); PG8_SCHED; PG8_LDA(At, 1, 0); PG8_STAGE(PG8_SA(0, 1), a2 + hstep, voffA);
;             PG8_WAIT_L(8); PG8_BAR; PG8_WAIT_L(0); PG8_MMA(0, 0, At, B0); PG8_BAR; PG8_SCHED;
;             PG8_LDB(B1, 1, 1); PG8_STAGE(PG8_SB(1, 0), b3, voffB);
	s_setprio 0
	s_waitcnt lgkmcnt(7)
	v_mfma_f32_16x16x32_bf16 v[62:65], v[146:149], v[162:165], 0
	v_mfma_f32_16x16x32_bf16 v[58:61], v[154:157], v[162:165], 0
	s_waitcnt lgkmcnt(5)
	v_mfma_f32_16x16x32_bf16 v[54:57], v[146:149], v[170:173], 0
	v_mfma_f32_16x16x32_bf16 v[44:47], v[154:157], v[170:173], 0
	s_waitcnt lgkmcnt(3)
	v_mfma_f32_16x16x32_bf16 v[36:39], v[146:149], v[180:183], 0
	v_mfma_f32_16x16x32_bf16 v[28:31], v[154:157], v[180:183], 0
	s_waitcnt lgkmcnt(1)
	v_mfma_f32_16x16x32_bf16 v[20:23], v[146:149], v[188:191], 0
	v_mfma_f32_16x16x32_bf16 v[12:15], v[154:157], v[188:191], 0
	v_mfma_f32_16x16x32_bf16 v[62:65], v[150:153], v[166:169], v[62:65]
	v_mfma_f32_16x16x32_bf16 v[58:61], v[158:161], v[166:169], v[58:61]
	v_mfma_f32_16x16x32_bf16 v[54:57], v[150:153], v[176:179], v[54:57]
	v_mfma_f32_16x16x32_bf16 v[44:47], v[158:161], v[176:179], v[44:47]
	v_mfma_f32_16x16x32_bf16 v[36:39], v[150:153], v[184:187], v[36:39]
	v_mfma_f32_16x16x32_bf16 v[28:31], v[158:161], v[184:187], v[28:31]
	s_waitcnt lgkmcnt(0)
	v_mfma_f32_16x16x32_bf16 v[20:23], v[150:153], v[192:195], v[20:23]
	v_mfma_f32_16x16x32_bf16 v[12:15], v[158:161], v[192:195], v[12:15]
	s_setprio 1
	s_barrier
	s_add_u32 s66, s34, 0x40000
	s_addc_u32 s67, s35, 0
	s_add_i32 s65, s68, s13
	v_lshl_add_u64 v[146:147], s[66:67], 0, v[48:49]
	s_mov_b32 m0, s65
	s_nop 0
	global_load_lds_dwordx4 v[146:147], off
	v_lshl_add_u64 v[146:147], s[66:67], 0, v[130:131]
	s_add_i32 m0, s65, 0x2000
	s_nop 0
	global_load_lds_dwordx4 v[146:147], off
	s_waitcnt vmcnt(6)
	s_barrier
	s_setprio 0
	v_mfma_f32_16x16x32_bf16 v[50:53], v[196:199], v[162:165], 0
	v_mfma_f32_16x16x32_bf16 v[40:43], v[204:207], v[162:165], 0
	v_mfma_f32_16x16x32_bf16 v[32:35], v[196:199], v[170:173], 0
	v_mfma_f32_16x16x32_bf16 v[24:27], v[204:207], v[170:173], 0
	v_mfma_f32_16x16x32_bf16 v[16:19], v[196:199], v[180:183], 0
	v_mfma_f32_16x16x32_bf16 v[8:11], v[204:207], v[180:183], 0
	v_mfma_f32_16x16x32_bf16 v[4:7], v[196:199], v[188:191], 0
	v_mfma_f32_16x16x32_bf16 v[0:3], v[204:207], v[188:191], 0
	v_mfma_f32_16x16x32_bf16 v[50:53], v[200:203], v[166:169], v[50:53]
	v_mfma_f32_16x16x32_bf16 v[40:43], v[208:211], v[166:169], v[40:43]
	v_mfma_f32_16x16x32_bf16 v[32:35], v[200:203], v[176:179], v[32:35]
	v_mfma_f32_16x16x32_bf16 v[24:27], v[208:211], v[176:179], v[24:27]
	v_mfma_f32_16x16x32_bf16 v[16:19], v[200:203], v[184:187], v[16:19]
	v_mfma_f32_16x16x32_bf16 v[8:11], v[208:211], v[184:187], v[8:11]
	v_mfma_f32_16x16x32_bf16 v[4:7], v[200:203], v[192:195], v[4:7]
	v_mfma_f32_16x16x32_bf16 v[0:3], v[208:211], v[192:195], v[0:3]
	s_setprio 1
	s_add_i32 s65, 0, 0x18000
	v_add_u32_e32 v158, s65, v143
	s_barrier
	ds_read_b128 v[146:149], v158
	ds_read_b128 v[150:153], v158 offset:1024
	ds_read_b128 v[154:157], v158 offset:2048
	ds_read_b128 v[158:161], v158 offset:3072
	s_add_u32 s36, s36, 0x40000
	s_addc_u32 s37, s37, 0
	s_mov_b32 m0, s47
	v_lshl_add_u64 v[196:197], s[36:37], 0, v[134:135]
	ds_read_b128 v[162:165], v145 offset:32768
	ds_read_b128 v[166:169], v145 offset:33792
	ds_read_b128 v[170:173], v145 offset:34816
	ds_read_b128 v[176:179], v145 offset:35840
	ds_read_b128 v[180:183], v145 offset:36864
	ds_read_b128 v[184:187], v145 offset:37888
	ds_read_b128 v[188:191], v145 offset:38912
	ds_read_b128 v[192:195], v145 offset:39936
	global_load_lds_dwordx4 v[196:197], off
	v_lshl_add_u64 v[196:197], s[36:37], 0, v[132:133]
	s_mov_b32 m0, s48
	s_nop 0
	global_load_lds_dwordx4 v[196:197], off
	s_waitcnt lgkmcnt(8)
	s_barrier
	s_setprio 0
	s_waitcnt lgkmcnt(7)
	v_mfma_f32_16x16x32_bf16 v[126:129], v[146:149], v[162:165], v[126:129]
	v_mfma_f32_16x16x32_bf16 v[122:125], v[154:157], v[162:165], v[122:125]
	s_waitcnt lgkmcnt(5)
	v_mfma_f32_16x16x32_bf16 v[118:121], v[146:149], v[170:173], v[118:121]
	v_mfma_f32_16x16x32_bf16 v[110:113], v[154:157], v[170:173], v[110:113]
	s_waitcnt lgkmcnt(3)
	v_mfma_f32_16x16x32_bf16 v[102:105], v[146:149], v[180:183], v[102:105]
	v_mfma_f32_16x16x32_bf16 v[94:97], v[154:157], v[180:183], v[94:97]
	s_waitcnt lgkmcnt(1)
	v_mfma_f32_16x16x32_bf16 v[86:89], v[146:149], v[188:191], v[86:89]
	v_mfma_f32_16x16x32_bf16 v[78:81], v[154:157], v[188:191], v[78:81]
	v_mfma_f32_16x16x32_bf16 v[126:129], v[150:153], v[166:169], v[126:129]
	v_mfma_f32_16x16x32_bf16 v[122:125], v[158:161], v[166:169], v[122:125]
	v_mfma_f32_16x16x32_bf16 v[118:121], v[150:153], v[176:179], v[118:121]
	v_mfma_f32_16x16x32_bf16 v[110:113], v[158:161], v[176:179], v[110:113]
	v_mfma_f32_16x16x32_bf16 v[102:105], v[150:153], v[184:187], v[102:105]
	v_mfma_f32_16x16x32_bf16 v[94:97], v[158:161], v[184:187], v[94:97]
	s_waitcnt lgkmcnt(0)
	v_mfma_f32_16x16x32_bf16 v[86:89], v[150:153], v[192:195], v[86:89]
	v_mfma_f32_16x16x32_bf16 v[78:81], v[158:161], v[192:195], v[78:81]
	s_setprio 1
	s_barrier
	s_add_i32 s36, 0, 0x1c000
	s_add_i32 s37, s65, s13
	v_add_u32_e32 v175, s36, v143
	v_lshl_add_u64 v[140:141], v[140:141], 0, s[0:1]
	s_mov_b32 m0, s37
	ds_read_b128 v[196:199], v175
	ds_read_b128 v[200:203], v175 offset:1024
	ds_read_b128 v[204:207], v175 offset:2048
	ds_read_b128 v[208:211], v175 offset:3072
	global_load_lds_dwordx4 v[140:141], off
	v_lshl_add_u64 v[140:141], v[212:213], 0, s[0:1]
	s_add_i32 m0, s37, 0x2000
	s_nop 0
	global_load_lds_dwordx4 v[140:141], off
	s_barrier
; #define PG8_STAGE(bufoff, gbase, voff) do { _Pragma("unroll") for (int _i = 0; _i < 2; ++_i) \
;         __builtin_amdgcn_global_load_lds((const unsigned*)((const char*)(gbase) + (voff)[_i]), (PG8_LAS unsigned*)(lds + (bufoff) + ldsw + _i * 8192), 16, 0, 0); } while (0)
; #define PG8_LDA(dst, b, h) do { _Pragma("unroll") for (int m = 0; m < 4; ++m) _Pragma("unroll") for (int k = 0; k < 2; ++k) dst[m][k] = *(const PG8_LAS bf16x8*)(lds + PG8_SA(b, h) + aoff + m * 2048 + k * 1024); } while (0)
; #define PG8_MMA(ai, bj, At, Bt) do { __builtin_amdgcn_s_setprio(1); _Pragma("unroll") for (int m = 0; m < 4; ++m) _Pragma("unroll") for (int n = 0; n < 2; ++n) _Pragma("unroll") for (int k = 0; k < 2; ++k) \
;         acc[ai][bj][m][n] = __builtin_amdgcn_mfma_f32_16x16x32_bf16(Bt[n][k], At[m][k], acc[ai][bj][m][n], 0, 0, 0); __builtin_amdgcn_s_setprio(0); } while (0)
; #define PG8_WAIT_V(n) asm volatile("s_waitcnt vmcnt(" #n ")" ::: "memory")
; #define PG8_WAIT_L(n) asm volatile("s_waitcnt lgkmcnt(" #n ")" ::: "memory")
; #define PG8_BAR __builtin_amdgcn_s_barrier()
; #define PG8_SCHED __builtin_amdgcn_sched_barrier(0)
; template <class Epi, class Sched>
; __device__ __forceinline__ void gemm_phase(PG8_LAS unsigned char* lds, const Gemm g, const Sched& S, const Epi& E) {
;     ...
;             PG8_BAR; PG8_WAIT_L(0); PG8_MMA(0, 1, At, B1); PG8_BAR;
;             PG8_LDA(At, 1, 1); PG8_STAGE(PG8_SA(1, 0), a3, voffA);
;             PG8_BAR; PG8_WAIT_L(0); PG8_MMA(1, 0, At, B0); PG8_BAR; PG8_SCHED;
;             PG8_STAGE(PG8_SB(1, 1), b3 + hstep, voffB);
;             PG8_WAIT_V(6); PG8_BAR; PG8_MMA(1, 1, At, B1); PG8_BAR;
	s_setprio 0
	s_waitcnt lgkmcnt(3)
	v_mfma_f32_16x16x32_bf16 v[114:117], v[196:199], v[162:165], v[114:117]
	s_waitcnt lgkmcnt(1)
	v_mfma_f32_16x16x32_bf16 v[106:109], v[204:207], v[162:165], v[106:109]
	v_mfma_f32_16x16x32_bf16 v[98:101], v[196:199], v[170:173], v[98:101]
	v_mfma_f32_16x16x32_bf16 v[90:93], v[204:207], v[170:173], v[90:93]
	v_mfma_f32_16x16x32_bf16 v[82:85], v[196:199], v[180:183], v[82:85]
	v_mfma_f32_16x16x32_bf16 v[74:77], v[204:207], v[180:183], v[74:77]
	v_mfma_f32_16x16x32_bf16 v[70:73], v[196:199], v[188:191], v[70:73]
	v_mfma_f32_16x16x32_bf16 v[66:69], v[204:207], v[188:191], v[66:69]
	v_mfma_f32_16x16x32_bf16 v[114:117], v[200:203], v[166:169], v[114:117]
	s_waitcnt lgkmcnt(0)
	v_mfma_f32_16x16x32_bf16 v[106:109], v[208:211], v[166:169], v[106:109]
	v_mfma_f32_16x16x32_bf16 v[98:101], v[200:203], v[176:179], v[98:101]
	v_mfma_f32_16x16x32_bf16 v[90:93], v[208:211], v[176:179], v[90:93]
	v_mfma_f32_16x16x32_bf16 v[82:85], v[200:203], v[184:187], v[82:85]
	v_mfma_f32_16x16x32_bf16 v[74:77], v[208:211], v[184:187], v[74:77]
	v_mfma_f32_16x16x32_bf16 v[70:73], v[200:203], v[192:195], v[70:73]
	v_mfma_f32_16x16x32_bf16 v[66:69], v[208:211], v[192:195], v[66:69]
	s_setprio 1
	s_mov_b32 m0, s49
	v_lshl_add_u64 v[140:141], v[214:215], 0, s[0:1]
	s_barrier
	ds_read_b128 v[162:165], v145 offset:49152
	ds_read_b128 v[166:169], v145 offset:50176
	ds_read_b128 v[170:173], v145 offset:51200
	ds_read_b128 v[176:179], v145 offset:52224
	ds_read_b128 v[180:183], v145 offset:53248
	ds_read_b128 v[184:187], v145 offset:54272
	ds_read_b128 v[188:191], v145 offset:55296
	ds_read_b128 v[192:195], v145 offset:56320
	global_load_lds_dwordx4 v[140:141], off
	v_lshl_add_u64 v[140:141], v[216:217], 0, s[0:1]
	s_mov_b32 m0, s50
	s_nop 0
	global_load_lds_dwordx4 v[140:141], off
	s_barrier
	s_setprio 0
	s_waitcnt lgkmcnt(7)
	v_mfma_f32_16x16x32_bf16 v[62:65], v[146:149], v[162:165], v[62:65]
	v_mfma_f32_16x16x32_bf16 v[58:61], v[154:157], v[162:165], v[58:61]
	s_waitcnt lgkmcnt(5)
	v_mfma_f32_16x16x32_bf16 v[54:57], v[146:149], v[170:173], v[54:57]
	v_mfma_f32_16x16x32_bf16 v[44:47], v[154:157], v[170:173], v[44:47]
	s_waitcnt lgkmcnt(3)
	v_mfma_f32_16x16x32_bf16 v[36:39], v[146:149], v[180:183], v[36:39]
	v_mfma_f32_16x16x32_bf16 v[28:31], v[154:157], v[180:183], v[28:31]
	s_waitcnt lgkmcnt(1)
	v_mfma_f32_16x16x32_bf16 v[20:23], v[146:149], v[188:191], v[20:23]
	v_mfma_f32_16x16x32_bf16 v[12:15], v[154:157], v[188:191], v[12:15]
	v_mfma_f32_16x16x32_bf16 v[62:65], v[150:153], v[166:169], v[62:65]
	v_mfma_f32_16x16x32_bf16 v[58:61], v[158:161], v[166:169], v[58:61]
	v_mfma_f32_16x16x32_bf16 v[54:57], v[150:153], v[176:179], v[54:57]
	v_mfma_f32_16x16x32_bf16 v[44:47], v[158:161], v[176:179], v[44:47]
	v_mfma_f32_16x16x32_bf16 v[36:39], v[150:153], v[184:187], v[36:39]
	v_mfma_f32_16x16x32_bf16 v[28:31], v[158:161], v[184:187], v[28:31]
	s_waitcnt lgkmcnt(0)
	v_mfma_f32_16x16x32_bf16 v[20:23], v[150:153], v[192:195], v[20:23]
	v_mfma_f32_16x16x32_bf16 v[12:15], v[158:161], v[192:195], v[12:15]
	s_setprio 1
	s_barrier
	s_add_u32 s34, s34, 0x40080
	s_addc_u32 s35, s35, 0
	s_add_i32 s36, s36, s13
	v_lshl_add_u64 v[140:141], s[34:35], 0, v[48:49]
	s_mov_b32 m0, s36
	s_nop 0
	global_load_lds_dwordx4 v[140:141], off
	v_lshl_add_u64 v[140:141], s[34:35], 0, v[130:131]
	s_add_i32 m0, s36, 0x2000
	s_nop 0
	global_load_lds_dwordx4 v[140:141], off
	s_waitcnt vmcnt(6)
	s_barrier
	s_setprio 0
	v_mfma_f32_16x16x32_bf16 v[50:53], v[196:199], v[162:165], v[50:53]
	v_mfma_f32_16x16x32_bf16 v[40:43], v[204:207], v[162:165], v[40:43]
	v_mfma_f32_16x16x32_bf16 v[32:35], v[196:199], v[170:173], v[32:35]
	v_mfma_f32_16x16x32_bf16 v[24:27], v[204:207], v[170:173], v[24:27]
	v_mfma_f32_16x16x32_bf16 v[16:19], v[196:199], v[180:183], v[16:19]
	v_mfma_f32_16x16x32_bf16 v[8:11], v[204:207], v[180:183], v[8:11]
	v_mfma_f32_16x16x32_bf16 v[4:7], v[196:199], v[188:191], v[4:7]
	v_mfma_f32_16x16x32_bf16 v[0:3], v[204:207], v[188:191], v[0:3]
	v_mfma_f32_16x16x32_bf16 v[50:53], v[200:203], v[166:169], v[50:53]
	v_mfma_f32_16x16x32_bf16 v[40:43], v[208:211], v[166:169], v[40:43]
	v_mfma_f32_16x16x32_bf16 v[32:35], v[200:203], v[176:179], v[32:35]
	v_mfma_f32_16x16x32_bf16 v[24:27], v[208:211], v[176:179], v[24:27]
	v_mfma_f32_16x16x32_bf16 v[16:19], v[200:203], v[184:187], v[16:19]
	v_mfma_f32_16x16x32_bf16 v[8:11], v[208:211], v[184:187], v[8:11]
	v_mfma_f32_16x16x32_bf16 v[4:7], v[200:203], v[192:195], v[4:7]
	v_mfma_f32_16x16x32_bf16 v[0:3], v[208:211], v[192:195], v[0:3]
	s_setprio 1
	s_add_i32 s64, s64, 2
	s_add_u32 s30, s30, 0x100
	s_addc_u32 s31, s31, 0
	s_add_u32 s59, s59, 0x100
	s_addc_u32 s63, s63, 0
	s_cmp_gt_u32 s64, 13
	s_barrier
	s_cbranch_scc1 .Lkpeel_exit_320
; #define PG8_STAGE(bufoff, gbase, voff) do { _Pragma("unroll") for (int _i = 0; _i < 2; ++_i) \
;         __builtin_amdgcn_global_load_lds((const unsigned*)((const char*)(gbase) + (voff)[_i]), (PG8_LAS unsigned*)(lds + (bufoff) + ldsw + _i * 8192), 16, 0, 0); } while (0)
; #define PG8_LDA(dst, b, h) do { _Pragma("unroll") for (int m = 0; m < 4; ++m) _Pragma("unroll") for (int k = 0; k < 2; ++k) dst[m][k] = *(const PG8_LAS bf16x8*)(lds + PG8_SA(b, h) + aoff + m * 2048 + k * 1024); } while (0)
; #define PG8_LDB(dst, b, h) do { _Pragma("unroll") for (int n = 0; n < 2; ++n) _Pragma("unroll") for (int k = 0; k < 2; ++k) dst[n][k] = *(const PG8_LAS bf16x8*)(lds + PG8_SB(b, h) + boff + n * 2048 + k * 1024); } while (0)
; #define PG8_MMA(ai, bj, At, Bt) do { __builtin_amdgcn_s_setprio(1); _Pragma("unroll") for (int m = 0; m < 4; ++m) _Pragma("unroll") for (int n = 0; n < 2; ++n) _Pragma("unroll") for (int k = 0; k < 2; ++k) \
;         acc[ai][bj][m][n] = __builtin_amdgcn_mfma_f32_16x16x32_bf16(Bt[n][k], At[m][k], acc[ai][bj][m][n], 0, 0, 0); __builtin_amdgcn_s_setprio(0); } while (0)
; #define PG8_WAIT_L(n) asm volatile("s_waitcnt lgkmcnt(" #n ")" ::: "memory")
; #define PG8_BAR __builtin_amdgcn_s_barrier()
; #define PG8_SCHED __builtin_amdgcn_sched_barrier(0)
; template <class Epi, class Sched>
; __device__ __forceinline__ void gemm_phase(PG8_LAS unsigned char* lds, const Gemm g, const Sched& S, const Epi& E) {
;     ...
;             PG8_LDB(B0, 0, 0); PG8_SCHED; PG8_LDA(At, 0, 0); PG8_STAGE(PG8_SA(1, 1), a1 + hstep, voffA);
;             PG8_WAIT_L(8); PG8_BAR; PG8_WAIT_L(0); PG8_MMA(0, 0, At, B0); PG8_BAR; PG8_SCHED;
;             PG8_LDB(B1, 0, 1); PG8_STAGE(PG8_SB(0, 0), b2, voffB);
;             PG8_BAR; PG8_WAIT_L(0); PG8_MMA(0, 1, At, B1); PG8_BAR;
;             PG8_LDA(At, 0, 1); PG8_STAGE(PG8_SA(0, 0), a2, voffA);
;             PG8_BAR; PG8_WAIT_L(0); PG8_MMA(1, 0, At, B0); PG8_BAR; PG8_SCHED;
.LBB0_320:
	s_add_u32 s34, s30, 0xfffc0080
	s_addc_u32 s35, s31, -1
	s_add_i32 s65, 0, 0x10000
	v_add_u32_e32 v140, s65, v143
	ds_read_b128 v[146:149], v140
	ds_read_b128 v[150:153], v140 offset:1024
	ds_read_b128 v[154:157], v140 offset:2048
	ds_read_b128 v[158:161], v140 offset:3072
	s_cmp_eq_u32 s64, 12
	s_cselect_b32 s37, s25, s35
	s_cselect_b32 s36, s56, s34
	s_cselect_b32 s35, s23, s63
	s_cselect_b32 s34, s57, s59
	v_lshl_add_u64 v[140:141], s[30:31], 0, v[136:137]
	s_add_i32 m0, s21, 0xc000
	ds_read_b128 v[162:165], v145
	ds_read_b128 v[166:169], v145 offset:1024
	ds_read_b128 v[170:173], v145 offset:2048
	ds_read_b128 v[176:179], v145 offset:3072
	ds_read_b128 v[180:183], v145 offset:4096
	ds_read_b128 v[184:187], v145 offset:5120
	ds_read_b128 v[188:191], v145 offset:6144
	ds_read_b128 v[192:195], v145 offset:7168
	global_load_lds_dwordx4 v[140:141], off
	v_lshl_add_u64 v[140:141], s[30:31], 0, v[138:139]
	s_add_i32 m0, s21, 0xe000
	s_nop 0
	global_load_lds_dwordx4 v[140:141], off
	s_waitcnt lgkmcnt(8)
	s_barrier
	s_setprio 0
	s_waitcnt lgkmcnt(7)
	v_mfma_f32_16x16x32_bf16 v[126:129], v[146:149], v[162:165], v[126:129]
	v_mfma_f32_16x16x32_bf16 v[122:125], v[154:157], v[162:165], v[122:125]
	s_waitcnt lgkmcnt(5)
	v_mfma_f32_16x16x32_bf16 v[118:121], v[146:149], v[170:173], v[118:121]
	v_mfma_f32_16x16x32_bf16 v[110:113], v[154:157], v[170:173], v[110:113]
	s_waitcnt lgkmcnt(3)
	v_mfma_f32_16x16x32_bf16 v[102:105], v[146:149], v[180:183], v[102:105]
	v_mfma_f32_16x16x32_bf16 v[94:97], v[154:157], v[180:183], v[94:97]
	s_waitcnt lgkmcnt(1)
	v_mfma_f32_16x16x32_bf16 v[86:89], v[146:149], v[188:191], v[86:89]
	v_mfma_f32_16x16x32_bf16 v[78:81], v[154:157], v[188:191], v[78:81]
	v_mfma_f32_16x16x32_bf16 v[126:129], v[150:153], v[166:169], v[126:129]
	v_mfma_f32_16x16x32_bf16 v[122:125], v[158:161], v[166:169], v[122:125]
	v_mfma_f32_16x16x32_bf16 v[118:121], v[150:153], v[176:179], v[118:121]
	v_mfma_f32_16x16x32_bf16 v[110:113], v[158:161], v[176:179], v[110:113]
	v_mfma_f32_16x16x32_bf16 v[102:105], v[150:153], v[184:187], v[102:105]
	v_mfma_f32_16x16x32_bf16 v[94:97], v[158:161], v[184:187], v[94:97]
	s_waitcnt lgkmcnt(0)
	v_mfma_f32_16x16x32_bf16 v[86:89], v[150:153], v[192:195], v[86:89]
	v_mfma_f32_16x16x32_bf16 v[78:81], v[158:161], v[192:195], v[78:81]
	s_setprio 1
	s_barrier
	s_add_i32 s68, 0, 0x14000
	v_add_u32_e32 v140, s68, v143
	s_add_i32 s65, s65, s13
	ds_read_b128 v[196:199], v140
	ds_read_b128 v[200:203], v140 offset:1024
	ds_read_b128 v[204:207], v140 offset:2048
	ds_read_b128 v[208:211], v140 offset:3072
	v_lshl_add_u64 v[140:141], s[34:35], 0, v[48:49]
	s_mov_b32 m0, s65
	v_lshl_add_u64 v[212:213], s[34:35], 0, v[130:131]
	global_load_lds_dwordx4 v[140:141], off
	s_add_i32 m0, s65, 0x2000
	s_nop 0
	global_load_lds_dwordx4 v[212:213], off
	s_barrier
	s_setprio 0
	s_waitcnt lgkmcnt(3)
	v_mfma_f32_16x16x32_bf16 v[114:117], v[196:199], v[162:165], v[114:117]
	s_waitcnt lgkmcnt(1)
	v_mfma_f32_16x16x32_bf16 v[106:109], v[204:207], v[162:165], v[106:109]
	v_mfma_f32_16x16x32_bf16 v[98:101], v[196:199], v[170:173], v[98:101]
	v_mfma_f32_16x16x32_bf16 v[90:93], v[204:207], v[170:173], v[90:93]
	v_mfma_f32_16x16x32_bf16 v[82:85], v[196:199], v[180:183], v[82:85]
	v_mfma_f32_16x16x32_bf16 v[74:77], v[204:207], v[180:183], v[74:77]
	v_mfma_f32_16x16x32_bf16 v[70:73], v[196:199], v[188:191], v[70:73]
	v_mfma_f32_16x16x32_bf16 v[66:69], v[204:207], v[188:191], v[66:69]
	v_mfma_f32_16x16x32_bf16 v[114:117], v[200:203], v[166:169], v[114:117]
	s_waitcnt lgkmcnt(0)
	v_mfma_f32_16x16x32_bf16 v[106:109], v[208:211], v[166:169], v[106:109]
	v_mfma_f32_16x16x32_bf16 v[98:101], v[200:203], v[176:179], v[98:101]
	v_mfma_f32_16x16x32_bf16 v[90:93], v[208:211], v[176:179], v[90:93]
	v_mfma_f32_16x16x32_bf16 v[82:85], v[200:203], v[184:187], v[82:85]
	v_mfma_f32_16x16x32_bf16 v[74:77], v[208:211], v[184:187], v[74:77]
	v_mfma_f32_16x16x32_bf16 v[70:73], v[200:203], v[192:195], v[70:73]
	v_mfma_f32_16x16x32_bf16 v[66:69], v[208:211], v[192:195], v[66:69]
	s_setprio 1
	s_mov_b32 m0, s21
	v_lshl_add_u64 v[214:215], s[36:37], 0, v[134:135]
	s_barrier
	ds_read_b128 v[162:165], v145 offset:16384
	ds_read_b128 v[166:169], v145 offset:17408
	ds_read_b128 v[170:173], v145 offset:18432
	ds_read_b128 v[176:179], v145 offset:19456
	ds_read_b128 v[180:183], v145 offset:20480
	ds_read_b128 v[184:187], v145 offset:21504
	ds_read_b128 v[188:191], v145 offset:22528
	ds_read_b128 v[192:195], v145 offset:23552
	global_load_lds_dwordx4 v[214:215], off
	v_lshl_add_u64 v[216:217], s[36:37], 0, v[132:133]
	s_mov_b32 m0, s46
	s_nop 0
	global_load_lds_dwordx4 v[216:217], off
	s_barrier
	s_setprio 0
	s_waitcnt lgkmcnt(7)
	v_mfma_f32_16x16x32_bf16 v[62:65], v[146:149], v[162:165], v[62:65]
	v_mfma_f32_16x16x32_bf16 v[58:61], v[154:157], v[162:165], v[58:61]
	s_waitcnt lgkmcnt(5)
	v_mfma_f32_16x16x32_bf16 v[54:57], v[146:149], v[170:173], v[54:57]
	v_mfma_f32_16x16x32_bf16 v[44:47], v[154:157], v[170:173], v[44:47]
	s_waitcnt lgkmcnt(3)
	v_mfma_f32_16x16x32_bf16 v[36:39], v[146:149], v[180:183], v[36:39]
	v_mfma_f32_16x16x32_bf16 v[28:31], v[154:157], v[180:183], v[28:31]
	s_waitcnt lgkmcnt(1)
	v_mfma_f32_16x16x32_bf16 v[20:23], v[146:149], v[188:191], v[20:23]
	v_mfma_f32_16x16x32_bf16 v[12:15], v[154:157], v[188:191], v[12:15]
	v_mfma_f32_16x16x32_bf16 v[62:65], v[150:153], v[166:169], v[62:65]
	v_mfma_f32_16x16x32_bf16 v[58:61], v[158:161], v[166:169], v[58:61]
	v_mfma_f32_16x16x32_bf16 v[54:57], v[150:153], v[176:179], v[54:57]
	v_mfma_f32_16x16x32_bf16 v[44:47], v[158:161], v[176:179], v[44:47]
	v_mfma_f32_16x16x32_bf16 v[36:39], v[150:153], v[184:187], v[36:39]
	v_mfma_f32_16x16x32_bf16 v[28:31], v[158:161], v[184:187], v[28:31]
	s_waitcnt lgkmcnt(0)
	v_mfma_f32_16x16x32_bf16 v[20:23], v[150:153], v[192:195], v[20:23]
	v_mfma_f32_16x16x32_bf16 v[12:15], v[158:161], v[192:195], v[12:15]
	s_setprio 1
	s_barrier
; #define PG8_STAGE(bufoff, gbase, voff) do { _Pragma("unroll") for (int _i = 0; _i < 2; ++_i) \
;         __builtin_amdgcn_global_load_lds((const unsigned*)((const char*)(gbase) + (voff)[_i]), (PG8_LAS unsigned*)(lds + (bufoff) + ldsw + _i * 8192), 16, 0, 0); } while (0)
; #define PG8_LDA(dst, b, h) do { _Pragma("unroll") for (int m = 0; m < 4; ++m) _Pragma("unroll") for (int k = 0; k < 2; ++k) dst[m][k] = *(const PG8_LAS bf16x8*)(lds + PG8_SA(b, h) + aoff + m * 2048 + k * 1024); } while (0)
; #define PG8_LDB(dst, b, h) do { _Pragma("unroll") for (int n = 0; n < 2; ++n) _Pragma("unroll") for (int k = 0; k < 2; ++k) dst[n][k] = *(const PG8_LAS bf16x8*)(lds + PG8_SB(b, h) + boff + n * 2048 + k * 1024); } while (0)
; #define PG8_MMA(ai, bj, At, Bt) do { __builtin_amdgcn_s_setprio(1); _Pragma("unroll") for (int m = 0; m < 4; ++m) _Pragma("unroll") for (int n = 0; n < 2; ++n) _Pragma("unroll") for (int k = 0; k < 2; ++k) \
;         acc[ai][bj][m][n] = __builtin_amdgcn_mfma_f32_16x16x32_bf16(Bt[n][k], At[m][k], acc[ai][bj][m][n], 0, 0, 0); __builtin_amdgcn_s_setprio(0); } while (0)
; #define PG8_WAIT_V(n) asm volatile("s_waitcnt vmcnt(" #n ")" ::: "memory")
; #define PG8_WAIT_L(n) asm volatile("s_waitcnt lgkmcnt(" #n ")" ::: "memory")
; #define PG8_BAR __builtin_amdgcn_s_barrier()
; #define PG8_SCHED __builtin_amdgcn_sched_barrier(0)
; template <class Epi, class Sched>
; __device__ __forceinline__ void gemm_phase(PG8_LAS unsigned char* lds, const Gemm g, const Sched& S, const Epi& E) {
;     ...
;             PG8_STAGE(PG8_SB(0, 1), b2 + hstep, voffB);
;             PG8_WAIT_V(6); PG8_BAR; PG8_MMA(1, 1, At, B1); PG8_BAR;
;             PG8_LDB(B0, 1, 0); PG8_SCHED; PG8_LDA(At, 1, 0); PG8_STAGE(PG8_SA(0, 1), a2 + hstep, voffA);
;             PG8_WAIT_L(8); PG8_BAR; PG8_WAIT_L(0); PG8_MMA(0, 0, At, B0); PG8_BAR; PG8_SCHED;
;             PG8_LDB(B1, 1, 1); PG8_STAGE(PG8_SB(1, 0), b3, voffB);
	s_add_u32 s66, s34, 0x40000
	s_addc_u32 s67, s35, 0
	s_add_i32 s65, s68, s13
	v_lshl_add_u64 v[146:147], s[66:67], 0, v[48:49]
	s_mov_b32 m0, s65
	s_nop 0
	global_load_lds_dwordx4 v[146:147], off
	v_lshl_add_u64 v[146:147], s[66:67], 0, v[130:131]
	s_add_i32 m0, s65, 0x2000
	s_nop 0
	global_load_lds_dwordx4 v[146:147], off
	s_waitcnt vmcnt(6)
	s_barrier
	s_setprio 0
	v_mfma_f32_16x16x32_bf16 v[50:53], v[196:199], v[162:165], v[50:53]
	v_mfma_f32_16x16x32_bf16 v[40:43], v[204:207], v[162:165], v[40:43]
	v_mfma_f32_16x16x32_bf16 v[32:35], v[196:199], v[170:173], v[32:35]
	v_mfma_f32_16x16x32_bf16 v[24:27], v[204:207], v[170:173], v[24:27]
	v_mfma_f32_16x16x32_bf16 v[16:19], v[196:199], v[180:183], v[16:19]
	v_mfma_f32_16x16x32_bf16 v[8:11], v[204:207], v[180:183], v[8:11]
	v_mfma_f32_16x16x32_bf16 v[4:7], v[196:199], v[188:191], v[4:7]
	v_mfma_f32_16x16x32_bf16 v[0:3], v[204:207], v[188:191], v[0:3]
	v_mfma_f32_16x16x32_bf16 v[50:53], v[200:203], v[166:169], v[50:53]
	v_mfma_f32_16x16x32_bf16 v[40:43], v[208:211], v[166:169], v[40:43]
	v_mfma_f32_16x16x32_bf16 v[32:35], v[200:203], v[176:179], v[32:35]
	v_mfma_f32_16x16x32_bf16 v[24:27], v[208:211], v[176:179], v[24:27]
	v_mfma_f32_16x16x32_bf16 v[16:19], v[200:203], v[184:187], v[16:19]
	v_mfma_f32_16x16x32_bf16 v[8:11], v[208:211], v[184:187], v[8:11]
	v_mfma_f32_16x16x32_bf16 v[4:7], v[200:203], v[192:195], v[4:7]
	v_mfma_f32_16x16x32_bf16 v[0:3], v[208:211], v[192:195], v[0:3]
	s_setprio 1
	s_add_i32 s65, 0, 0x18000
	v_add_u32_e32 v158, s65, v143
	s_barrier
	ds_read_b128 v[146:149], v158
	ds_read_b128 v[150:153], v158 offset:1024
	ds_read_b128 v[154:157], v158 offset:2048
	ds_read_b128 v[158:161], v158 offset:3072
	s_add_u32 s36, s36, 0x40000
	s_addc_u32 s37, s37, 0
	s_mov_b32 m0, s47
	v_lshl_add_u64 v[196:197], s[36:37], 0, v[134:135]
	ds_read_b128 v[162:165], v145 offset:32768
	ds_read_b128 v[166:169], v145 offset:33792
	ds_read_b128 v[170:173], v145 offset:34816
	ds_read_b128 v[176:179], v145 offset:35840
	ds_read_b128 v[180:183], v145 offset:36864
	ds_read_b128 v[184:187], v145 offset:37888
	ds_read_b128 v[188:191], v145 offset:38912
	ds_read_b128 v[192:195], v145 offset:39936
	global_load_lds_dwordx4 v[196:197], off
	v_lshl_add_u64 v[196:197], s[36:37], 0, v[132:133]
	s_mov_b32 m0, s48
	s_nop 0
	global_load_lds_dwordx4 v[196:197], off
	s_waitcnt lgkmcnt(8)
	s_barrier
	s_setprio 0
	s_waitcnt lgkmcnt(7)
	v_mfma_f32_16x16x32_bf16 v[126:129], v[146:149], v[162:165], v[126:129]
	v_mfma_f32_16x16x32_bf16 v[122:125], v[154:157], v[162:165], v[122:125]
	s_waitcnt lgkmcnt(5)
	v_mfma_f32_16x16x32_bf16 v[118:121], v[146:149], v[170:173], v[118:121]
	v_mfma_f32_16x16x32_bf16 v[110:113], v[154:157], v[170:173], v[110:113]
	s_waitcnt lgkmcnt(3)
	v_mfma_f32_16x16x32_bf16 v[102:105], v[146:149], v[180:183], v[102:105]
	v_mfma_f32_16x16x32_bf16 v[94:97], v[154:157], v[180:183], v[94:97]
	s_waitcnt lgkmcnt(1)
	v_mfma_f32_16x16x32_bf16 v[86:89], v[146:149], v[188:191], v[86:89]
	v_mfma_f32_16x16x32_bf16 v[78:81], v[154:157], v[188:191], v[78:81]
	v_mfma_f32_16x16x32_bf16 v[126:129], v[150:153], v[166:169], v[126:129]
	v_mfma_f32_16x16x32_bf16 v[122:125], v[158:161], v[166:169], v[122:125]
	v_mfma_f32_16x16x32_bf16 v[118:121], v[150:153], v[176:179], v[118:121]
	v_mfma_f32_16x16x32_bf16 v[110:113], v[158:161], v[176:179], v[110:113]
	v_mfma_f32_16x16x32_bf16 v[102:105], v[150:153], v[184:187], v[102:105]
	v_mfma_f32_16x16x32_bf16 v[94:97], v[158:161], v[184:187], v[94:97]
	s_waitcnt lgkmcnt(0)
	v_mfma_f32_16x16x32_bf16 v[86:89], v[150:153], v[192:195], v[86:89]
	v_mfma_f32_16x16x32_bf16 v[78:81], v[158:161], v[192:195], v[78:81]
	s_setprio 1
	s_barrier
	s_add_i32 s36, 0, 0x1c000
	s_add_i32 s37, s65, s13
	v_add_u32_e32 v175, s36, v143
	v_lshl_add_u64 v[140:141], v[140:141], 0, s[0:1]
	s_mov_b32 m0, s37
	ds_read_b128 v[196:199], v175
	ds_read_b128 v[200:203], v175 offset:1024
	ds_read_b128 v[204:207], v175 offset:2048
	ds_read_b128 v[208:211], v175 offset:3072
	global_load_lds_dwordx4 v[140:141], off
	v_lshl_add_u64 v[140:141], v[212:213], 0, s[0:1]
	s_add_i32 m0, s37, 0x2000
	s_nop 0
	global_load_lds_dwordx4 v[140:141], off
	s_barrier
; #define PG8_STAGE(bufoff, gbase, voff) do { _Pragma("unroll") for (int _i = 0; _i < 2; ++_i) \
;         __builtin_amdgcn_global_load_lds((const unsigned*)((const char*)(gbase) + (voff)[_i]), (PG8_LAS unsigned*)(lds + (bufoff) + ldsw + _i * 8192), 16, 0, 0); } while (0)
; #define PG8_LDA(dst, b, h) do { _Pragma("unroll") for (int m = 0; m < 4; ++m) _Pragma("unroll") for (int k = 0; k < 2; ++k) dst[m][k] = *(const PG8_LAS bf16x8*)(lds + PG8_SA(b, h) + aoff + m * 2048 + k * 1024); } while (0)
; #define PG8_MMA(ai, bj, At, Bt) do { __builtin_amdgcn_s_setprio(1); _Pragma("unroll") for (int m = 0; m < 4; ++m) _Pragma("unroll") for (int n = 0; n < 2; ++n) _Pragma("unroll") for (int k = 0; k < 2; ++k) \
;         acc[ai][bj][m][n] = __builtin_amdgcn_mfma_f32_16x16x32_bf16(Bt[n][k], At[m][k], acc[ai][bj][m][n], 0, 0, 0); __builtin_amdgcn_s_setprio(0); } while (0)
; #define PG8_WAIT_V(n) asm volatile("s_waitcnt vmcnt(" #n ")" ::: "memory")
; #define PG8_WAIT_L(n) asm volatile("s_waitcnt lgkmcnt(" #n ")" ::: "memory")
; #define PG8_BAR __builtin_amdgcn_s_barrier()
; #define PG8_SCHED __builtin_amdgcn_sched_barrier(0)
; template <class Epi, class Sched>
; __device__ __forceinline__ void gemm_phase(PG8_LAS unsigned char* lds, const Gemm g, const Sched& S, const Epi& E) {
;     ...
;             PG8_BAR; PG8_WAIT_L(0); PG8_MMA(0, 1, At, B1); PG8_BAR;
;             PG8_LDA(At, 1, 1); PG8_STAGE(PG8_SA(1, 0), a3, voffA);
;             PG8_BAR; PG8_WAIT_L(0); PG8_MMA(1, 0, At, B0); PG8_BAR; PG8_SCHED;
;             PG8_STAGE(PG8_SB(1, 1), b3 + hstep, voffB);
;             PG8_WAIT_V(6); PG8_BAR; PG8_MMA(1, 1, At, B1); PG8_BAR;
	s_setprio 0
	s_waitcnt lgkmcnt(3)
	v_mfma_f32_16x16x32_bf16 v[114:117], v[196:199], v[162:165], v[114:117]
	s_waitcnt lgkmcnt(1)
	v_mfma_f32_16x16x32_bf16 v[106:109], v[204:207], v[162:165], v[106:109]
	v_mfma_f32_16x16x32_bf16 v[98:101], v[196:199], v[170:173], v[98:101]
	v_mfma_f32_16x16x32_bf16 v[90:93], v[204:207], v[170:173], v[90:93]
	v_mfma_f32_16x16x32_bf16 v[82:85], v[196:199], v[180:183], v[82:85]
	v_mfma_f32_16x16x32_bf16 v[74:77], v[204:207], v[180:183], v[74:77]
	v_mfma_f32_16x16x32_bf16 v[70:73], v[196:199], v[188:191], v[70:73]
	v_mfma_f32_16x16x32_bf16 v[66:69], v[204:207], v[188:191], v[66:69]
	v_mfma_f32_16x16x32_bf16 v[114:117], v[200:203], v[166:169], v[114:117]
	s_waitcnt lgkmcnt(0)
	v_mfma_f32_16x16x32_bf16 v[106:109], v[208:211], v[166:169], v[106:109]
	v_mfma_f32_16x16x32_bf16 v[98:101], v[200:203], v[176:179], v[98:101]
	v_mfma_f32_16x16x32_bf16 v[90:93], v[208:211], v[176:179], v[90:93]
	v_mfma_f32_16x16x32_bf16 v[82:85], v[200:203], v[184:187], v[82:85]
	v_mfma_f32_16x16x32_bf16 v[74:77], v[208:211], v[184:187], v[74:77]
	v_mfma_f32_16x16x32_bf16 v[70:73], v[200:203], v[192:195], v[70:73]
	v_mfma_f32_16x16x32_bf16 v[66:69], v[208:211], v[192:195], v[66:69]
	s_setprio 1
	s_mov_b32 m0, s49
	v_lshl_add_u64 v[140:141], v[214:215], 0, s[0:1]
	s_barrier
	ds_read_b128 v[162:165], v145 offset:49152
	ds_read_b128 v[166:169], v145 offset:50176
	ds_read_b128 v[170:173], v145 offset:51200
	ds_read_b128 v[176:179], v145 offset:52224
	ds_read_b128 v[180:183], v145 offset:53248
	ds_read_b128 v[184:187], v145 offset:54272
	ds_read_b128 v[188:191], v145 offset:55296
	ds_read_b128 v[192:195], v145 offset:56320
	global_load_lds_dwordx4 v[140:141], off
	v_lshl_add_u64 v[140:141], v[216:217], 0, s[0:1]
	s_mov_b32 m0, s50
	s_nop 0
	global_load_lds_dwordx4 v[140:141], off
	s_barrier
	s_setprio 0
	s_waitcnt lgkmcnt(7)
	v_mfma_f32_16x16x32_bf16 v[62:65], v[146:149], v[162:165], v[62:65]
	v_mfma_f32_16x16x32_bf16 v[58:61], v[154:157], v[162:165], v[58:61]
	s_waitcnt lgkmcnt(5)
	v_mfma_f32_16x16x32_bf16 v[54:57], v[146:149], v[170:173], v[54:57]
	v_mfma_f32_16x16x32_bf16 v[44:47], v[154:157], v[170:173], v[44:47]
	s_waitcnt lgkmcnt(3)
	v_mfma_f32_16x16x32_bf16 v[36:39], v[146:149], v[180:183], v[36:39]
	v_mfma_f32_16x16x32_bf16 v[28:31], v[154:157], v[180:183], v[28:31]
	s_waitcnt lgkmcnt(1)
	v_mfma_f32_16x16x32_bf16 v[20:23], v[146:149], v[188:191], v[20:23]
	v_mfma_f32_16x16x32_bf16 v[12:15], v[154:157], v[188:191], v[12:15]
	v_mfma_f32_16x16x32_bf16 v[62:65], v[150:153], v[166:169], v[62:65]
	v_mfma_f32_16x16x32_bf16 v[58:61], v[158:161], v[166:169], v[58:61]
	v_mfma_f32_16x16x32_bf16 v[54:57], v[150:153], v[176:179], v[54:57]
	v_mfma_f32_16x16x32_bf16 v[44:47], v[158:161], v[176:179], v[44:47]
	v_mfma_f32_16x16x32_bf16 v[36:39], v[150:153], v[184:187], v[36:39]
	v_mfma_f32_16x16x32_bf16 v[28:31], v[158:161], v[184:187], v[28:31]
	s_waitcnt lgkmcnt(0)
	v_mfma_f32_16x16x32_bf16 v[20:23], v[150:153], v[192:195], v[20:23]
	v_mfma_f32_16x16x32_bf16 v[12:15], v[158:161], v[192:195], v[12:15]
	s_setprio 1
	s_barrier
	s_add_u32 s34, s34, 0x40080
	s_addc_u32 s35, s35, 0
	s_add_i32 s36, s36, s13
	v_lshl_add_u64 v[140:141], s[34:35], 0, v[48:49]
	s_mov_b32 m0, s36
	s_nop 0
	global_load_lds_dwordx4 v[140:141], off
	v_lshl_add_u64 v[140:141], s[34:35], 0, v[130:131]
	s_add_i32 m0, s36, 0x2000
	s_nop 0
	global_load_lds_dwordx4 v[140:141], off
	s_waitcnt vmcnt(6)
	s_barrier
	s_setprio 0
	v_mfma_f32_16x16x32_bf16 v[50:53], v[196:199], v[162:165], v[50:53]
	v_mfma_f32_16x16x32_bf16 v[40:43], v[204:207], v[162:165], v[40:43]
	v_mfma_f32_16x16x32_bf16 v[32:35], v[196:199], v[170:173], v[32:35]
	v_mfma_f32_16x16x32_bf16 v[24:27], v[204:207], v[170:173], v[24:27]
	v_mfma_f32_16x16x32_bf16 v[16:19], v[196:199], v[180:183], v[16:19]
	v_mfma_f32_16x16x32_bf16 v[8:11], v[204:207], v[180:183], v[8:11]
	v_mfma_f32_16x16x32_bf16 v[4:7], v[196:199], v[188:191], v[4:7]
	v_mfma_f32_16x16x32_bf16 v[0:3], v[204:207], v[188:191], v[0:3]
	v_mfma_f32_16x16x32_bf16 v[50:53], v[200:203], v[166:169], v[50:53]
	v_mfma_f32_16x16x32_bf16 v[40:43], v[208:211], v[166:169], v[40:43]
	v_mfma_f32_16x16x32_bf16 v[32:35], v[200:203], v[176:179], v[32:35]
	v_mfma_f32_16x16x32_bf16 v[24:27], v[208:211], v[176:179], v[24:27]
	v_mfma_f32_16x16x32_bf16 v[16:19], v[200:203], v[184:187], v[16:19]
	v_mfma_f32_16x16x32_bf16 v[8:11], v[208:211], v[184:187], v[8:11]
	v_mfma_f32_16x16x32_bf16 v[4:7], v[200:203], v[192:195], v[4:7]
	v_mfma_f32_16x16x32_bf16 v[0:3], v[208:211], v[192:195], v[0:3]
	s_setprio 1
	s_add_i32 s64, s64, 2
	s_add_u32 s30, s30, 0x100
	s_addc_u32 s31, s31, 0
	s_add_u32 s59, s59, 0x100
	s_addc_u32 s63, s63, 0
	s_cmp_gt_u32 s64, 13
	s_barrier
	s_cbranch_scc0 .LBB0_320
.Lkpeel_exit_320:
	s_setprio 0
	s_andn2_b64 vcc, exec, s[16:17]
	s_lshl_b32 s23, s55, 8
	s_cbranch_vccz .LBB0_315
	s_mov_b64 s[30:31], s[2:3]
	s_branch .LBB0_316

; #define PG8_STAGE(bufoff, gbase, voff) do { _Pragma("unroll") for (int _i = 0; _i < 2; ++_i) \
;         __builtin_amdgcn_global_load_lds((const unsigned*)((const char*)(gbase) + (voff)[_i]), (PG8_LAS unsigned*)(lds + (bufoff) + ldsw + _i * 8192), 16, 0, 0); } while (0)
; #define PG8_LDA(dst, b, h) do { _Pragma("unroll") for (int m = 0; m < 4; ++m) _Pragma("unroll") for (int k = 0; k < 2; ++k) dst[m][k] = *(const PG8_LAS bf16x8*)(lds + PG8_SA(b, h) + aoff + m * 2048 + k * 1024); } while (0)
; #define PG8_LDB(dst, b, h) do { _Pragma("unroll") for (int n = 0; n < 2; ++n) _Pragma("unroll") for (int k = 0; k < 2; ++k) dst[n][k] = *(const PG8_LAS bf16x8*)(lds + PG8_SB(b, h) + boff + n * 2048 + k * 1024); } while (0)
; #define PG8_MMA(ai, bj, At, Bt) do { __builtin_amdgcn_s_setprio(1); _Pragma("unroll") for (int m = 0; m < 4; ++m) _Pragma("unroll") for (int n = 0; n < 2; ++n) _Pragma("unroll") for (int k = 0; k < 2; ++k) \
;         acc[ai][bj][m][n] = __builtin_amdgcn_mfma_f32_16x16x32_bf16(Bt[n][k], At[m][k], acc[ai][bj][m][n], 0, 0, 0); __builtin_amdgcn_s_setprio(0); } while (0)
; #define PG8_BAR __builtin_amdgcn_s_barrier()
; template <class Epi, class Sched>
; __device__ __forceinline__ void gemm_phase(PG8_LAS unsigned char* lds, const Gemm g, const Sched& S, const Epi& E) {
;     ...
;         const bool has_next = S.next(ui + 1, nxt);
;         const char* nA = has_next ? (const char*)g.A + (size_t)nxt.pm * tstepA + (size_t)nxt.kc * cstep : cA; const char* nB = has_next ? (const char*)g.Bt + (size_t)nxt.pn * tstep + (size_t)nxt.kc * cstep : cB;
;         for (int t = 0; t < nt; t += 2) {
;             const bool last = (t == nt - 2);
;             const char* a1 = cA + (size_t)(t + 1) * kstep;
;             const char* a2 = last ? nA : cA + (size_t)(t + 2) * kstep; const char* b2 = last ? nB : cB + (size_t)(t + 2) * kstep;
;             const char* a3 = a2 + kstep; const char* b3 = b2 + kstep;
;             if (last && has_next) S.a_ready(nxt);
;             PG8_LDB(B0, 0, 0); PG8_SCHED; PG8_LDA(At, 0, 0); PG8_STAGE(PG8_SA(1, 1), a1 + hstep, voffA);
;             PG8_WAIT_L(8); PG8_BAR; PG8_WAIT_L(0); PG8_MMA(0, 0, At, B0); PG8_BAR; PG8_SCHED;
;             PG8_LDB(B1, 0, 1); PG8_STAGE(PG8_SB(0, 0), b2, voffB);
;             PG8_BAR; PG8_WAIT_L(0); PG8_MMA(0, 1, At, B1); PG8_BAR;
;             PG8_LDA(At, 0, 1); PG8_STAGE(PG8_SA(0, 0), a2, voffA);
.LBB0_334:
	v_mov_b64_e32 v[0:1], 0x440
	s_ashr_i32 s23, s22, 31
	v_cmp_lt_i64_e32 vcc, s[16:17], v[0:1]
	s_lshl_b64 s[16:17], s[22:23], 19
	s_add_u32 s24, s28, s16
	s_addc_u32 s25, s29, s17
	s_and_b64 s[16:17], vcc, exec
	s_cselect_b32 s23, s25, s7
	s_cselect_b32 s50, s24, s6
	s_ashr_i32 s21, s20, 31
	s_lshl_b64 s[16:17], s[20:21], 19
	s_add_u32 s26, s30, s16
	s_addc_u32 s27, s31, s17
	s_and_b64 s[16:17], vcc, exec
	s_cselect_b32 s21, s27, s13
	s_cselect_b32 s51, s26, s12
	s_add_u32 s6, s6, 0x40080
	s_addc_u32 s7, s7, 0
	s_add_u32 s54, s12, 0x100
	s_addc_u32 s55, s13, 0
	s_mov_b32 s56, -2
	s_add_u32 s12, s6, 0xfffc0080
	s_addc_u32 s13, s7, -1
	s_add_i32 s57, 0, 0x10000
	v_add_u32_e32 v48, s57, v166
	ds_read_b128 v[144:147], v48
	ds_read_b128 v[148:151], v48 offset:1024
	ds_read_b128 v[152:155], v48 offset:2048
	ds_read_b128 v[156:159], v48 offset:3072
	s_cmp_eq_u32 s56, 12
	s_cselect_b32 s17, s23, s13
	s_cselect_b32 s16, s50, s12
	s_cselect_b32 s13, s21, s55
	s_cselect_b32 s12, s51, s54
	v_lshl_add_u64 v[164:165], s[6:7], 0, v[140:141]
	s_add_i32 m0, s3, 0xc000
	ds_read_b128 v[160:163], v167
	ds_read_b128 v[168:171], v167 offset:1024
	ds_read_b128 v[176:179], v167 offset:2048
	ds_read_b128 v[180:183], v167 offset:3072
	ds_read_b128 v[184:187], v167 offset:4096
	ds_read_b128 v[188:191], v167 offset:5120
	ds_read_b128 v[192:195], v167 offset:6144
	ds_read_b128 v[196:199], v167 offset:7168
	global_load_lds_dwordx4 v[164:165], off
	v_lshl_add_u64 v[164:165], s[6:7], 0, v[142:143]
	s_add_i32 m0, s3, 0xe000
	s_nop 0
	global_load_lds_dwordx4 v[164:165], off
	s_waitcnt lgkmcnt(8)
	s_barrier
	s_setprio 0
	s_waitcnt lgkmcnt(7)
	v_mfma_f32_16x16x32_bf16 v[126:129], v[144:147], v[160:163], 0
	v_mfma_f32_16x16x32_bf16 v[122:125], v[152:155], v[160:163], 0
	s_waitcnt lgkmcnt(5)
	v_mfma_f32_16x16x32_bf16 v[110:113], v[144:147], v[176:179], 0
	v_mfma_f32_16x16x32_bf16 v[106:109], v[152:155], v[176:179], 0
	s_waitcnt lgkmcnt(3)
	v_mfma_f32_16x16x32_bf16 v[94:97], v[144:147], v[184:187], 0
	v_mfma_f32_16x16x32_bf16 v[90:93], v[152:155], v[184:187], 0
	s_waitcnt lgkmcnt(1)
	v_mfma_f32_16x16x32_bf16 v[78:81], v[144:147], v[192:195], 0
	v_mfma_f32_16x16x32_bf16 v[74:77], v[152:155], v[192:195], 0
	v_mfma_f32_16x16x32_bf16 v[126:129], v[148:151], v[168:171], v[126:129]
	v_mfma_f32_16x16x32_bf16 v[122:125], v[156:159], v[168:171], v[122:125]
	v_mfma_f32_16x16x32_bf16 v[110:113], v[148:151], v[180:183], v[110:113]
	v_mfma_f32_16x16x32_bf16 v[106:109], v[156:159], v[180:183], v[106:109]
	v_mfma_f32_16x16x32_bf16 v[94:97], v[148:151], v[188:191], v[94:97]
	v_mfma_f32_16x16x32_bf16 v[90:93], v[156:159], v[188:191], v[90:93]
	s_waitcnt lgkmcnt(0)
	v_mfma_f32_16x16x32_bf16 v[78:81], v[148:151], v[196:199], v[78:81]
	v_mfma_f32_16x16x32_bf16 v[74:77], v[156:159], v[196:199], v[74:77]
	s_setprio 1
	s_barrier
	s_add_i32 s59, 0, 0x14000
	s_add_i32 s57, s57, s34
	v_add_u32_e32 v48, s59, v166
	v_lshl_add_u64 v[164:165], s[12:13], 0, v[134:135]
	s_mov_b32 m0, s57
	ds_read_b128 v[200:203], v48
	ds_read_b128 v[204:207], v48 offset:1024
	ds_read_b128 v[208:211], v48 offset:2048
	ds_read_b128 v[212:215], v48 offset:3072
	global_load_lds_dwordx4 v[164:165], off
	v_lshl_add_u64 v[172:173], s[12:13], 0, v[130:131]
	s_add_i32 m0, s57, 0x2000
	s_nop 0
	global_load_lds_dwordx4 v[172:173], off
	s_barrier
	s_setprio 0
	s_waitcnt lgkmcnt(3)
	v_mfma_f32_16x16x32_bf16 v[118:121], v[200:203], v[160:163], 0
	s_waitcnt lgkmcnt(1)
	v_mfma_f32_16x16x32_bf16 v[114:117], v[208:211], v[160:163], 0
	v_mfma_f32_16x16x32_bf16 v[102:105], v[200:203], v[176:179], 0
	v_mfma_f32_16x16x32_bf16 v[98:101], v[208:211], v[176:179], 0
	v_mfma_f32_16x16x32_bf16 v[86:89], v[200:203], v[184:187], 0
	v_mfma_f32_16x16x32_bf16 v[82:85], v[208:211], v[184:187], 0
	v_mfma_f32_16x16x32_bf16 v[70:73], v[200:203], v[192:195], 0
	v_mfma_f32_16x16x32_bf16 v[66:69], v[208:211], v[192:195], 0
	v_mfma_f32_16x16x32_bf16 v[118:121], v[204:207], v[168:171], v[118:121]
	s_waitcnt lgkmcnt(0)
	v_mfma_f32_16x16x32_bf16 v[114:117], v[212:215], v[168:171], v[114:117]
	v_mfma_f32_16x16x32_bf16 v[102:105], v[204:207], v[180:183], v[102:105]
	v_mfma_f32_16x16x32_bf16 v[98:101], v[212:215], v[180:183], v[98:101]
	v_mfma_f32_16x16x32_bf16 v[86:89], v[204:207], v[188:191], v[86:89]
	v_mfma_f32_16x16x32_bf16 v[82:85], v[212:215], v[188:191], v[82:85]
	v_mfma_f32_16x16x32_bf16 v[70:73], v[204:207], v[196:199], v[70:73]
	v_mfma_f32_16x16x32_bf16 v[66:69], v[212:215], v[196:199], v[66:69]
	s_setprio 1
	s_mov_b32 m0, s3
	v_lshl_add_u64 v[216:217], s[16:17], 0, v[136:137]
	s_barrier
	ds_read_b128 v[160:163], v167 offset:16384
	ds_read_b128 v[168:171], v167 offset:17408
	ds_read_b128 v[176:179], v167 offset:18432
	ds_read_b128 v[180:183], v167 offset:19456
	ds_read_b128 v[184:187], v167 offset:20480
	ds_read_b128 v[188:191], v167 offset:21504
	ds_read_b128 v[192:195], v167 offset:22528
	ds_read_b128 v[196:199], v167 offset:23552
	global_load_lds_dwordx4 v[216:217], off
	v_lshl_add_u64 v[218:219], s[16:17], 0, v[132:133]
	s_mov_b32 m0, s36
	s_nop 0
	global_load_lds_dwordx4 v[218:219], off
	s_barrier
; #define PG8_STAGE(bufoff, gbase, voff) do { _Pragma("unroll") for (int _i = 0; _i < 2; ++_i) \
;         __builtin_amdgcn_global_load_lds((const unsigned*)((const char*)(gbase) + (voff)[_i]), (PG8_LAS unsigned*)(lds + (bufoff) + ldsw + _i * 8192), 16, 0, 0); } while (0)
; #define PG8_LDA(dst, b, h) do { _Pragma("unroll") for (int m = 0; m < 4; ++m) _Pragma("unroll") for (int k = 0; k < 2; ++k) dst[m][k] = *(const PG8_LAS bf16x8*)(lds + PG8_SA(b, h) + aoff + m * 2048 + k * 1024); } while (0)
; #define PG8_LDB(dst, b, h) do { _Pragma("unroll") for (int n = 0; n < 2; ++n) _Pragma("unroll") for (int k = 0; k < 2; ++k) dst[n][k] = *(const PG8_LAS bf16x8*)(lds + PG8_SB(b, h) + boff + n * 2048 + k * 1024); } while (0)
; #define PG8_MMA(ai, bj, At, Bt) do { __builtin_amdgcn_s_setprio(1); _Pragma("unroll") for (int m = 0; m < 4; ++m) _Pragma("unroll") for (int n = 0; n < 2; ++n) _Pragma("unroll") for (int k = 0; k < 2; ++k) \
;         acc[ai][bj][m][n] = __builtin_amdgcn_mfma_f32_16x16x32_bf16(Bt[n][k], At[m][k], acc[ai][bj][m][n], 0, 0, 0); __builtin_amdgcn_s_setprio(0); } while (0)
; #define PG8_WAIT_V(n) asm volatile("s_waitcnt vmcnt(" #n ")" ::: "memory")
; #define PG8_WAIT_L(n) asm volatile("s_waitcnt lgkmcnt(" #n ")" ::: "memory")
; #define PG8_BAR __builtin_amdgcn_s_barrier()
; #define PG8_SCHED __builtin_amdgcn_sched_barrier(0)
; template <class Epi, class Sched>
; __device__ __forceinline__ void gemm_phase(PG8_LAS unsigned char* lds, const Gemm g, const Sched& S, const Epi& E) {
;     ...
;             PG8_BAR; PG8_WAIT_L(0); PG8_MMA(1, 0, At, B0); PG8_BAR; PG8_SCHED;
;             PG8_STAGE(PG8_SB(0, 1), b2 + hstep, voffB);
;             PG8_WAIT_V(6); PG8_BAR; PG8_MMA(1, 1, At, B1); PG8_BAR;
;             PG8_LDB(B0, 1, 0); PG8_SCHED; PG8_LDA(At, 1, 0); PG8_STAGE(PG8_SA(0, 1), a2 + hstep, voffA);
;             PG8_WAIT_L(8); PG8_BAR; PG8_WAIT_L(0); PG8_MMA(0, 0, At, B0); PG8_BAR; PG8_SCHED;
;             PG8_LDB(B1, 1, 1); PG8_STAGE(PG8_SB(1, 0), b3, voffB);
	s_setprio 0
	s_waitcnt lgkmcnt(7)
	v_mfma_f32_16x16x32_bf16 v[62:65], v[144:147], v[160:163], 0
	v_mfma_f32_16x16x32_bf16 v[58:61], v[152:155], v[160:163], 0
	s_waitcnt lgkmcnt(5)
	v_mfma_f32_16x16x32_bf16 v[44:47], v[144:147], v[176:179], 0
	v_mfma_f32_16x16x32_bf16 v[40:43], v[152:155], v[176:179], 0
	s_waitcnt lgkmcnt(3)
	v_mfma_f32_16x16x32_bf16 v[28:31], v[144:147], v[184:187], 0
	v_mfma_f32_16x16x32_bf16 v[24:27], v[152:155], v[184:187], 0
	s_waitcnt lgkmcnt(1)
	v_mfma_f32_16x16x32_bf16 v[12:15], v[144:147], v[192:195], 0
	v_mfma_f32_16x16x32_bf16 v[8:11], v[152:155], v[192:195], 0
	v_mfma_f32_16x16x32_bf16 v[62:65], v[148:151], v[168:171], v[62:65]
	v_mfma_f32_16x16x32_bf16 v[58:61], v[156:159], v[168:171], v[58:61]
	v_mfma_f32_16x16x32_bf16 v[44:47], v[148:151], v[180:183], v[44:47]
	v_mfma_f32_16x16x32_bf16 v[40:43], v[156:159], v[180:183], v[40:43]
	v_mfma_f32_16x16x32_bf16 v[28:31], v[148:151], v[188:191], v[28:31]
	v_mfma_f32_16x16x32_bf16 v[24:27], v[156:159], v[188:191], v[24:27]
	s_waitcnt lgkmcnt(0)
	v_mfma_f32_16x16x32_bf16 v[12:15], v[148:151], v[196:199], v[12:15]
	v_mfma_f32_16x16x32_bf16 v[8:11], v[156:159], v[196:199], v[8:11]
	s_setprio 1
	s_barrier
	s_add_u32 s64, s12, 0x40000
	s_addc_u32 s65, s13, 0
	s_add_i32 s57, s59, s34
	v_lshl_add_u64 v[144:145], s[64:65], 0, v[134:135]
	s_mov_b32 m0, s57
	s_nop 0
	global_load_lds_dwordx4 v[144:145], off
	v_lshl_add_u64 v[144:145], s[64:65], 0, v[130:131]
	s_add_i32 m0, s57, 0x2000
	s_nop 0
	global_load_lds_dwordx4 v[144:145], off
	s_waitcnt vmcnt(6)
	s_barrier
	s_setprio 0
	v_mfma_f32_16x16x32_bf16 v[54:57], v[200:203], v[160:163], 0
	v_mfma_f32_16x16x32_bf16 v[50:53], v[208:211], v[160:163], 0
	v_mfma_f32_16x16x32_bf16 v[36:39], v[200:203], v[176:179], 0
	v_mfma_f32_16x16x32_bf16 v[32:35], v[208:211], v[176:179], 0
	v_mfma_f32_16x16x32_bf16 v[20:23], v[200:203], v[184:187], 0
	v_mfma_f32_16x16x32_bf16 v[16:19], v[208:211], v[184:187], 0
	v_mfma_f32_16x16x32_bf16 v[4:7], v[200:203], v[192:195], 0
	v_mfma_f32_16x16x32_bf16 v[0:3], v[208:211], v[192:195], 0
	v_mfma_f32_16x16x32_bf16 v[54:57], v[204:207], v[168:171], v[54:57]
	v_mfma_f32_16x16x32_bf16 v[50:53], v[212:215], v[168:171], v[50:53]
	v_mfma_f32_16x16x32_bf16 v[36:39], v[204:207], v[180:183], v[36:39]
	v_mfma_f32_16x16x32_bf16 v[32:35], v[212:215], v[180:183], v[32:35]
	v_mfma_f32_16x16x32_bf16 v[20:23], v[204:207], v[188:191], v[20:23]
	v_mfma_f32_16x16x32_bf16 v[16:19], v[212:215], v[188:191], v[16:19]
	v_mfma_f32_16x16x32_bf16 v[4:7], v[204:207], v[196:199], v[4:7]
	v_mfma_f32_16x16x32_bf16 v[0:3], v[212:215], v[196:199], v[0:3]
	s_setprio 1
	s_add_i32 s57, 0, 0x18000
	v_add_u32_e32 v48, s57, v166
	s_barrier
	ds_read_b128 v[144:147], v48
	ds_read_b128 v[148:151], v48 offset:1024
	ds_read_b128 v[152:155], v48 offset:2048
	ds_read_b128 v[156:159], v48 offset:3072
	s_add_u32 s16, s16, 0x40000
	s_addc_u32 s17, s17, 0
	s_mov_b32 m0, s37
	v_lshl_add_u64 v[200:201], s[16:17], 0, v[136:137]
	ds_read_b128 v[160:163], v167 offset:32768
	ds_read_b128 v[168:171], v167 offset:33792
	ds_read_b128 v[176:179], v167 offset:34816
	ds_read_b128 v[180:183], v167 offset:35840
	ds_read_b128 v[184:187], v167 offset:36864
	ds_read_b128 v[188:191], v167 offset:37888
	ds_read_b128 v[192:195], v167 offset:38912
	ds_read_b128 v[196:199], v167 offset:39936
	global_load_lds_dwordx4 v[200:201], off
	v_lshl_add_u64 v[200:201], s[16:17], 0, v[132:133]
	s_mov_b32 m0, s38
	s_nop 0
	global_load_lds_dwordx4 v[200:201], off
	s_waitcnt lgkmcnt(8)
	s_barrier
	s_setprio 0
	s_waitcnt lgkmcnt(7)
	v_mfma_f32_16x16x32_bf16 v[126:129], v[144:147], v[160:163], v[126:129]
	v_mfma_f32_16x16x32_bf16 v[122:125], v[152:155], v[160:163], v[122:125]
	s_waitcnt lgkmcnt(5)
	v_mfma_f32_16x16x32_bf16 v[110:113], v[144:147], v[176:179], v[110:113]
	v_mfma_f32_16x16x32_bf16 v[106:109], v[152:155], v[176:179], v[106:109]
	s_waitcnt lgkmcnt(3)
	v_mfma_f32_16x16x32_bf16 v[94:97], v[144:147], v[184:187], v[94:97]
	v_mfma_f32_16x16x32_bf16 v[90:93], v[152:155], v[184:187], v[90:93]
	s_waitcnt lgkmcnt(1)
	v_mfma_f32_16x16x32_bf16 v[78:81], v[144:147], v[192:195], v[78:81]
	v_mfma_f32_16x16x32_bf16 v[74:77], v[152:155], v[192:195], v[74:77]
	v_mfma_f32_16x16x32_bf16 v[126:129], v[148:151], v[168:171], v[126:129]
	v_mfma_f32_16x16x32_bf16 v[122:125], v[156:159], v[168:171], v[122:125]
	v_mfma_f32_16x16x32_bf16 v[110:113], v[148:151], v[180:183], v[110:113]
	v_mfma_f32_16x16x32_bf16 v[106:109], v[156:159], v[180:183], v[106:109]
	v_mfma_f32_16x16x32_bf16 v[94:97], v[148:151], v[188:191], v[94:97]
	v_mfma_f32_16x16x32_bf16 v[90:93], v[156:159], v[188:191], v[90:93]
	s_waitcnt lgkmcnt(0)
	v_mfma_f32_16x16x32_bf16 v[78:81], v[148:151], v[196:199], v[78:81]
	v_mfma_f32_16x16x32_bf16 v[74:77], v[156:159], v[196:199], v[74:77]
	s_setprio 1
	s_barrier
	s_add_i32 s16, 0, 0x1c000
	s_add_i32 s17, s57, s34
	v_add_u32_e32 v48, s16, v166
	v_lshl_add_u64 v[164:165], v[164:165], 0, s[0:1]
	s_mov_b32 m0, s17
	ds_read_b128 v[200:203], v48
	ds_read_b128 v[204:207], v48 offset:1024
	ds_read_b128 v[208:211], v48 offset:2048
	ds_read_b128 v[212:215], v48 offset:3072
	global_load_lds_dwordx4 v[164:165], off
	v_lshl_add_u64 v[164:165], v[172:173], 0, s[0:1]
	s_add_i32 m0, s17, 0x2000
	s_nop 0
	global_load_lds_dwordx4 v[164:165], off
	s_barrier
; #define PG8_STAGE(bufoff, gbase, voff) do { _Pragma("unroll") for (int _i = 0; _i < 2; ++_i) \
;         __builtin_amdgcn_global_load_lds((const unsigned*)((const char*)(gbase) + (voff)[_i]), (PG8_LAS unsigned*)(lds + (bufoff) + ldsw + _i * 8192), 16, 0, 0); } while (0)
; #define PG8_LDA(dst, b, h) do { _Pragma("unroll") for (int m = 0; m < 4; ++m) _Pragma("unroll") for (int k = 0; k < 2; ++k) dst[m][k] = *(const PG8_LAS bf16x8*)(lds + PG8_SA(b, h) + aoff + m * 2048 + k * 1024); } while (0)
; #define PG8_MMA(ai, bj, At, Bt) do { __builtin_amdgcn_s_setprio(1); _Pragma("unroll") for (int m = 0; m < 4; ++m) _Pragma("unroll") for (int n = 0; n < 2; ++n) _Pragma("unroll") for (int k = 0; k < 2; ++k) \
;         acc[ai][bj][m][n] = __builtin_amdgcn_mfma_f32_16x16x32_bf16(Bt[n][k], At[m][k], acc[ai][bj][m][n], 0, 0, 0); __builtin_amdgcn_s_setprio(0); } while (0)
; #define PG8_WAIT_V(n) asm volatile("s_waitcnt vmcnt(" #n ")" ::: "memory")
; #define PG8_WAIT_L(n) asm volatile("s_waitcnt lgkmcnt(" #n ")" ::: "memory")
; #define PG8_BAR __builtin_amdgcn_s_barrier()
; #define PG8_SCHED __builtin_amdgcn_sched_barrier(0)
; template <class Epi, class Sched>
; __device__ __forceinline__ void gemm_phase(PG8_LAS unsigned char* lds, const Gemm g, const Sched& S, const Epi& E) {
;     ...
;             PG8_BAR; PG8_WAIT_L(0); PG8_MMA(0, 1, At, B1); PG8_BAR;
;             PG8_LDA(At, 1, 1); PG8_STAGE(PG8_SA(1, 0), a3, voffA);
;             PG8_BAR; PG8_WAIT_L(0); PG8_MMA(1, 0, At, B0); PG8_BAR; PG8_SCHED;
;             PG8_STAGE(PG8_SB(1, 1), b3 + hstep, voffB);
;             PG8_WAIT_V(6); PG8_BAR; PG8_MMA(1, 1, At, B1); PG8_BAR;
	s_setprio 0
	s_waitcnt lgkmcnt(3)
	v_mfma_f32_16x16x32_bf16 v[118:121], v[200:203], v[160:163], v[118:121]
	s_waitcnt lgkmcnt(1)
	v_mfma_f32_16x16x32_bf16 v[114:117], v[208:211], v[160:163], v[114:117]
	v_mfma_f32_16x16x32_bf16 v[102:105], v[200:203], v[176:179], v[102:105]
	v_mfma_f32_16x16x32_bf16 v[98:101], v[208:211], v[176:179], v[98:101]
	v_mfma_f32_16x16x32_bf16 v[86:89], v[200:203], v[184:187], v[86:89]
	v_mfma_f32_16x16x32_bf16 v[82:85], v[208:211], v[184:187], v[82:85]
	v_mfma_f32_16x16x32_bf16 v[70:73], v[200:203], v[192:195], v[70:73]
	v_mfma_f32_16x16x32_bf16 v[66:69], v[208:211], v[192:195], v[66:69]
	v_mfma_f32_16x16x32_bf16 v[118:121], v[204:207], v[168:171], v[118:121]
	s_waitcnt lgkmcnt(0)
	v_mfma_f32_16x16x32_bf16 v[114:117], v[212:215], v[168:171], v[114:117]
	v_mfma_f32_16x16x32_bf16 v[102:105], v[204:207], v[180:183], v[102:105]
	v_mfma_f32_16x16x32_bf16 v[98:101], v[212:215], v[180:183], v[98:101]
	v_mfma_f32_16x16x32_bf16 v[86:89], v[204:207], v[188:191], v[86:89]
	v_mfma_f32_16x16x32_bf16 v[82:85], v[212:215], v[188:191], v[82:85]
	v_mfma_f32_16x16x32_bf16 v[70:73], v[204:207], v[196:199], v[70:73]
	v_mfma_f32_16x16x32_bf16 v[66:69], v[212:215], v[196:199], v[66:69]
	s_setprio 1
	s_mov_b32 m0, s39
	v_lshl_add_u64 v[164:165], v[216:217], 0, s[0:1]
	s_barrier
	ds_read_b128 v[160:163], v167 offset:49152
	ds_read_b128 v[168:171], v167 offset:50176
	ds_read_b128 v[176:179], v167 offset:51200
	ds_read_b128 v[180:183], v167 offset:52224
	ds_read_b128 v[184:187], v167 offset:53248
	ds_read_b128 v[188:191], v167 offset:54272
	ds_read_b128 v[192:195], v167 offset:55296
	ds_read_b128 v[196:199], v167 offset:56320
	global_load_lds_dwordx4 v[164:165], off
	v_lshl_add_u64 v[164:165], v[218:219], 0, s[0:1]
	s_mov_b32 m0, s42
	s_nop 0
	global_load_lds_dwordx4 v[164:165], off
	s_barrier
	s_setprio 0
	s_waitcnt lgkmcnt(7)
	v_mfma_f32_16x16x32_bf16 v[62:65], v[144:147], v[160:163], v[62:65]
	v_mfma_f32_16x16x32_bf16 v[58:61], v[152:155], v[160:163], v[58:61]
	s_waitcnt lgkmcnt(5)
	v_mfma_f32_16x16x32_bf16 v[44:47], v[144:147], v[176:179], v[44:47]
	v_mfma_f32_16x16x32_bf16 v[40:43], v[152:155], v[176:179], v[40:43]
	s_waitcnt lgkmcnt(3)
	v_mfma_f32_16x16x32_bf16 v[28:31], v[144:147], v[184:187], v[28:31]
	v_mfma_f32_16x16x32_bf16 v[24:27], v[152:155], v[184:187], v[24:27]
	s_waitcnt lgkmcnt(1)
	v_mfma_f32_16x16x32_bf16 v[12:15], v[144:147], v[192:195], v[12:15]
	v_mfma_f32_16x16x32_bf16 v[8:11], v[152:155], v[192:195], v[8:11]
	v_mfma_f32_16x16x32_bf16 v[62:65], v[148:151], v[168:171], v[62:65]
	v_mfma_f32_16x16x32_bf16 v[58:61], v[156:159], v[168:171], v[58:61]
	v_mfma_f32_16x16x32_bf16 v[44:47], v[148:151], v[180:183], v[44:47]
	v_mfma_f32_16x16x32_bf16 v[40:43], v[156:159], v[180:183], v[40:43]
	v_mfma_f32_16x16x32_bf16 v[28:31], v[148:151], v[188:191], v[28:31]
	v_mfma_f32_16x16x32_bf16 v[24:27], v[156:159], v[188:191], v[24:27]
	s_waitcnt lgkmcnt(0)
	v_mfma_f32_16x16x32_bf16 v[12:15], v[148:151], v[196:199], v[12:15]
	v_mfma_f32_16x16x32_bf16 v[8:11], v[156:159], v[196:199], v[8:11]
	s_setprio 1
	s_barrier
	s_add_u32 s12, s12, 0x40080
	s_addc_u32 s13, s13, 0
	s_add_i32 s16, s16, s34
	v_lshl_add_u64 v[144:145], s[12:13], 0, v[134:135]
	s_mov_b32 m0, s16
	s_nop 0
	global_load_lds_dwordx4 v[144:145], off
	v_lshl_add_u64 v[144:145], s[12:13], 0, v[130:131]
	s_add_i32 m0, s16, 0x2000
	s_nop 0
	global_load_lds_dwordx4 v[144:145], off
	s_waitcnt vmcnt(6)
	s_barrier
	s_setprio 0
	v_mfma_f32_16x16x32_bf16 v[54:57], v[200:203], v[160:163], v[54:57]
	v_mfma_f32_16x16x32_bf16 v[50:53], v[208:211], v[160:163], v[50:53]
	v_mfma_f32_16x16x32_bf16 v[36:39], v[200:203], v[176:179], v[36:39]
	v_mfma_f32_16x16x32_bf16 v[32:35], v[208:211], v[176:179], v[32:35]
	v_mfma_f32_16x16x32_bf16 v[20:23], v[200:203], v[184:187], v[20:23]
	v_mfma_f32_16x16x32_bf16 v[16:19], v[208:211], v[184:187], v[16:19]
	v_mfma_f32_16x16x32_bf16 v[4:7], v[200:203], v[192:195], v[4:7]
	v_mfma_f32_16x16x32_bf16 v[0:3], v[208:211], v[192:195], v[0:3]
	v_mfma_f32_16x16x32_bf16 v[54:57], v[204:207], v[168:171], v[54:57]
	v_mfma_f32_16x16x32_bf16 v[50:53], v[212:215], v[168:171], v[50:53]
	v_mfma_f32_16x16x32_bf16 v[36:39], v[204:207], v[180:183], v[36:39]
	v_mfma_f32_16x16x32_bf16 v[32:35], v[212:215], v[180:183], v[32:35]
	v_mfma_f32_16x16x32_bf16 v[20:23], v[204:207], v[188:191], v[20:23]
	v_mfma_f32_16x16x32_bf16 v[16:19], v[212:215], v[188:191], v[16:19]
	v_mfma_f32_16x16x32_bf16 v[4:7], v[204:207], v[196:199], v[4:7]
	v_mfma_f32_16x16x32_bf16 v[0:3], v[212:215], v[196:199], v[0:3]
	s_setprio 1
	s_add_i32 s56, s56, 2
	s_add_u32 s6, s6, 0x100
	s_addc_u32 s7, s7, 0
	s_add_u32 s54, s54, 0x100
	s_addc_u32 s55, s55, 0
	s_cmp_gt_u32 s56, 13
	s_barrier
	s_cbranch_scc1 .Lkpeel_exit_335
; #define PG8_STAGE(bufoff, gbase, voff) do { _Pragma("unroll") for (int _i = 0; _i < 2; ++_i) \
;         __builtin_amdgcn_global_load_lds((const unsigned*)((const char*)(gbase) + (voff)[_i]), (PG8_LAS unsigned*)(lds + (bufoff) + ldsw + _i * 8192), 16, 0, 0); } while (0)
; #define PG8_LDA(dst, b, h) do { _Pragma("unroll") for (int m = 0; m < 4; ++m) _Pragma("unroll") for (int k = 0; k < 2; ++k) dst[m][k] = *(const PG8_LAS bf16x8*)(lds + PG8_SA(b, h) + aoff + m * 2048 + k * 1024); } while (0)
; #define PG8_LDB(dst, b, h) do { _Pragma("unroll") for (int n = 0; n < 2; ++n) _Pragma("unroll") for (int k = 0; k < 2; ++k) dst[n][k] = *(const PG8_LAS bf16x8*)(lds + PG8_SB(b, h) + boff + n * 2048 + k * 1024); } while (0)
; #define PG8_MMA(ai, bj, At, Bt) do { __builtin_amdgcn_s_setprio(1); _Pragma("unroll") for (int m = 0; m < 4; ++m) _Pragma("unroll") for (int n = 0; n < 2; ++n) _Pragma("unroll") for (int k = 0; k < 2; ++k) \
;         acc[ai][bj][m][n] = __builtin_amdgcn_mfma_f32_16x16x32_bf16(Bt[n][k], At[m][k], acc[ai][bj][m][n], 0, 0, 0); __builtin_amdgcn_s_setprio(0); } while (0)
; #define PG8_WAIT_L(n) asm volatile("s_waitcnt lgkmcnt(" #n ")" ::: "memory")
; #define PG8_BAR __builtin_amdgcn_s_barrier()
; #define PG8_SCHED __builtin_amdgcn_sched_barrier(0)
; template <class Epi, class Sched>
; __device__ __forceinline__ void gemm_phase(PG8_LAS unsigned char* lds, const Gemm g, const Sched& S, const Epi& E) {
;     ...
;             PG8_LDB(B0, 0, 0); PG8_SCHED; PG8_LDA(At, 0, 0); PG8_STAGE(PG8_SA(1, 1), a1 + hstep, voffA);
;             PG8_WAIT_L(8); PG8_BAR; PG8_WAIT_L(0); PG8_MMA(0, 0, At, B0); PG8_BAR; PG8_SCHED;
;             PG8_LDB(B1, 0, 1); PG8_STAGE(PG8_SB(0, 0), b2, voffB);
;             PG8_BAR; PG8_WAIT_L(0); PG8_MMA(0, 1, At, B1); PG8_BAR;
;             PG8_LDA(At, 0, 1); PG8_STAGE(PG8_SA(0, 0), a2, voffA);
;             PG8_BAR; PG8_WAIT_L(0); PG8_MMA(1, 0, At, B0); PG8_BAR; PG8_SCHED;
.LBB0_335:
	s_add_u32 s12, s6, 0xfffc0080
	s_addc_u32 s13, s7, -1
	s_add_i32 s57, 0, 0x10000
	v_add_u32_e32 v48, s57, v166
	ds_read_b128 v[144:147], v48
	ds_read_b128 v[148:151], v48 offset:1024
	ds_read_b128 v[152:155], v48 offset:2048
	ds_read_b128 v[156:159], v48 offset:3072
	s_cmp_eq_u32 s56, 12
	s_cselect_b32 s17, s23, s13
	s_cselect_b32 s16, s50, s12
	s_cselect_b32 s13, s21, s55
	s_cselect_b32 s12, s51, s54
	v_lshl_add_u64 v[164:165], s[6:7], 0, v[140:141]
	s_add_i32 m0, s3, 0xc000
	ds_read_b128 v[160:163], v167
	ds_read_b128 v[168:171], v167 offset:1024
	ds_read_b128 v[176:179], v167 offset:2048
	ds_read_b128 v[180:183], v167 offset:3072
	ds_read_b128 v[184:187], v167 offset:4096
	ds_read_b128 v[188:191], v167 offset:5120
	ds_read_b128 v[192:195], v167 offset:6144
	ds_read_b128 v[196:199], v167 offset:7168
	global_load_lds_dwordx4 v[164:165], off
	v_lshl_add_u64 v[164:165], s[6:7], 0, v[142:143]
	s_add_i32 m0, s3, 0xe000
	s_nop 0
	global_load_lds_dwordx4 v[164:165], off
	s_waitcnt lgkmcnt(8)
	s_barrier
	s_setprio 0
	s_waitcnt lgkmcnt(7)
	v_mfma_f32_16x16x32_bf16 v[126:129], v[144:147], v[160:163], v[126:129]
	v_mfma_f32_16x16x32_bf16 v[122:125], v[152:155], v[160:163], v[122:125]
	s_waitcnt lgkmcnt(5)
	v_mfma_f32_16x16x32_bf16 v[110:113], v[144:147], v[176:179], v[110:113]
	v_mfma_f32_16x16x32_bf16 v[106:109], v[152:155], v[176:179], v[106:109]
	s_waitcnt lgkmcnt(3)
	v_mfma_f32_16x16x32_bf16 v[94:97], v[144:147], v[184:187], v[94:97]
	v_mfma_f32_16x16x32_bf16 v[90:93], v[152:155], v[184:187], v[90:93]
	s_waitcnt lgkmcnt(1)
	v_mfma_f32_16x16x32_bf16 v[78:81], v[144:147], v[192:195], v[78:81]
	v_mfma_f32_16x16x32_bf16 v[74:77], v[152:155], v[192:195], v[74:77]
	v_mfma_f32_16x16x32_bf16 v[126:129], v[148:151], v[168:171], v[126:129]
	v_mfma_f32_16x16x32_bf16 v[122:125], v[156:159], v[168:171], v[122:125]
	v_mfma_f32_16x16x32_bf16 v[110:113], v[148:151], v[180:183], v[110:113]
	v_mfma_f32_16x16x32_bf16 v[106:109], v[156:159], v[180:183], v[106:109]
	v_mfma_f32_16x16x32_bf16 v[94:97], v[148:151], v[188:191], v[94:97]
	v_mfma_f32_16x16x32_bf16 v[90:93], v[156:159], v[188:191], v[90:93]
	s_waitcnt lgkmcnt(0)
	v_mfma_f32_16x16x32_bf16 v[78:81], v[148:151], v[196:199], v[78:81]
	v_mfma_f32_16x16x32_bf16 v[74:77], v[156:159], v[196:199], v[74:77]
	s_setprio 1
	s_barrier
	s_add_i32 s59, 0, 0x14000
	s_add_i32 s57, s57, s34
	v_add_u32_e32 v48, s59, v166
	v_lshl_add_u64 v[164:165], s[12:13], 0, v[134:135]
	s_mov_b32 m0, s57
	ds_read_b128 v[200:203], v48
	ds_read_b128 v[204:207], v48 offset:1024
	ds_read_b128 v[208:211], v48 offset:2048
	ds_read_b128 v[212:215], v48 offset:3072
	global_load_lds_dwordx4 v[164:165], off
	v_lshl_add_u64 v[172:173], s[12:13], 0, v[130:131]
	s_add_i32 m0, s57, 0x2000
	s_nop 0
	global_load_lds_dwordx4 v[172:173], off
	s_barrier
	s_setprio 0
	s_waitcnt lgkmcnt(3)
	v_mfma_f32_16x16x32_bf16 v[118:121], v[200:203], v[160:163], v[118:121]
	s_waitcnt lgkmcnt(1)
	v_mfma_f32_16x16x32_bf16 v[114:117], v[208:211], v[160:163], v[114:117]
	v_mfma_f32_16x16x32_bf16 v[102:105], v[200:203], v[176:179], v[102:105]
	v_mfma_f32_16x16x32_bf16 v[98:101], v[208:211], v[176:179], v[98:101]
	v_mfma_f32_16x16x32_bf16 v[86:89], v[200:203], v[184:187], v[86:89]
	v_mfma_f32_16x16x32_bf16 v[82:85], v[208:211], v[184:187], v[82:85]
	v_mfma_f32_16x16x32_bf16 v[70:73], v[200:203], v[192:195], v[70:73]
	v_mfma_f32_16x16x32_bf16 v[66:69], v[208:211], v[192:195], v[66:69]
	v_mfma_f32_16x16x32_bf16 v[118:121], v[204:207], v[168:171], v[118:121]
	s_waitcnt lgkmcnt(0)
	v_mfma_f32_16x16x32_bf16 v[114:117], v[212:215], v[168:171], v[114:117]
	v_mfma_f32_16x16x32_bf16 v[102:105], v[204:207], v[180:183], v[102:105]
	v_mfma_f32_16x16x32_bf16 v[98:101], v[212:215], v[180:183], v[98:101]
	v_mfma_f32_16x16x32_bf16 v[86:89], v[204:207], v[188:191], v[86:89]
	v_mfma_f32_16x16x32_bf16 v[82:85], v[212:215], v[188:191], v[82:85]
	v_mfma_f32_16x16x32_bf16 v[70:73], v[204:207], v[196:199], v[70:73]
	v_mfma_f32_16x16x32_bf16 v[66:69], v[212:215], v[196:199], v[66:69]
	s_setprio 1
	s_mov_b32 m0, s3
	v_lshl_add_u64 v[216:217], s[16:17], 0, v[136:137]
	s_barrier
	ds_read_b128 v[160:163], v167 offset:16384
	ds_read_b128 v[168:171], v167 offset:17408
	ds_read_b128 v[176:179], v167 offset:18432
	ds_read_b128 v[180:183], v167 offset:19456
	ds_read_b128 v[184:187], v167 offset:20480
	ds_read_b128 v[188:191], v167 offset:21504
	ds_read_b128 v[192:195], v167 offset:22528
	ds_read_b128 v[196:199], v167 offset:23552
	global_load_lds_dwordx4 v[216:217], off
	v_lshl_add_u64 v[218:219], s[16:17], 0, v[132:133]
	s_mov_b32 m0, s36
	s_nop 0
	global_load_lds_dwordx4 v[218:219], off
	s_barrier
	s_setprio 0
	s_waitcnt lgkmcnt(7)
	v_mfma_f32_16x16x32_bf16 v[62:65], v[144:147], v[160:163], v[62:65]
	v_mfma_f32_16x16x32_bf16 v[58:61], v[152:155], v[160:163], v[58:61]
	s_waitcnt lgkmcnt(5)
	v_mfma_f32_16x16x32_bf16 v[44:47], v[144:147], v[176:179], v[44:47]
	v_mfma_f32_16x16x32_bf16 v[40:43], v[152:155], v[176:179], v[40:43]
	s_waitcnt lgkmcnt(3)
	v_mfma_f32_16x16x32_bf16 v[28:31], v[144:147], v[184:187], v[28:31]
	v_mfma_f32_16x16x32_bf16 v[24:27], v[152:155], v[184:187], v[24:27]
	s_waitcnt lgkmcnt(1)
	v_mfma_f32_16x16x32_bf16 v[12:15], v[144:147], v[192:195], v[12:15]
	v_mfma_f32_16x16x32_bf16 v[8:11], v[152:155], v[192:195], v[8:11]
	v_mfma_f32_16x16x32_bf16 v[62:65], v[148:151], v[168:171], v[62:65]
	v_mfma_f32_16x16x32_bf16 v[58:61], v[156:159], v[168:171], v[58:61]
	v_mfma_f32_16x16x32_bf16 v[44:47], v[148:151], v[180:183], v[44:47]
	v_mfma_f32_16x16x32_bf16 v[40:43], v[156:159], v[180:183], v[40:43]
	v_mfma_f32_16x16x32_bf16 v[28:31], v[148:151], v[188:191], v[28:31]
	v_mfma_f32_16x16x32_bf16 v[24:27], v[156:159], v[188:191], v[24:27]
	s_waitcnt lgkmcnt(0)
	v_mfma_f32_16x16x32_bf16 v[12:15], v[148:151], v[196:199], v[12:15]
	v_mfma_f32_16x16x32_bf16 v[8:11], v[156:159], v[196:199], v[8:11]
	s_setprio 1
	s_barrier
; #define PG8_STAGE(bufoff, gbase, voff) do { _Pragma("unroll") for (int _i = 0; _i < 2; ++_i) \
;         __builtin_amdgcn_global_load_lds((const unsigned*)((const char*)(gbase) + (voff)[_i]), (PG8_LAS unsigned*)(lds + (bufoff) + ldsw + _i * 8192), 16, 0, 0); } while (0)
; #define PG8_LDA(dst, b, h) do { _Pragma("unroll") for (int m = 0; m < 4; ++m) _Pragma("unroll") for (int k = 0; k < 2; ++k) dst[m][k] = *(const PG8_LAS bf16x8*)(lds + PG8_SA(b, h) + aoff + m * 2048 + k * 1024); } while (0)
; #define PG8_LDB(dst, b, h) do { _Pragma("unroll") for (int n = 0; n < 2; ++n) _Pragma("unroll") for (int k = 0; k < 2; ++k) dst[n][k] = *(const PG8_LAS bf16x8*)(lds + PG8_SB(b, h) + boff + n * 2048 + k * 1024); } while (0)
; #define PG8_MMA(ai, bj, At, Bt) do { __builtin_amdgcn_s_setprio(1); _Pragma("unroll") for (int m = 0; m < 4; ++m) _Pragma("unroll") for (int n = 0; n < 2; ++n) _Pragma("unroll") for (int k = 0; k < 2; ++k) \
;         acc[ai][bj][m][n] = __builtin_amdgcn_mfma_f32_16x16x32_bf16(Bt[n][k], At[m][k], acc[ai][bj][m][n], 0, 0, 0); __builtin_amdgcn_s_setprio(0); } while (0)
; #define PG8_WAIT_V(n) asm volatile("s_waitcnt vmcnt(" #n ")" ::: "memory")
; #define PG8_WAIT_L(n) asm volatile("s_waitcnt lgkmcnt(" #n ")" ::: "memory")
; #define PG8_BAR __builtin_amdgcn_s_barrier()
; #define PG8_SCHED __builtin_amdgcn_sched_barrier(0)
; template <class Epi, class Sched>
; __device__ __forceinline__ void gemm_phase(PG8_LAS unsigned char* lds, const Gemm g, const Sched& S, const Epi& E) {
;     ...
;             PG8_STAGE(PG8_SB(0, 1), b2 + hstep, voffB);
;             PG8_WAIT_V(6); PG8_BAR; PG8_MMA(1, 1, At, B1); PG8_BAR;
;             PG8_LDB(B0, 1, 0); PG8_SCHED; PG8_LDA(At, 1, 0); PG8_STAGE(PG8_SA(0, 1), a2 + hstep, voffA);
;             PG8_WAIT_L(8); PG8_BAR; PG8_WAIT_L(0); PG8_MMA(0, 0, At, B0); PG8_BAR; PG8_SCHED;
;             PG8_LDB(B1, 1, 1); PG8_STAGE(PG8_SB(1, 0), b3, voffB);
;             PG8_BAR; PG8_WAIT_L(0); PG8_MMA(0, 1, At, B1); PG8_BAR;
	s_add_u32 s64, s12, 0x40000
	s_addc_u32 s65, s13, 0
	s_add_i32 s57, s59, s34
	v_lshl_add_u64 v[144:145], s[64:65], 0, v[134:135]
	s_mov_b32 m0, s57
	s_nop 0
	global_load_lds_dwordx4 v[144:145], off
	v_lshl_add_u64 v[144:145], s[64:65], 0, v[130:131]
	s_add_i32 m0, s57, 0x2000
	s_nop 0
	global_load_lds_dwordx4 v[144:145], off
	s_waitcnt vmcnt(6)
	s_barrier
	s_setprio 0
	v_mfma_f32_16x16x32_bf16 v[54:57], v[200:203], v[160:163], v[54:57]
	v_mfma_f32_16x16x32_bf16 v[50:53], v[208:211], v[160:163], v[50:53]
	v_mfma_f32_16x16x32_bf16 v[36:39], v[200:203], v[176:179], v[36:39]
	v_mfma_f32_16x16x32_bf16 v[32:35], v[208:211], v[176:179], v[32:35]
	v_mfma_f32_16x16x32_bf16 v[20:23], v[200:203], v[184:187], v[20:23]
	v_mfma_f32_16x16x32_bf16 v[16:19], v[208:211], v[184:187], v[16:19]
	v_mfma_f32_16x16x32_bf16 v[4:7], v[200:203], v[192:195], v[4:7]
	v_mfma_f32_16x16x32_bf16 v[0:3], v[208:211], v[192:195], v[0:3]
	v_mfma_f32_16x16x32_bf16 v[54:57], v[204:207], v[168:171], v[54:57]
	v_mfma_f32_16x16x32_bf16 v[50:53], v[212:215], v[168:171], v[50:53]
	v_mfma_f32_16x16x32_bf16 v[36:39], v[204:207], v[180:183], v[36:39]
	v_mfma_f32_16x16x32_bf16 v[32:35], v[212:215], v[180:183], v[32:35]
	v_mfma_f32_16x16x32_bf16 v[20:23], v[204:207], v[188:191], v[20:23]
	v_mfma_f32_16x16x32_bf16 v[16:19], v[212:215], v[188:191], v[16:19]
	v_mfma_f32_16x16x32_bf16 v[4:7], v[204:207], v[196:199], v[4:7]
	v_mfma_f32_16x16x32_bf16 v[0:3], v[212:215], v[196:199], v[0:3]
	s_setprio 1
	s_add_i32 s57, 0, 0x18000
	v_add_u32_e32 v48, s57, v166
	s_barrier
	ds_read_b128 v[144:147], v48
	ds_read_b128 v[148:151], v48 offset:1024
	ds_read_b128 v[152:155], v48 offset:2048
	ds_read_b128 v[156:159], v48 offset:3072
	s_add_u32 s16, s16, 0x40000
	s_addc_u32 s17, s17, 0
	s_mov_b32 m0, s37
	v_lshl_add_u64 v[200:201], s[16:17], 0, v[136:137]
	ds_read_b128 v[160:163], v167 offset:32768
	ds_read_b128 v[168:171], v167 offset:33792
	ds_read_b128 v[176:179], v167 offset:34816
	ds_read_b128 v[180:183], v167 offset:35840
	ds_read_b128 v[184:187], v167 offset:36864
	ds_read_b128 v[188:191], v167 offset:37888
	ds_read_b128 v[192:195], v167 offset:38912
	ds_read_b128 v[196:199], v167 offset:39936
	global_load_lds_dwordx4 v[200:201], off
	v_lshl_add_u64 v[200:201], s[16:17], 0, v[132:133]
	s_mov_b32 m0, s38
	s_nop 0
	global_load_lds_dwordx4 v[200:201], off
	s_waitcnt lgkmcnt(8)
	s_barrier
	s_setprio 0
	s_waitcnt lgkmcnt(7)
	v_mfma_f32_16x16x32_bf16 v[126:129], v[144:147], v[160:163], v[126:129]
	v_mfma_f32_16x16x32_bf16 v[122:125], v[152:155], v[160:163], v[122:125]
	s_waitcnt lgkmcnt(5)
	v_mfma_f32_16x16x32_bf16 v[110:113], v[144:147], v[176:179], v[110:113]
	v_mfma_f32_16x16x32_bf16 v[106:109], v[152:155], v[176:179], v[106:109]
	s_waitcnt lgkmcnt(3)
	v_mfma_f32_16x16x32_bf16 v[94:97], v[144:147], v[184:187], v[94:97]
	v_mfma_f32_16x16x32_bf16 v[90:93], v[152:155], v[184:187], v[90:93]
	s_waitcnt lgkmcnt(1)
	v_mfma_f32_16x16x32_bf16 v[78:81], v[144:147], v[192:195], v[78:81]
	v_mfma_f32_16x16x32_bf16 v[74:77], v[152:155], v[192:195], v[74:77]
	v_mfma_f32_16x16x32_bf16 v[126:129], v[148:151], v[168:171], v[126:129]
	v_mfma_f32_16x16x32_bf16 v[122:125], v[156:159], v[168:171], v[122:125]
	v_mfma_f32_16x16x32_bf16 v[110:113], v[148:151], v[180:183], v[110:113]
	v_mfma_f32_16x16x32_bf16 v[106:109], v[156:159], v[180:183], v[106:109]
	v_mfma_f32_16x16x32_bf16 v[94:97], v[148:151], v[188:191], v[94:97]
	v_mfma_f32_16x16x32_bf16 v[90:93], v[156:159], v[188:191], v[90:93]
	s_waitcnt lgkmcnt(0)
	v_mfma_f32_16x16x32_bf16 v[78:81], v[148:151], v[196:199], v[78:81]
	v_mfma_f32_16x16x32_bf16 v[74:77], v[156:159], v[196:199], v[74:77]
	s_setprio 1
	s_barrier
	s_add_i32 s16, 0, 0x1c000
	s_add_i32 s17, s57, s34
	v_add_u32_e32 v48, s16, v166
	v_lshl_add_u64 v[164:165], v[164:165], 0, s[0:1]
	s_mov_b32 m0, s17
	ds_read_b128 v[200:203], v48
	ds_read_b128 v[204:207], v48 offset:1024
	ds_read_b128 v[208:211], v48 offset:2048
	ds_read_b128 v[212:215], v48 offset:3072
	global_load_lds_dwordx4 v[164:165], off
	v_lshl_add_u64 v[164:165], v[172:173], 0, s[0:1]
	s_add_i32 m0, s17, 0x2000
	s_nop 0
	global_load_lds_dwordx4 v[164:165], off
	s_barrier
	s_setprio 0
	s_waitcnt lgkmcnt(3)
	v_mfma_f32_16x16x32_bf16 v[118:121], v[200:203], v[160:163], v[118:121]
	s_waitcnt lgkmcnt(1)
	v_mfma_f32_16x16x32_bf16 v[114:117], v[208:211], v[160:163], v[114:117]
	v_mfma_f32_16x16x32_bf16 v[102:105], v[200:203], v[176:179], v[102:105]
	v_mfma_f32_16x16x32_bf16 v[98:101], v[208:211], v[176:179], v[98:101]
	v_mfma_f32_16x16x32_bf16 v[86:89], v[200:203], v[184:187], v[86:89]
	v_mfma_f32_16x16x32_bf16 v[82:85], v[208:211], v[184:187], v[82:85]
	v_mfma_f32_16x16x32_bf16 v[70:73], v[200:203], v[192:195], v[70:73]
	v_mfma_f32_16x16x32_bf16 v[66:69], v[208:211], v[192:195], v[66:69]
	v_mfma_f32_16x16x32_bf16 v[118:121], v[204:207], v[168:171], v[118:121]
	s_waitcnt lgkmcnt(0)
	v_mfma_f32_16x16x32_bf16 v[114:117], v[212:215], v[168:171], v[114:117]
	v_mfma_f32_16x16x32_bf16 v[102:105], v[204:207], v[180:183], v[102:105]
	v_mfma_f32_16x16x32_bf16 v[98:101], v[212:215], v[180:183], v[98:101]
	v_mfma_f32_16x16x32_bf16 v[86:89], v[204:207], v[188:191], v[86:89]
	v_mfma_f32_16x16x32_bf16 v[82:85], v[212:215], v[188:191], v[82:85]
	v_mfma_f32_16x16x32_bf16 v[70:73], v[204:207], v[196:199], v[70:73]
	v_mfma_f32_16x16x32_bf16 v[66:69], v[212:215], v[196:199], v[66:69]
	s_setprio 1
	s_mov_b32 m0, s39
	v_lshl_add_u64 v[164:165], v[216:217], 0, s[0:1]
	s_barrier
; #define PG8_STAGE(bufoff, gbase, voff) do { _Pragma("unroll") for (int _i = 0; _i < 2; ++_i) \
;         __builtin_amdgcn_global_load_lds((const unsigned*)((const char*)(gbase) + (voff)[_i]), (PG8_LAS unsigned*)(lds + (bufoff) + ldsw + _i * 8192), 16, 0, 0); } while (0)
; #define PG8_LDA(dst, b, h) do { _Pragma("unroll") for (int m = 0; m < 4; ++m) _Pragma("unroll") for (int k = 0; k < 2; ++k) dst[m][k] = *(const PG8_LAS bf16x8*)(lds + PG8_SA(b, h) + aoff + m * 2048 + k * 1024); } while (0)
; #define PG8_WAIT_V(n) asm volatile("s_waitcnt vmcnt(" #n ")" ::: "memory")
; #define PG8_WAIT_L(n) asm volatile("s_waitcnt lgkmcnt(" #n ")" ::: "memory")
; #define PG8_BAR __builtin_amdgcn_s_barrier()
; #define PG8_SCHED __builtin_amdgcn_sched_barrier(0)
; template <class Epi, class Sched>
; __device__ __forceinline__ void gemm_phase(PG8_LAS unsigned char* lds, const Gemm g, const Sched& S, const Epi& E) {
;     ...
;             PG8_LDA(At, 1, 1); PG8_STAGE(PG8_SA(1, 0), a3, voffA);
;             PG8_BAR; PG8_WAIT_L(0); PG8_MMA(1, 0, At, B0); PG8_BAR; PG8_SCHED;
;             PG8_STAGE(PG8_SB(1, 1), b3 + hstep, voffB);
;             PG8_WAIT_V(6); PG8_BAR; PG8_MMA(1, 1, At, B1); PG8_BAR;
;     __device__ __forceinline__ void operator()(const f32x4 (&acc)[2][2][4][2], const pg8::Unit& u, int wr, int wc, int fr, int fq) const {
;         const int row0 = u.pm * 256 + wr * 64 + fr; const bool isk = u.pn >= 4;
;         bf16_t* base = (isk ? K : Q) + (u.pn & 3) * 256 + 64 * wc + 8 * fq;
;         const float* g = isk ? kg : qg; const float sc = isk ? 1.0f : 0.125f * 1.4426950408889634f;
;         f32x4 gv[2][2];
; #pragma unroll
;         for (int bj = 0; bj < 2; ++bj)
; #pragma unroll
;             for (int n = 0; n < 2; ++n) gv[bj][n] = *(const f32x4*)(g + 32 * bj + 8 * fq + 4 * n) * sc;
; #pragma unroll
;         for (int ai = 0; ai < 2; ++ai)
; #pragma unroll
;             for (int m = 0; m < 4; ++m) {
;                 float ss = 0.f;
; #pragma unroll
;                 for (int bj = 0; bj < 2; ++bj)
; #pragma unroll
;                     for (int n = 0; n < 2; ++n) { const f32x4 x = acc[ai][bj][m][n]; ss += (x[0] * x[0] + x[1] * x[1]) + (x[2] * x[2] + x[3] * x[3]); }
;                 ss += __shfl_xor(ss, 16); ss += __shfl_xor(ss, 32);
;                 const float rs = __builtin_amdgcn_rsqf(ss * (1.0f / 64.0f) + EPSN);
	ds_read_b128 v[160:163], v167 offset:49152
	ds_read_b128 v[168:171], v167 offset:50176
	ds_read_b128 v[176:179], v167 offset:51200
	ds_read_b128 v[180:183], v167 offset:52224
	ds_read_b128 v[184:187], v167 offset:53248
	ds_read_b128 v[188:191], v167 offset:54272
	ds_read_b128 v[192:195], v167 offset:55296
	ds_read_b128 v[196:199], v167 offset:56320
	global_load_lds_dwordx4 v[164:165], off
	v_lshl_add_u64 v[164:165], v[218:219], 0, s[0:1]
	s_mov_b32 m0, s42
	s_nop 0
	global_load_lds_dwordx4 v[164:165], off
	s_barrier
	s_setprio 0
	s_waitcnt lgkmcnt(7)
	v_mfma_f32_16x16x32_bf16 v[62:65], v[144:147], v[160:163], v[62:65]
	v_mfma_f32_16x16x32_bf16 v[58:61], v[152:155], v[160:163], v[58:61]
	s_waitcnt lgkmcnt(5)
	v_mfma_f32_16x16x32_bf16 v[44:47], v[144:147], v[176:179], v[44:47]
	v_mfma_f32_16x16x32_bf16 v[40:43], v[152:155], v[176:179], v[40:43]
	s_waitcnt lgkmcnt(3)
	v_mfma_f32_16x16x32_bf16 v[28:31], v[144:147], v[184:187], v[28:31]
	v_mfma_f32_16x16x32_bf16 v[24:27], v[152:155], v[184:187], v[24:27]
	s_waitcnt lgkmcnt(1)
	v_mfma_f32_16x16x32_bf16 v[12:15], v[144:147], v[192:195], v[12:15]
	v_mfma_f32_16x16x32_bf16 v[8:11], v[152:155], v[192:195], v[8:11]
	v_mfma_f32_16x16x32_bf16 v[62:65], v[148:151], v[168:171], v[62:65]
	v_mfma_f32_16x16x32_bf16 v[58:61], v[156:159], v[168:171], v[58:61]
	v_mfma_f32_16x16x32_bf16 v[44:47], v[148:151], v[180:183], v[44:47]
	v_mfma_f32_16x16x32_bf16 v[40:43], v[156:159], v[180:183], v[40:43]
	v_mfma_f32_16x16x32_bf16 v[28:31], v[148:151], v[188:191], v[28:31]
	v_mfma_f32_16x16x32_bf16 v[24:27], v[156:159], v[188:191], v[24:27]
	s_waitcnt lgkmcnt(0)
	v_mfma_f32_16x16x32_bf16 v[12:15], v[148:151], v[196:199], v[12:15]
	v_mfma_f32_16x16x32_bf16 v[8:11], v[156:159], v[196:199], v[8:11]
	s_setprio 1
	s_barrier
	s_add_u32 s12, s12, 0x40080
	s_addc_u32 s13, s13, 0
	s_add_i32 s16, s16, s34
	v_lshl_add_u64 v[144:145], s[12:13], 0, v[134:135]
	s_mov_b32 m0, s16
	s_nop 0
	global_load_lds_dwordx4 v[144:145], off
	v_lshl_add_u64 v[144:145], s[12:13], 0, v[130:131]
	s_add_i32 m0, s16, 0x2000
	s_nop 0
	global_load_lds_dwordx4 v[144:145], off
	s_waitcnt vmcnt(6)
	s_barrier
	s_setprio 0
	v_mfma_f32_16x16x32_bf16 v[54:57], v[200:203], v[160:163], v[54:57]
	v_mfma_f32_16x16x32_bf16 v[50:53], v[208:211], v[160:163], v[50:53]
	v_mfma_f32_16x16x32_bf16 v[36:39], v[200:203], v[176:179], v[36:39]
	v_mfma_f32_16x16x32_bf16 v[32:35], v[208:211], v[176:179], v[32:35]
	v_mfma_f32_16x16x32_bf16 v[20:23], v[200:203], v[184:187], v[20:23]
	v_mfma_f32_16x16x32_bf16 v[16:19], v[208:211], v[184:187], v[16:19]
	v_mfma_f32_16x16x32_bf16 v[4:7], v[200:203], v[192:195], v[4:7]
	v_mfma_f32_16x16x32_bf16 v[0:3], v[208:211], v[192:195], v[0:3]
	v_mfma_f32_16x16x32_bf16 v[54:57], v[204:207], v[168:171], v[54:57]
	v_mfma_f32_16x16x32_bf16 v[50:53], v[212:215], v[168:171], v[50:53]
	v_mfma_f32_16x16x32_bf16 v[36:39], v[204:207], v[180:183], v[36:39]
	v_mfma_f32_16x16x32_bf16 v[32:35], v[212:215], v[180:183], v[32:35]
	v_mfma_f32_16x16x32_bf16 v[20:23], v[204:207], v[188:191], v[20:23]
	v_mfma_f32_16x16x32_bf16 v[16:19], v[212:215], v[188:191], v[16:19]
	v_mfma_f32_16x16x32_bf16 v[4:7], v[204:207], v[196:199], v[4:7]
	v_mfma_f32_16x16x32_bf16 v[0:3], v[212:215], v[196:199], v[0:3]
	s_setprio 1
	s_add_i32 s56, s56, 2
	s_add_u32 s6, s6, 0x100
	s_addc_u32 s7, s7, 0
	s_add_u32 s54, s54, 0x100
	s_addc_u32 s55, s55, 0
	s_cmp_gt_u32 s56, 13
	s_barrier
	s_cbranch_scc0 .LBB0_335
.Lkpeel_exit_335:
	s_setprio 0
	s_cmp_gt_i32 s49, 3
	s_cselect_b64 s[6:7], -1, 0
	s_and_b64 s[12:13], s[6:7], exec
	s_mov_b32 s12, 0xfe00000
	s_cselect_b32 s12, s12, 0xba00000
	v_mov_b32_e32 v48, 0x3e38aa3b
	v_cndmask_b32_e64 v48, v48, 1.0, s[6:7]
	s_cselect_b32 s6, s46, s44
	s_cselect_b32 s7, s47, s45
	s_add_u32 s12, s8, s12
	s_addc_u32 s13, s9, 0
	s_add_u32 s6, s6, s10
	s_addc_u32 s7, s7, s11
	v_lshlrev_b32_e32 v156, 2, v138
	global_load_dwordx4 v[152:155], v156, s[6:7] offset:16
	global_load_dwordx4 v[144:147], v156, s[6:7]
	v_pk_mul_f32 v[170:171], v[126:127], v[126:127]
	v_mul_f32_e32 v169, v115, v115
	v_mul_f32_e32 v175, v117, v117
	s_waitcnt vmcnt(0)
	v_pk_mul_f32 v[148:149], v[48:49], v[146:147] op_sel_hi:[0,1]
	v_pk_mul_f32 v[150:151], v[48:49], v[144:145] op_sel_hi:[0,1]
	v_pk_mul_f32 v[144:145], v[48:49], v[154:155] op_sel_hi:[0,1]
	v_pk_mul_f32 v[146:147], v[48:49], v[152:153] op_sel_hi:[0,1]
	global_load_dwordx4 v[160:163], v156, s[6:7] offset:144
	global_load_dwordx4 v[152:155], v156, s[6:7] offset:128
	s_waitcnt vmcnt(0)
	v_pk_mul_f32 v[156:157], v[48:49], v[154:155] op_sel_hi:[0,1]
	v_pk_mul_f32 v[154:155], v[48:49], v[160:161] op_sel_hi:[0,1]
	v_pk_mul_f32 v[160:161], v[128:129], v[128:129]
	v_pk_mul_f32 v[158:159], v[48:49], v[152:153] op_sel_hi:[0,1]
	v_pk_mov_b32 v[172:173], v[170:171], v[160:161] op_sel:[1,0]
	v_mov_b32_e32 v171, v161
	v_pk_add_f32 v[160:161], v[172:173], v[170:171]
	v_pk_mul_f32 v[170:171], v[124:125], v[124:125]
	v_pk_mul_f32 v[172:173], v[122:123], v[122:123]
	v_pk_mul_f32 v[152:153], v[48:49], v[162:163] op_sel_hi:[0,1]
	v_pk_mov_b32 v[176:177], v[172:173], v[170:171] op_sel:[1,0]
	v_mov_b32_e32 v173, v171
	v_pk_add_f32 v[170:171], v[176:177], v[172:173]
	v_lshl_add_u32 v162, s2, 8, v139
	s_lshl_b32 s2, s49, 9
	v_mul_f32_e32 v163, v114, v114
	v_pk_add_f32 v[160:161], v[160:161], v[160:161] op_sel:[0,1] op_sel_hi:[1,0]
	v_pk_add_f32 v[170:171], v[170:171], v[170:171] op_sel:[0,1] op_sel_hi:[1,0]
	s_and_b32 s2, s2, 0x600
	v_mov_b32_e32 v161, v163
	v_mov_b32_e32 v171, v169
	s_add_u32 s2, s12, s2
	v_pk_add_f32 v[160:161], v[160:161], v[170:171]
	v_mul_f32_e32 v170, v119, v119
	s_addc_u32 s7, s13, 0
	v_mul_f32_e32 v172, v116, v116
	v_pk_fma_f32 v[170:171], v[118:119], v[118:119], v[170:171] op_sel_hi:[1,1,0]
	s_add_u32 s6, s2, s48
	v_mov_b32_e32 v171, v172
	v_mul_f32_e32 v172, v121, v121
	s_addc_u32 s7, s7, 0
	v_lshlrev_b32_e32 v48, 1, v138
	v_pk_fma_f32 v[172:173], v[120:121], v[120:121], v[172:173] op_sel_hi:[1,1,0]
	v_lshl_add_u64 v[164:165], s[6:7], 0, v[48:49]
	v_xor_b32_e32 v48, 16, v222
	v_mov_b32_e32 v173, v175
	v_cmp_lt_i32_e32 vcc, v48, v227
	v_pk_add_f32 v[170:171], v[170:171], v[172:173]
	v_ashrrev_i32_e32 v163, 31, v162
	v_cndmask_b32_e32 v48, v222, v48, vcc
	v_pk_add_f32 v[160:161], v[160:161], v[170:171]
	v_lshlrev_b32_e32 v168, 2, v48
	v_add_f32_e32 v160, v160, v161
	ds_bpermute_b32 v161, v168, v160
	v_cmp_lt_i32_e32 vcc, v226, v227
	s_mov_b32 s2, 0x40000
	s_mov_b64 s[6:7], 0x40000
	v_cndmask_b32_e32 v48, v222, v226, vcc
	v_lshlrev_b32_e32 v48, 2, v48
	s_waitcnt lgkmcnt(0)
; __device__ __forceinline__ unsigned cvt_pk_bf16(float lo, float hi) { unsigned r; asm volatile("v_cvt_pk_bf16_f32 %0, %1, %2" : "=v"(r) : "v"(lo), "v"(hi)); return r; }
;     __device__ __forceinline__ void operator()(const f32x4 (&acc)[2][2][4][2], const pg8::Unit& u, int wr, int wc, int fr, int fq) const {
;     ...
;             for (int m = 0; m < 4; ++m) {
;                 float ss = 0.f;
; #pragma unroll
;                 for (int bj = 0; bj < 2; ++bj)
; #pragma unroll
;                     for (int n = 0; n < 2; ++n) { const f32x4 x = acc[ai][bj][m][n]; ss += (x[0] * x[0] + x[1] * x[1]) + (x[2] * x[2] + x[3] * x[3]); }
;                 ss += __shfl_xor(ss, 16); ss += __shfl_xor(ss, 32);
;                 const float rs = __builtin_amdgcn_rsqf(ss * (1.0f / 64.0f) + EPSN);
;                 bf16_t* rowp = base + (size_t)(row0 + ai * 128 + m * 16) * DM;
; #pragma unroll
;                 for (int bj = 0; bj < 2; ++bj) { const f32x4 v0 = acc[ai][bj][m][0] * rs * gv[bj][0], v1 = acc[ai][bj][m][1] * rs * gv[bj][1];
;                     u32x4 w; w.x = pg8::cvt_pk_bf16(v0[0], v0[1]); w.y = pg8::cvt_pk_bf16(v0[2], v0[3]); w.z = pg8::cvt_pk_bf16(v1[0], v1[1]); w.w = pg8::cvt_pk_bf16(v1[2], v1[3]);
;                     *(u32x4*)(rowp + 32 * bj) = w; }
	v_add_f32_e32 v160, v160, v161
	ds_bpermute_b32 v161, v48, v160
	s_mov_b32 s49, s20
	s_mov_b64 s[12:13], s[26:27]
	s_waitcnt lgkmcnt(0)
	v_add_f32_e32 v160, v160, v161
	v_fmamk_f32 v160, v160, 0x3c800000, v223
	v_rsq_f32_e32 v170, v160
	v_lshlrev_b64 v[160:161], 11, v[162:163]
	v_lshl_add_u64 v[160:161], v[164:165], 0, v[160:161]
	v_pk_mul_f32 v[126:127], v[126:127], v[170:171] op_sel_hi:[1,0]
	v_pk_mul_f32 v[128:129], v[128:129], v[170:171] op_sel_hi:[1,0]
	v_pk_mul_f32 v[122:123], v[122:123], v[170:171] op_sel_hi:[1,0]
	v_pk_mul_f32 v[124:125], v[124:125], v[170:171] op_sel_hi:[1,0]
	v_pk_mul_f32 v[128:129], v[148:149], v[128:129]
	v_pk_mul_f32 v[126:127], v[150:151], v[126:127]
	v_pk_mul_f32 v[172:173], v[144:145], v[124:125]
	v_pk_mul_f32 v[124:125], v[146:147], v[122:123]
	v_cvt_pk_bf16_f32 v122, v126, v127
	v_cvt_pk_bf16_f32 v123, v128, v129
	v_pk_mul_f32 v[114:115], v[114:115], v[170:171] op_sel_hi:[1,0]
	v_pk_mul_f32 v[116:117], v[116:117], v[170:171] op_sel_hi:[1,0]
	v_cvt_pk_bf16_f32 v124, v124, v125
	v_cvt_pk_bf16_f32 v125, v172, v173
	global_store_dwordx4 v[160:161], v[122:125], off
	v_pk_mul_f32 v[118:119], v[118:119], v[170:171] op_sel_hi:[1,0]
	v_pk_mul_f32 v[120:121], v[120:121], v[170:171] op_sel_hi:[1,0]
	v_pk_mul_f32 v[122:123], v[152:153], v[116:117]
	v_pk_mul_f32 v[116:117], v[154:155], v[114:115]
	v_pk_mul_f32 v[120:121], v[156:157], v[120:121]
	v_pk_mul_f32 v[118:119], v[158:159], v[118:119]
	s_nop 0
	v_cvt_pk_bf16_f32 v114, v118, v119
	v_cvt_pk_bf16_f32 v115, v120, v121
	v_cvt_pk_bf16_f32 v116, v116, v117
	v_cvt_pk_bf16_f32 v117, v122, v123
	global_store_dwordx4 v[160:161], v[114:117], off offset:64
	s_nop 1
	v_pk_mul_f32 v[114:115], v[112:113], v[112:113]
	v_pk_mul_f32 v[116:117], v[110:111], v[110:111]
	s_nop 0
	v_pk_mov_b32 v[118:119], v[116:117], v[114:115] op_sel:[1,0]
	v_mov_b32_e32 v117, v115
	v_pk_add_f32 v[114:115], v[118:119], v[116:117]
	v_pk_mul_f32 v[116:117], v[108:109], v[108:109]
	v_pk_mul_f32 v[118:119], v[106:107], v[106:107]
	v_pk_add_f32 v[114:115], v[114:115], v[114:115] op_sel:[0,1] op_sel_hi:[1,0]
	v_pk_mov_b32 v[120:121], v[118:119], v[116:117] op_sel:[1,0]
	v_mov_b32_e32 v119, v117
	v_pk_add_f32 v[116:117], v[120:121], v[118:119]
	v_mul_f32_e32 v118, v98, v98
	v_mul_f32_e32 v119, v99, v99
	v_pk_add_f32 v[116:117], v[116:117], v[116:117] op_sel:[0,1] op_sel_hi:[1,0]
	v_mov_b32_e32 v115, v118
	v_mov_b32_e32 v117, v119
	v_pk_add_f32 v[114:115], v[114:115], v[116:117]
	v_mul_f32_e32 v116, v103, v103
	v_mul_f32_e32 v118, v105, v105
	v_mul_f32_e32 v120, v100, v100
	v_mul_f32_e32 v121, v101, v101
	v_pk_fma_f32 v[116:117], v[102:103], v[102:103], v[116:117] op_sel_hi:[1,1,0]
	v_pk_fma_f32 v[118:119], v[104:105], v[104:105], v[118:119] op_sel_hi:[1,1,0]
	v_mov_b32_e32 v117, v120
	v_mov_b32_e32 v119, v121
	v_pk_add_f32 v[116:117], v[116:117], v[118:119]
	s_nop 0
	v_pk_add_f32 v[114:115], v[114:115], v[116:117]
	v_or_b32_e32 v116, 16, v162
	v_add_f32_e32 v114, v114, v115
	ds_bpermute_b32 v115, v168, v114
	v_ashrrev_i32_e32 v117, 31, v116
	v_lshlrev_b64 v[116:117], 11, v[116:117]
	v_lshl_add_u64 v[116:117], v[164:165], 0, v[116:117]
	s_waitcnt lgkmcnt(0)
	v_add_f32_e32 v114, v114, v115
	ds_bpermute_b32 v115, v48, v114
	s_waitcnt lgkmcnt(0)
	v_add_f32_e32 v114, v114, v115
	v_fmamk_f32 v114, v114, 0x3c800000, v223
	v_rsq_f32_e32 v114, v114
	s_nop 0
	v_pk_mul_f32 v[110:111], v[110:111], v[114:115] op_sel_hi:[1,0]
	v_pk_mul_f32 v[112:113], v[112:113], v[114:115] op_sel_hi:[1,0]
	v_pk_mul_f32 v[106:107], v[106:107], v[114:115] op_sel_hi:[1,0]
	v_pk_mul_f32 v[108:109], v[108:109], v[114:115] op_sel_hi:[1,0]
	v_pk_mul_f32 v[112:113], v[148:149], v[112:113]
	v_pk_mul_f32 v[110:111], v[150:151], v[110:111]
	v_pk_mul_f32 v[118:119], v[144:145], v[108:109]
	v_pk_mul_f32 v[108:109], v[146:147], v[106:107]
	v_cvt_pk_bf16_f32 v106, v110, v111
	v_cvt_pk_bf16_f32 v107, v112, v113
	v_pk_mul_f32 v[98:99], v[98:99], v[114:115] op_sel_hi:[1,0]
	v_pk_mul_f32 v[100:101], v[100:101], v[114:115] op_sel_hi:[1,0]
	v_cvt_pk_bf16_f32 v108, v108, v109
	v_cvt_pk_bf16_f32 v109, v118, v119
	global_store_dwordx4 v[116:117], v[106:109], off
	v_pk_mul_f32 v[102:103], v[102:103], v[114:115] op_sel_hi:[1,0]
	v_pk_mul_f32 v[104:105], v[104:105], v[114:115] op_sel_hi:[1,0]
	v_pk_mul_f32 v[106:107], v[152:153], v[100:101]
	v_pk_mul_f32 v[100:101], v[154:155], v[98:99]
	v_pk_mul_f32 v[104:105], v[156:157], v[104:105]
	v_pk_mul_f32 v[102:103], v[158:159], v[102:103]
	s_nop 0
	v_cvt_pk_bf16_f32 v98, v102, v103
	v_cvt_pk_bf16_f32 v99, v104, v105
	v_cvt_pk_bf16_f32 v100, v100, v101
	v_cvt_pk_bf16_f32 v101, v106, v107
	global_store_dwordx4 v[116:117], v[98:101], off offset:64
	s_nop 1
	v_pk_mul_f32 v[98:99], v[96:97], v[96:97]
	v_pk_mul_f32 v[100:101], v[94:95], v[94:95]
	s_nop 0
	v_pk_mov_b32 v[102:103], v[100:101], v[98:99] op_sel:[1,0]
	v_mov_b32_e32 v101, v99
	v_pk_add_f32 v[98:99], v[102:103], v[100:101]
	v_pk_mul_f32 v[100:101], v[92:93], v[92:93]
	v_pk_mul_f32 v[102:103], v[90:91], v[90:91]
	v_pk_add_f32 v[98:99], v[98:99], v[98:99] op_sel:[0,1] op_sel_hi:[1,0]
	v_pk_mov_b32 v[104:105], v[102:103], v[100:101] op_sel:[1,0]
	v_mov_b32_e32 v103, v101
	v_pk_add_f32 v[100:101], v[104:105], v[102:103]
	v_mul_f32_e32 v102, v82, v82
	v_mul_f32_e32 v103, v83, v83
	v_pk_add_f32 v[100:101], v[100:101], v[100:101] op_sel:[0,1] op_sel_hi:[1,0]
	v_mov_b32_e32 v99, v102
	v_mov_b32_e32 v101, v103
	v_pk_add_f32 v[98:99], v[98:99], v[100:101]
	v_mul_f32_e32 v100, v87, v87
	v_mul_f32_e32 v102, v89, v89
	v_mul_f32_e32 v104, v84, v84
	v_mul_f32_e32 v105, v85, v85
	v_pk_fma_f32 v[100:101], v[86:87], v[86:87], v[100:101] op_sel_hi:[1,1,0]
	v_pk_fma_f32 v[102:103], v[88:89], v[88:89], v[102:103] op_sel_hi:[1,1,0]
	v_mov_b32_e32 v101, v104
	v_mov_b32_e32 v103, v105
	v_pk_add_f32 v[100:101], v[100:101], v[102:103]
	s_nop 0
	v_pk_add_f32 v[98:99], v[98:99], v[100:101]
	v_or_b32_e32 v100, 32, v162
	v_add_f32_e32 v98, v98, v99
	ds_bpermute_b32 v99, v168, v98
	v_ashrrev_i32_e32 v101, 31, v100
	v_lshlrev_b64 v[100:101], 11, v[100:101]
	v_lshl_add_u64 v[100:101], v[164:165], 0, v[100:101]
	s_waitcnt lgkmcnt(0)
; __device__ __forceinline__ unsigned cvt_pk_bf16(float lo, float hi) { unsigned r; asm volatile("v_cvt_pk_bf16_f32 %0, %1, %2" : "=v"(r) : "v"(lo), "v"(hi)); return r; }
;     __device__ __forceinline__ void operator()(const f32x4 (&acc)[2][2][4][2], const pg8::Unit& u, int wr, int wc, int fr, int fq) const {
;     ...
; #pragma unroll
;         for (int ai = 0; ai < 2; ++ai)
; #pragma unroll
;             for (int m = 0; m < 4; ++m) {
;                 float ss = 0.f;
; #pragma unroll
;                 for (int bj = 0; bj < 2; ++bj)
; #pragma unroll
;                     for (int n = 0; n < 2; ++n) { const f32x4 x = acc[ai][bj][m][n]; ss += (x[0] * x[0] + x[1] * x[1]) + (x[2] * x[2] + x[3] * x[3]); }
;                 ss += __shfl_xor(ss, 16); ss += __shfl_xor(ss, 32);
;                 const float rs = __builtin_amdgcn_rsqf(ss * (1.0f / 64.0f) + EPSN);
;                 bf16_t* rowp = base + (size_t)(row0 + ai * 128 + m * 16) * DM;
; #pragma unroll
;                 for (int bj = 0; bj < 2; ++bj) { const f32x4 v0 = acc[ai][bj][m][0] * rs * gv[bj][0], v1 = acc[ai][bj][m][1] * rs * gv[bj][1];
;                     u32x4 w; w.x = pg8::cvt_pk_bf16(v0[0], v0[1]); w.y = pg8::cvt_pk_bf16(v0[2], v0[3]); w.z = pg8::cvt_pk_bf16(v1[0], v1[1]); w.w = pg8::cvt_pk_bf16(v1[2], v1[3]);
;                     *(u32x4*)(rowp + 32 * bj) = w; }
;             }
	v_add_f32_e32 v98, v98, v99
	ds_bpermute_b32 v99, v48, v98
	s_waitcnt lgkmcnt(0)
	v_add_f32_e32 v98, v98, v99
	v_fmamk_f32 v98, v98, 0x3c800000, v223
	v_rsq_f32_e32 v98, v98
	s_nop 0
	v_pk_mul_f32 v[94:95], v[94:95], v[98:99] op_sel_hi:[1,0]
	v_pk_mul_f32 v[96:97], v[96:97], v[98:99] op_sel_hi:[1,0]
	v_pk_mul_f32 v[90:91], v[90:91], v[98:99] op_sel_hi:[1,0]
	v_pk_mul_f32 v[92:93], v[92:93], v[98:99] op_sel_hi:[1,0]
	v_pk_mul_f32 v[96:97], v[148:149], v[96:97]
	v_pk_mul_f32 v[94:95], v[150:151], v[94:95]
	v_pk_mul_f32 v[102:103], v[144:145], v[92:93]
	v_pk_mul_f32 v[92:93], v[146:147], v[90:91]
	v_cvt_pk_bf16_f32 v90, v94, v95
	v_cvt_pk_bf16_f32 v91, v96, v97
	v_pk_mul_f32 v[82:83], v[82:83], v[98:99] op_sel_hi:[1,0]
	v_pk_mul_f32 v[84:85], v[84:85], v[98:99] op_sel_hi:[1,0]
	v_cvt_pk_bf16_f32 v92, v92, v93
	v_cvt_pk_bf16_f32 v93, v102, v103
	global_store_dwordx4 v[100:101], v[90:93], off
	v_pk_mul_f32 v[86:87], v[86:87], v[98:99] op_sel_hi:[1,0]
	v_pk_mul_f32 v[88:89], v[88:89], v[98:99] op_sel_hi:[1,0]
	v_pk_mul_f32 v[90:91], v[152:153], v[84:85]
	v_pk_mul_f32 v[84:85], v[154:155], v[82:83]
	v_pk_mul_f32 v[88:89], v[156:157], v[88:89]
	v_pk_mul_f32 v[86:87], v[158:159], v[86:87]
	s_nop 0
	v_cvt_pk_bf16_f32 v82, v86, v87
	v_cvt_pk_bf16_f32 v83, v88, v89
	v_cvt_pk_bf16_f32 v84, v84, v85
	v_cvt_pk_bf16_f32 v85, v90, v91
	global_store_dwordx4 v[100:101], v[82:85], off offset:64
	s_nop 1
	v_pk_mul_f32 v[82:83], v[80:81], v[80:81]
	v_pk_mul_f32 v[84:85], v[78:79], v[78:79]
	s_nop 0
	v_pk_mov_b32 v[86:87], v[84:85], v[82:83] op_sel:[1,0]
	v_mov_b32_e32 v85, v83
	v_pk_add_f32 v[82:83], v[86:87], v[84:85]
	v_pk_mul_f32 v[84:85], v[76:77], v[76:77]
	v_pk_mul_f32 v[86:87], v[74:75], v[74:75]
	v_pk_add_f32 v[82:83], v[82:83], v[82:83] op_sel:[0,1] op_sel_hi:[1,0]
	v_pk_mov_b32 v[88:89], v[86:87], v[84:85] op_sel:[1,0]
	v_mov_b32_e32 v87, v85
	v_pk_add_f32 v[84:85], v[88:89], v[86:87]
	v_mul_f32_e32 v86, v66, v66
	v_mul_f32_e32 v87, v67, v67
	v_pk_add_f32 v[84:85], v[84:85], v[84:85] op_sel:[0,1] op_sel_hi:[1,0]
	v_mov_b32_e32 v83, v86
	v_mov_b32_e32 v85, v87
	v_pk_add_f32 v[82:83], v[82:83], v[84:85]
	v_mul_f32_e32 v84, v71, v71
	v_mul_f32_e32 v86, v73, v73
	v_mul_f32_e32 v88, v68, v68
	v_mul_f32_e32 v89, v69, v69
	v_pk_fma_f32 v[84:85], v[70:71], v[70:71], v[84:85] op_sel_hi:[1,1,0]
	v_pk_fma_f32 v[86:87], v[72:73], v[72:73], v[86:87] op_sel_hi:[1,1,0]
	v_mov_b32_e32 v85, v88
	v_mov_b32_e32 v87, v89
	v_pk_add_f32 v[84:85], v[84:85], v[86:87]
	s_nop 0
	v_pk_add_f32 v[82:83], v[82:83], v[84:85]
	v_or_b32_e32 v84, 48, v162
	v_add_f32_e32 v82, v82, v83
	ds_bpermute_b32 v83, v168, v82
	v_ashrrev_i32_e32 v85, 31, v84
	v_lshlrev_b64 v[84:85], 11, v[84:85]
	v_lshl_add_u64 v[84:85], v[164:165], 0, v[84:85]
	s_waitcnt lgkmcnt(0)
	v_add_f32_e32 v82, v82, v83
	ds_bpermute_b32 v83, v48, v82
	s_waitcnt lgkmcnt(0)
	v_add_f32_e32 v82, v82, v83
	v_fmamk_f32 v82, v82, 0x3c800000, v223
	v_rsq_f32_e32 v82, v82
	s_nop 0
	v_pk_mul_f32 v[78:79], v[78:79], v[82:83] op_sel_hi:[1,0]
	v_pk_mul_f32 v[80:81], v[80:81], v[82:83] op_sel_hi:[1,0]
	v_pk_mul_f32 v[74:75], v[74:75], v[82:83] op_sel_hi:[1,0]
	v_pk_mul_f32 v[76:77], v[76:77], v[82:83] op_sel_hi:[1,0]
	v_pk_mul_f32 v[80:81], v[148:149], v[80:81]
	v_pk_mul_f32 v[78:79], v[150:151], v[78:79]
	v_pk_mul_f32 v[86:87], v[144:145], v[76:77]
	v_pk_mul_f32 v[76:77], v[146:147], v[74:75]
	v_cvt_pk_bf16_f32 v74, v78, v79
	v_cvt_pk_bf16_f32 v75, v80, v81
	v_pk_mul_f32 v[66:67], v[66:67], v[82:83] op_sel_hi:[1,0]
	v_pk_mul_f32 v[68:69], v[68:69], v[82:83] op_sel_hi:[1,0]
	v_cvt_pk_bf16_f32 v76, v76, v77
	v_cvt_pk_bf16_f32 v77, v86, v87
	global_store_dwordx4 v[84:85], v[74:77], off
	v_pk_mul_f32 v[70:71], v[70:71], v[82:83] op_sel_hi:[1,0]
	v_pk_mul_f32 v[72:73], v[72:73], v[82:83] op_sel_hi:[1,0]
	v_pk_mul_f32 v[74:75], v[152:153], v[68:69]
	v_pk_mul_f32 v[68:69], v[154:155], v[66:67]
	v_pk_mul_f32 v[72:73], v[156:157], v[72:73]
	v_pk_mul_f32 v[70:71], v[158:159], v[70:71]
	s_nop 0
	v_cvt_pk_bf16_f32 v66, v70, v71
	v_cvt_pk_bf16_f32 v67, v72, v73
	v_cvt_pk_bf16_f32 v68, v68, v69
	v_cvt_pk_bf16_f32 v69, v74, v75
	global_store_dwordx4 v[84:85], v[66:69], off offset:64
	s_nop 1
	v_pk_mul_f32 v[66:67], v[64:65], v[64:65]
	v_pk_mul_f32 v[68:69], v[62:63], v[62:63]
	s_nop 0
	v_pk_mov_b32 v[70:71], v[68:69], v[66:67] op_sel:[1,0]
	v_mov_b32_e32 v69, v67
	v_pk_add_f32 v[66:67], v[70:71], v[68:69]
	v_pk_mul_f32 v[68:69], v[60:61], v[60:61]
	v_pk_mul_f32 v[70:71], v[58:59], v[58:59]
	v_pk_add_f32 v[66:67], v[66:67], v[66:67] op_sel:[0,1] op_sel_hi:[1,0]
	v_pk_mov_b32 v[72:73], v[70:71], v[68:69] op_sel:[1,0]
	v_mov_b32_e32 v71, v69
	v_pk_add_f32 v[68:69], v[72:73], v[70:71]
	v_mul_f32_e32 v70, v50, v50
	v_mul_f32_e32 v71, v51, v51
	v_pk_add_f32 v[68:69], v[68:69], v[68:69] op_sel:[0,1] op_sel_hi:[1,0]
	v_mov_b32_e32 v67, v70
	v_mov_b32_e32 v69, v71
	v_pk_add_f32 v[66:67], v[66:67], v[68:69]
	v_mul_f32_e32 v68, v55, v55
	v_mul_f32_e32 v70, v57, v57
	v_mul_f32_e32 v72, v52, v52
	v_mul_f32_e32 v73, v53, v53
	v_pk_fma_f32 v[68:69], v[54:55], v[54:55], v[68:69] op_sel_hi:[1,1,0]
	v_pk_fma_f32 v[70:71], v[56:57], v[56:57], v[70:71] op_sel_hi:[1,1,0]
	v_mov_b32_e32 v69, v72
	v_mov_b32_e32 v71, v73
	v_pk_add_f32 v[68:69], v[68:69], v[70:71]
	s_nop 0
	v_pk_add_f32 v[66:67], v[66:67], v[68:69]
	v_lshl_add_u64 v[68:69], v[160:161], 0, s[6:7]
	v_add_f32_e32 v66, v66, v67
	ds_bpermute_b32 v67, v168, v66
	s_mov_b64 s[6:7], 0x48000
	s_waitcnt lgkmcnt(0)
	v_add_f32_e32 v66, v66, v67
	ds_bpermute_b32 v67, v48, v66
	s_waitcnt lgkmcnt(0)
; __device__ __forceinline__ unsigned cvt_pk_bf16(float lo, float hi) { unsigned r; asm volatile("v_cvt_pk_bf16_f32 %0, %1, %2" : "=v"(r) : "v"(lo), "v"(hi)); return r; }
;     __device__ __forceinline__ void operator()(const f32x4 (&acc)[2][2][4][2], const pg8::Unit& u, int wr, int wc, int fr, int fq) const {
;     ...
; #pragma unroll
;         for (int ai = 0; ai < 2; ++ai)
; #pragma unroll
;             for (int m = 0; m < 4; ++m) {
;                 float ss = 0.f;
; #pragma unroll
;                 for (int bj = 0; bj < 2; ++bj)
; #pragma unroll
;                     for (int n = 0; n < 2; ++n) { const f32x4 x = acc[ai][bj][m][n]; ss += (x[0] * x[0] + x[1] * x[1]) + (x[2] * x[2] + x[3] * x[3]); }
;                 ss += __shfl_xor(ss, 16); ss += __shfl_xor(ss, 32);
;                 const float rs = __builtin_amdgcn_rsqf(ss * (1.0f / 64.0f) + EPSN);
;                 bf16_t* rowp = base + (size_t)(row0 + ai * 128 + m * 16) * DM;
; #pragma unroll
;                 for (int bj = 0; bj < 2; ++bj) { const f32x4 v0 = acc[ai][bj][m][0] * rs * gv[bj][0], v1 = acc[ai][bj][m][1] * rs * gv[bj][1];
;                     u32x4 w; w.x = pg8::cvt_pk_bf16(v0[0], v0[1]); w.y = pg8::cvt_pk_bf16(v0[2], v0[3]); w.z = pg8::cvt_pk_bf16(v1[0], v1[1]); w.w = pg8::cvt_pk_bf16(v1[2], v1[3]);
;                     *(u32x4*)(rowp + 32 * bj) = w; }
;             }
	v_add_f32_e32 v66, v66, v67
	v_fmamk_f32 v66, v66, 0x3c800000, v223
	v_rsq_f32_e32 v66, v66
	s_nop 0
	v_pk_mul_f32 v[62:63], v[62:63], v[66:67] op_sel_hi:[1,0]
	s_nop 0
	v_pk_mul_f32 v[62:63], v[150:151], v[62:63]
	v_pk_mul_f32 v[58:59], v[58:59], v[66:67] op_sel_hi:[1,0]
	v_pk_mul_f32 v[60:61], v[60:61], v[66:67] op_sel_hi:[1,0]
	v_pk_mul_f32 v[64:65], v[64:65], v[66:67] op_sel_hi:[1,0]
	v_pk_mul_f32 v[70:71], v[144:145], v[60:61]
	v_pk_mul_f32 v[60:61], v[146:147], v[58:59]
	v_cvt_pk_bf16_f32 v58, v62, v63
	v_add_co_u32_e32 v62, vcc, s2, v160
	v_pk_mul_f32 v[64:65], v[148:149], v[64:65]
	s_nop 0
	v_addc_co_u32_e32 v63, vcc, 0, v161, vcc
	v_cvt_pk_bf16_f32 v59, v64, v65
	v_pk_mul_f32 v[50:51], v[50:51], v[66:67] op_sel_hi:[1,0]
	v_pk_mul_f32 v[52:53], v[52:53], v[66:67] op_sel_hi:[1,0]
	v_cvt_pk_bf16_f32 v60, v60, v61
	v_cvt_pk_bf16_f32 v61, v70, v71
	global_store_dwordx4 v[62:63], v[58:61], off
	v_pk_mul_f32 v[54:55], v[54:55], v[66:67] op_sel_hi:[1,0]
	v_pk_mul_f32 v[56:57], v[56:57], v[66:67] op_sel_hi:[1,0]
	v_pk_mul_f32 v[58:59], v[152:153], v[52:53]
	v_pk_mul_f32 v[52:53], v[154:155], v[50:51]
	v_pk_mul_f32 v[56:57], v[156:157], v[56:57]
	v_pk_mul_f32 v[54:55], v[158:159], v[54:55]
	s_mov_b32 s2, 0x50000
	v_cvt_pk_bf16_f32 v50, v54, v55
	v_cvt_pk_bf16_f32 v51, v56, v57
	v_cvt_pk_bf16_f32 v52, v52, v53
	v_cvt_pk_bf16_f32 v53, v58, v59
	global_store_dwordx4 v[68:69], v[50:53], off offset:64
	s_nop 1
	v_pk_mul_f32 v[50:51], v[46:47], v[46:47]
	v_pk_mul_f32 v[52:53], v[44:45], v[44:45]
	s_nop 0
	v_pk_mov_b32 v[54:55], v[52:53], v[50:51] op_sel:[1,0]
	v_mov_b32_e32 v53, v51
	v_pk_add_f32 v[50:51], v[54:55], v[52:53]
	v_pk_mul_f32 v[52:53], v[42:43], v[42:43]
	v_pk_mul_f32 v[54:55], v[40:41], v[40:41]
	v_pk_add_f32 v[50:51], v[50:51], v[50:51] op_sel:[0,1] op_sel_hi:[1,0]
	v_pk_mov_b32 v[56:57], v[54:55], v[52:53] op_sel:[1,0]
	v_mov_b32_e32 v55, v53
	v_pk_add_f32 v[52:53], v[56:57], v[54:55]
	v_mul_f32_e32 v54, v32, v32
	v_mul_f32_e32 v55, v33, v33
	v_pk_add_f32 v[52:53], v[52:53], v[52:53] op_sel:[0,1] op_sel_hi:[1,0]
	v_mov_b32_e32 v51, v54
	v_mov_b32_e32 v53, v55
	v_pk_add_f32 v[50:51], v[50:51], v[52:53]
	v_mul_f32_e32 v52, v37, v37
	v_mul_f32_e32 v54, v39, v39
	v_mul_f32_e32 v56, v34, v34
	v_mul_f32_e32 v57, v35, v35
	v_pk_fma_f32 v[52:53], v[36:37], v[36:37], v[52:53] op_sel_hi:[1,1,0]
	v_pk_fma_f32 v[54:55], v[38:39], v[38:39], v[54:55] op_sel_hi:[1,1,0]
	v_mov_b32_e32 v53, v56
	v_mov_b32_e32 v55, v57
	v_pk_add_f32 v[52:53], v[52:53], v[54:55]
	s_nop 0
	v_pk_add_f32 v[50:51], v[50:51], v[52:53]
	v_lshl_add_u64 v[52:53], v[160:161], 0, s[6:7]
	v_add_f32_e32 v50, v50, v51
	ds_bpermute_b32 v51, v168, v50
	s_mov_b64 s[6:7], 0x50000
	s_waitcnt lgkmcnt(0)
	v_add_f32_e32 v50, v50, v51
	ds_bpermute_b32 v51, v48, v50
	s_waitcnt lgkmcnt(0)
	v_add_f32_e32 v50, v50, v51
	v_fmamk_f32 v50, v50, 0x3c800000, v223
	v_rsq_f32_e32 v50, v50
	s_nop 0
	v_pk_mul_f32 v[44:45], v[44:45], v[50:51] op_sel_hi:[1,0]
	s_nop 0
	v_pk_mul_f32 v[44:45], v[150:151], v[44:45]
	v_pk_mul_f32 v[40:41], v[40:41], v[50:51] op_sel_hi:[1,0]
	v_pk_mul_f32 v[42:43], v[42:43], v[50:51] op_sel_hi:[1,0]
	v_pk_mul_f32 v[46:47], v[46:47], v[50:51] op_sel_hi:[1,0]
	v_pk_mul_f32 v[54:55], v[144:145], v[42:43]
	v_pk_mul_f32 v[42:43], v[146:147], v[40:41]
	v_cvt_pk_bf16_f32 v40, v44, v45
	v_add_co_u32_e32 v44, vcc, s58, v160
	v_pk_mul_f32 v[46:47], v[148:149], v[46:47]
	s_nop 0
	v_addc_co_u32_e32 v45, vcc, 0, v161, vcc
	v_cvt_pk_bf16_f32 v41, v46, v47
	v_pk_mul_f32 v[32:33], v[32:33], v[50:51] op_sel_hi:[1,0]
	v_pk_mul_f32 v[34:35], v[34:35], v[50:51] op_sel_hi:[1,0]
	v_cvt_pk_bf16_f32 v42, v42, v43
	v_cvt_pk_bf16_f32 v43, v54, v55
	global_store_dwordx4 v[44:45], v[40:43], off
	v_pk_mul_f32 v[36:37], v[36:37], v[50:51] op_sel_hi:[1,0]
	v_pk_mul_f32 v[38:39], v[38:39], v[50:51] op_sel_hi:[1,0]
	v_pk_mul_f32 v[40:41], v[152:153], v[34:35]
	v_pk_mul_f32 v[34:35], v[154:155], v[32:33]
	v_pk_mul_f32 v[38:39], v[156:157], v[38:39]
	v_pk_mul_f32 v[36:37], v[158:159], v[36:37]
	s_nop 0
	v_cvt_pk_bf16_f32 v32, v36, v37
	v_cvt_pk_bf16_f32 v33, v38, v39
	v_cvt_pk_bf16_f32 v34, v34, v35
	v_cvt_pk_bf16_f32 v35, v40, v41
	global_store_dwordx4 v[52:53], v[32:35], off offset:64
	s_nop 1
	v_pk_mul_f32 v[32:33], v[30:31], v[30:31]
	v_pk_mul_f32 v[34:35], v[28:29], v[28:29]
	s_nop 0
	v_pk_mov_b32 v[36:37], v[34:35], v[32:33] op_sel:[1,0]
	v_mov_b32_e32 v35, v33
	v_pk_add_f32 v[32:33], v[36:37], v[34:35]
	v_pk_mul_f32 v[34:35], v[26:27], v[26:27]
	v_pk_mul_f32 v[36:37], v[24:25], v[24:25]
	v_pk_add_f32 v[32:33], v[32:33], v[32:33] op_sel:[0,1] op_sel_hi:[1,0]
	v_pk_mov_b32 v[38:39], v[36:37], v[34:35] op_sel:[1,0]
	v_mov_b32_e32 v37, v35
	v_pk_add_f32 v[34:35], v[38:39], v[36:37]
	v_mul_f32_e32 v36, v16, v16
	v_mul_f32_e32 v37, v17, v17
	v_pk_add_f32 v[34:35], v[34:35], v[34:35] op_sel:[0,1] op_sel_hi:[1,0]
	v_mov_b32_e32 v33, v36
	v_mov_b32_e32 v35, v37
	v_pk_add_f32 v[32:33], v[32:33], v[34:35]
	v_mul_f32_e32 v34, v21, v21
	v_mul_f32_e32 v36, v23, v23
	v_mul_f32_e32 v38, v18, v18
	v_mul_f32_e32 v39, v19, v19
	v_pk_fma_f32 v[34:35], v[20:21], v[20:21], v[34:35] op_sel_hi:[1,1,0]
	v_pk_fma_f32 v[36:37], v[22:23], v[22:23], v[36:37] op_sel_hi:[1,1,0]
	v_mov_b32_e32 v35, v38
	v_mov_b32_e32 v37, v39
	v_pk_add_f32 v[34:35], v[34:35], v[36:37]
	s_nop 0
	v_pk_add_f32 v[32:33], v[32:33], v[34:35]
	v_lshl_add_u64 v[34:35], v[160:161], 0, s[6:7]
	v_add_f32_e32 v32, v32, v33
	ds_bpermute_b32 v33, v168, v32
	s_mov_b64 s[6:7], 0x58000
	s_waitcnt lgkmcnt(0)
; __device__ __forceinline__ unsigned cvt_pk_bf16(float lo, float hi) { unsigned r; asm volatile("v_cvt_pk_bf16_f32 %0, %1, %2" : "=v"(r) : "v"(lo), "v"(hi)); return r; }
; #define PG8_WAIT_V(n) asm volatile("s_waitcnt vmcnt(" #n ")" ::: "memory")
; #define PG8_BAR __builtin_amdgcn_s_barrier()
; template <class Epi, class Sched>
; __device__ __forceinline__ void gemm_phase(PG8_LAS unsigned char* lds, const Gemm g, const Sched& S, const Epi& E) {
;     ...
;         if constexpr (!Epi::AFTER_DRAIN) { E(acc, cur, wr, wc, fr, fq); S.done(cur); }
;         if (!has_next) break;
; #pragma unroll
;         for (int a = 0; a < 2; ++a)
; #pragma unroll
;             for (int b = 0; b < 2; ++b)
; #pragma unroll
;                 for (int m = 0; m < 4; ++m)
; #pragma unroll
;                     for (int n = 0; n < 2; ++n) acc[a][b][m][n] = (f32x4){0.f, 0.f, 0.f, 0.f};
;         cur = nxt; cA = nA; cB = nB; ++ui;
;     }
;     PG8_WAIT_V(0);
;     if (wr == 0) PG8_BAR;
;     __device__ __forceinline__ void operator()(const f32x4 (&acc)[2][2][4][2], const pg8::Unit& u, int wr, int wc, int fr, int fq) const {
;     ...
;             for (int m = 0; m < 4; ++m) {
;                 float ss = 0.f;
; #pragma unroll
;                 for (int bj = 0; bj < 2; ++bj)
; #pragma unroll
;                     for (int n = 0; n < 2; ++n) { const f32x4 x = acc[ai][bj][m][n]; ss += (x[0] * x[0] + x[1] * x[1]) + (x[2] * x[2] + x[3] * x[3]); }
;                 ss += __shfl_xor(ss, 16); ss += __shfl_xor(ss, 32);
;                 const float rs = __builtin_amdgcn_rsqf(ss * (1.0f / 64.0f) + EPSN);
;                 bf16_t* rowp = base + (size_t)(row0 + ai * 128 + m * 16) * DM;
; #pragma unroll
;                 for (int bj = 0; bj < 2; ++bj) { const f32x4 v0 = acc[ai][bj][m][0] * rs * gv[bj][0], v1 = acc[ai][bj][m][1] * rs * gv[bj][1];
;                     u32x4 w; w.x = pg8::cvt_pk_bf16(v0[0], v0[1]); w.y = pg8::cvt_pk_bf16(v0[2], v0[3]); w.z = pg8::cvt_pk_bf16(v1[0], v1[1]); w.w = pg8::cvt_pk_bf16(v1[2], v1[3]);
;                     *(u32x4*)(rowp + 32 * bj) = w; }
;             }
	v_add_f32_e32 v32, v32, v33
	ds_bpermute_b32 v33, v48, v32
	s_waitcnt lgkmcnt(0)
	v_add_f32_e32 v32, v32, v33
	v_fmamk_f32 v32, v32, 0x3c800000, v223
	v_rsq_f32_e32 v32, v32
	s_nop 0
	v_pk_mul_f32 v[28:29], v[28:29], v[32:33] op_sel_hi:[1,0]
	s_nop 0
	v_pk_mul_f32 v[28:29], v[150:151], v[28:29]
	v_pk_mul_f32 v[24:25], v[24:25], v[32:33] op_sel_hi:[1,0]
	v_pk_mul_f32 v[26:27], v[26:27], v[32:33] op_sel_hi:[1,0]
	v_pk_mul_f32 v[30:31], v[30:31], v[32:33] op_sel_hi:[1,0]
	v_pk_mul_f32 v[36:37], v[144:145], v[26:27]
	v_pk_mul_f32 v[26:27], v[146:147], v[24:25]
	v_cvt_pk_bf16_f32 v24, v28, v29
	v_add_co_u32_e32 v28, vcc, s2, v160
	v_pk_mul_f32 v[30:31], v[148:149], v[30:31]
	s_nop 0
	v_addc_co_u32_e32 v29, vcc, 0, v161, vcc
	v_cvt_pk_bf16_f32 v25, v30, v31
	v_pk_mul_f32 v[16:17], v[16:17], v[32:33] op_sel_hi:[1,0]
	v_pk_mul_f32 v[18:19], v[18:19], v[32:33] op_sel_hi:[1,0]
	v_cvt_pk_bf16_f32 v26, v26, v27
	v_cvt_pk_bf16_f32 v27, v36, v37
	global_store_dwordx4 v[28:29], v[24:27], off
	v_pk_mul_f32 v[20:21], v[20:21], v[32:33] op_sel_hi:[1,0]
	v_pk_mul_f32 v[22:23], v[22:23], v[32:33] op_sel_hi:[1,0]
	v_pk_mul_f32 v[24:25], v[152:153], v[18:19]
	v_pk_mul_f32 v[18:19], v[154:155], v[16:17]
	v_pk_mul_f32 v[22:23], v[156:157], v[22:23]
	v_pk_mul_f32 v[20:21], v[158:159], v[20:21]
	s_mov_b32 s2, 0x58000
	v_cvt_pk_bf16_f32 v16, v20, v21
	v_cvt_pk_bf16_f32 v17, v22, v23
	v_cvt_pk_bf16_f32 v18, v18, v19
	v_cvt_pk_bf16_f32 v19, v24, v25
	global_store_dwordx4 v[34:35], v[16:19], off offset:64
	s_nop 1
	v_pk_mul_f32 v[16:17], v[14:15], v[14:15]
	v_pk_mul_f32 v[18:19], v[12:13], v[12:13]
	s_nop 0
	v_pk_mov_b32 v[20:21], v[18:19], v[16:17] op_sel:[1,0]
	v_mov_b32_e32 v19, v17
	v_pk_add_f32 v[16:17], v[20:21], v[18:19]
	v_pk_mul_f32 v[18:19], v[10:11], v[10:11]
	v_pk_mul_f32 v[20:21], v[8:9], v[8:9]
	v_pk_add_f32 v[16:17], v[16:17], v[16:17] op_sel:[0,1] op_sel_hi:[1,0]
	v_pk_mov_b32 v[22:23], v[20:21], v[18:19] op_sel:[1,0]
	v_mov_b32_e32 v21, v19
	v_pk_add_f32 v[18:19], v[22:23], v[20:21]
	v_mul_f32_e32 v20, v0, v0
	v_mul_f32_e32 v21, v1, v1
	v_pk_add_f32 v[18:19], v[18:19], v[18:19] op_sel:[0,1] op_sel_hi:[1,0]
	v_mov_b32_e32 v17, v20
	v_mov_b32_e32 v19, v21
	v_pk_add_f32 v[16:17], v[16:17], v[18:19]
	v_mul_f32_e32 v18, v5, v5
	v_mul_f32_e32 v20, v7, v7
	v_mul_f32_e32 v22, v2, v2
	v_mul_f32_e32 v23, v3, v3
	v_pk_fma_f32 v[18:19], v[4:5], v[4:5], v[18:19] op_sel_hi:[1,1,0]
	v_pk_fma_f32 v[20:21], v[6:7], v[6:7], v[20:21] op_sel_hi:[1,1,0]
	v_mov_b32_e32 v19, v22
	v_mov_b32_e32 v21, v23
	v_pk_add_f32 v[18:19], v[18:19], v[20:21]
	s_nop 0
	v_pk_add_f32 v[16:17], v[16:17], v[18:19]
	v_lshl_add_u64 v[18:19], v[160:161], 0, s[6:7]
	v_add_f32_e32 v16, v16, v17
	ds_bpermute_b32 v17, v168, v16
	s_mov_b64 s[6:7], s[24:25]
	s_waitcnt lgkmcnt(0)
	v_add_f32_e32 v16, v16, v17
	ds_bpermute_b32 v17, v48, v16
	s_waitcnt lgkmcnt(0)
	v_add_f32_e32 v16, v16, v17
	v_fmamk_f32 v16, v16, 0x3c800000, v223
	v_rsq_f32_e32 v16, v16
	s_nop 0
	v_pk_mul_f32 v[12:13], v[12:13], v[16:17] op_sel_hi:[1,0]
	s_nop 0
	v_pk_mul_f32 v[12:13], v[150:151], v[12:13]
	v_pk_mul_f32 v[8:9], v[8:9], v[16:17] op_sel_hi:[1,0]
	v_pk_mul_f32 v[10:11], v[10:11], v[16:17] op_sel_hi:[1,0]
	v_pk_mul_f32 v[14:15], v[14:15], v[16:17] op_sel_hi:[1,0]
	v_pk_mul_f32 v[20:21], v[144:145], v[10:11]
	v_pk_mul_f32 v[10:11], v[146:147], v[8:9]
	v_cvt_pk_bf16_f32 v8, v12, v13
	v_add_co_u32_e32 v12, vcc, s2, v160
	v_pk_mul_f32 v[14:15], v[148:149], v[14:15]
	s_nop 0
	v_addc_co_u32_e32 v13, vcc, 0, v161, vcc
	v_cvt_pk_bf16_f32 v9, v14, v15
	v_pk_mul_f32 v[0:1], v[0:1], v[16:17] op_sel_hi:[1,0]
	v_pk_mul_f32 v[2:3], v[2:3], v[16:17] op_sel_hi:[1,0]
	v_cvt_pk_bf16_f32 v10, v10, v11
	v_cvt_pk_bf16_f32 v11, v20, v21
	global_store_dwordx4 v[12:13], v[8:11], off
	v_pk_mul_f32 v[4:5], v[4:5], v[16:17] op_sel_hi:[1,0]
	v_pk_mul_f32 v[6:7], v[6:7], v[16:17] op_sel_hi:[1,0]
	v_pk_mul_f32 v[8:9], v[152:153], v[2:3]
	v_pk_mul_f32 v[2:3], v[154:155], v[0:1]
	s_and_b64 vcc, exec, s[40:41]
	s_mov_b32 s2, s22
	v_pk_mul_f32 v[6:7], v[156:157], v[6:7]
	v_pk_mul_f32 v[4:5], v[158:159], v[4:5]
	s_nop 0
	v_cvt_pk_bf16_f32 v0, v4, v5
	v_cvt_pk_bf16_f32 v1, v6, v7
	v_cvt_pk_bf16_f32 v2, v2, v3
	v_cvt_pk_bf16_f32 v3, v8, v9
	global_store_dwordx4 v[18:19], v[0:3], off offset:64
	s_cbranch_vccz .LBB0_332
	s_waitcnt vmcnt(0)
	v_readlane_b32 s46, v254, 33
	v_readlane_b32 s48, v254, 35
	s_cmpk_gt_u32 s19, 0xff
	v_readlane_b32 s47, v254, 34
	v_readlane_b32 s49, v254, 36
	s_cbranch_scc1 .LBB0_339
	s_barrier

; #define PG8_STAGE(bufoff, gbase, voff) do { _Pragma("unroll") for (int _i = 0; _i < 2; ++_i) \
;         __builtin_amdgcn_global_load_lds((const unsigned*)((const char*)(gbase) + (voff)[_i]), (PG8_LAS unsigned*)(lds + (bufoff) + ldsw + _i * 8192), 16, 0, 0); } while (0)
; #define PG8_LDA(dst, b, h) do { _Pragma("unroll") for (int m = 0; m < 4; ++m) _Pragma("unroll") for (int k = 0; k < 2; ++k) dst[m][k] = *(const PG8_LAS bf16x8*)(lds + PG8_SA(b, h) + aoff + m * 2048 + k * 1024); } while (0)
; #define PG8_LDB(dst, b, h) do { _Pragma("unroll") for (int n = 0; n < 2; ++n) _Pragma("unroll") for (int k = 0; k < 2; ++k) dst[n][k] = *(const PG8_LAS bf16x8*)(lds + PG8_SB(b, h) + boff + n * 2048 + k * 1024); } while (0)
; template <class Epi, class Sched>
; __device__ __forceinline__ void gemm_phase(PG8_LAS unsigned char* lds, const Gemm g, const Sched& S, const Epi& E) {
;     ...
;         const bool has_next = S.next(ui + 1, nxt);
;         const char* nA = has_next ? (const char*)g.A + (size_t)nxt.pm * tstepA + (size_t)nxt.kc * cstep : cA; const char* nB = has_next ? (const char*)g.Bt + (size_t)nxt.pn * tstep + (size_t)nxt.kc * cstep : cB;
;         for (int t = 0; t < nt; t += 2) {
;             const bool last = (t == nt - 2);
;             const char* a1 = cA + (size_t)(t + 1) * kstep;
;             const char* a2 = last ? nA : cA + (size_t)(t + 2) * kstep; const char* b2 = last ? nB : cB + (size_t)(t + 2) * kstep;
;             const char* a3 = a2 + kstep; const char* b3 = b2 + kstep;
;             if (last && has_next) S.a_ready(nxt);
;             PG8_LDB(B0, 0, 0); PG8_SCHED; PG8_LDA(At, 0, 0); PG8_STAGE(PG8_SA(1, 1), a1 + hstep, voffA);
;             PG8_WAIT_L(8); PG8_BAR; PG8_WAIT_L(0); PG8_MMA(0, 0, At, B0); PG8_BAR; PG8_SCHED;
;             PG8_LDB(B1, 0, 1); PG8_STAGE(PG8_SB(0, 0), b2, voffB);
;             PG8_BAR; PG8_WAIT_L(0); PG8_MMA(0, 1, At, B1); PG8_BAR;
;             PG8_LDA(At, 0, 1); PG8_STAGE(PG8_SA(0, 0), a2, voffA);
;             PG8_BAR; PG8_WAIT_L(0); PG8_MMA(1, 0, At, B0); PG8_BAR; PG8_SCHED;
;             PG8_STAGE(PG8_SB(0, 1), b2 + hstep, voffB);
;             PG8_WAIT_V(6); PG8_BAR; PG8_MMA(1, 1, At, B1); PG8_BAR;
;             PG8_LDB(B0, 1, 0); PG8_SCHED; PG8_LDA(At, 1, 0); PG8_STAGE(PG8_SA(0, 1), a2 + hstep, voffA);
;             PG8_WAIT_L(8); PG8_BAR; PG8_WAIT_L(0); PG8_MMA(0, 0, At, B0); PG8_BAR; PG8_SCHED;
.LBB0_387:
	s_ashr_i32 s39, s38, 31
	s_lshl_b64 s[16:17], s[38:39], 19
	v_readlane_b32 s3, v254, 53
	s_add_u32 s94, s3, s16
	v_readlane_b32 s3, v254, 54
	s_addc_u32 s95, s3, s17
	s_and_b64 s[16:17], s[62:63], exec
	s_cselect_b32 s3, s95, s13
	s_cselect_b32 s26, s94, s12
	s_add_u32 s6, s6, 0x40080
	s_addc_u32 s7, s7, 0
	s_add_u32 s27, s12, 0x100
	s_addc_u32 s29, s13, 0
	s_mov_b32 s30, -2
	s_add_u32 s12, s6, 0xfffc0080
	s_addc_u32 s13, s7, -1
	s_add_i32 s22, 0, 0x10000
	v_add_u32_e32 v48, s22, v250
	ds_read_b128 v[130:133], v48
	ds_read_b128 v[134:137], v48 offset:1024
	ds_read_b128 v[138:141], v48 offset:2048
	ds_read_b128 v[142:145], v48 offset:3072
	s_cmp_eq_u32 s30, 12
	s_cselect_b32 s17, s9, s13
	s_cselect_b32 s16, s8, s12
	s_cselect_b32 s13, s3, s29
	s_cselect_b32 s12, s26, s27
	v_lshl_add_u64 v[192:193], s[6:7], 0, v[184:185]
	s_add_i32 m0, s37, 0xc000
	ds_read_b128 v[146:149], v242
	ds_read_b128 v[150:153], v242 offset:1024
	ds_read_b128 v[154:157], v242 offset:2048
	ds_read_b128 v[158:161], v242 offset:3072
	ds_read_b128 v[162:165], v242 offset:4096
	ds_read_b128 v[166:169], v242 offset:5120
	ds_read_b128 v[170:173], v242 offset:6144
	ds_read_b128 v[188:191], v242 offset:7168
	global_load_lds_dwordx4 v[192:193], off
	v_lshl_add_u64 v[192:193], s[6:7], 0, v[186:187]
	s_add_i32 m0, s37, 0xe000
	s_nop 0
	global_load_lds_dwordx4 v[192:193], off
	s_waitcnt lgkmcnt(8)
	s_barrier
	s_setprio 0
	s_waitcnt lgkmcnt(7)
	v_mfma_f32_16x16x32_bf16 v[126:129], v[130:133], v[146:149], 0
	v_mfma_f32_16x16x32_bf16 v[62:65], v[138:141], v[146:149], 0
	s_waitcnt lgkmcnt(5)
	v_mfma_f32_16x16x32_bf16 v[118:121], v[130:133], v[154:157], 0
	v_mfma_f32_16x16x32_bf16 v[54:57], v[138:141], v[154:157], 0
	s_waitcnt lgkmcnt(3)
	v_mfma_f32_16x16x32_bf16 v[110:113], v[130:133], v[162:165], 0
	v_mfma_f32_16x16x32_bf16 v[44:47], v[138:141], v[162:165], 0
	s_waitcnt lgkmcnt(1)
	v_mfma_f32_16x16x32_bf16 v[102:105], v[130:133], v[170:173], 0
	v_mfma_f32_16x16x32_bf16 v[36:39], v[138:141], v[170:173], 0
	v_mfma_f32_16x16x32_bf16 v[126:129], v[134:137], v[150:153], v[126:129]
	v_mfma_f32_16x16x32_bf16 v[62:65], v[142:145], v[150:153], v[62:65]
	v_mfma_f32_16x16x32_bf16 v[118:121], v[134:137], v[158:161], v[118:121]
	v_mfma_f32_16x16x32_bf16 v[54:57], v[142:145], v[158:161], v[54:57]
	v_mfma_f32_16x16x32_bf16 v[110:113], v[134:137], v[166:169], v[110:113]
	v_mfma_f32_16x16x32_bf16 v[44:47], v[142:145], v[166:169], v[44:47]
	s_waitcnt lgkmcnt(0)
	v_mfma_f32_16x16x32_bf16 v[102:105], v[134:137], v[188:191], v[102:105]
	v_mfma_f32_16x16x32_bf16 v[36:39], v[142:145], v[188:191], v[36:39]
	s_setprio 1
	s_barrier
	s_add_i32 s31, 0, 0x14000
	s_add_i32 s22, s22, s36
	v_add_u32_e32 v48, s31, v250
	v_lshl_add_u64 v[208:209], s[12:13], 0, v[178:179]
	s_mov_b32 m0, s22
	ds_read_b128 v[192:195], v48
	ds_read_b128 v[196:199], v48 offset:1024
	ds_read_b128 v[200:203], v48 offset:2048
	ds_read_b128 v[204:207], v48 offset:3072
	global_load_lds_dwordx4 v[208:209], off
	v_lshl_add_u64 v[210:211], s[12:13], 0, v[182:183]
	s_add_i32 m0, s22, 0x2000
	s_nop 0
	global_load_lds_dwordx4 v[210:211], off
	s_barrier
	s_setprio 0
	s_waitcnt lgkmcnt(3)
	v_mfma_f32_16x16x32_bf16 v[122:125], v[192:195], v[146:149], 0
	s_waitcnt lgkmcnt(1)
	v_mfma_f32_16x16x32_bf16 v[58:61], v[200:203], v[146:149], 0
	v_mfma_f32_16x16x32_bf16 v[114:117], v[192:195], v[154:157], 0
	v_mfma_f32_16x16x32_bf16 v[50:53], v[200:203], v[154:157], 0
	v_mfma_f32_16x16x32_bf16 v[106:109], v[192:195], v[162:165], 0
	v_mfma_f32_16x16x32_bf16 v[40:43], v[200:203], v[162:165], 0
	v_mfma_f32_16x16x32_bf16 v[98:101], v[192:195], v[170:173], 0
	v_mfma_f32_16x16x32_bf16 v[32:35], v[200:203], v[170:173], 0
	v_mfma_f32_16x16x32_bf16 v[122:125], v[196:199], v[150:153], v[122:125]
	s_waitcnt lgkmcnt(0)
	v_mfma_f32_16x16x32_bf16 v[58:61], v[204:207], v[150:153], v[58:61]
	v_mfma_f32_16x16x32_bf16 v[114:117], v[196:199], v[158:161], v[114:117]
	v_mfma_f32_16x16x32_bf16 v[50:53], v[204:207], v[158:161], v[50:53]
	v_mfma_f32_16x16x32_bf16 v[106:109], v[196:199], v[166:169], v[106:109]
	v_mfma_f32_16x16x32_bf16 v[40:43], v[204:207], v[166:169], v[40:43]
	v_mfma_f32_16x16x32_bf16 v[98:101], v[196:199], v[188:191], v[98:101]
	v_mfma_f32_16x16x32_bf16 v[32:35], v[204:207], v[188:191], v[32:35]
	s_setprio 1
	s_mov_b32 m0, s37
	v_lshl_add_u64 v[212:213], s[16:17], 0, v[176:177]
	s_barrier
	ds_read_b128 v[146:149], v242 offset:16384
	ds_read_b128 v[150:153], v242 offset:17408
	ds_read_b128 v[154:157], v242 offset:18432
	ds_read_b128 v[158:161], v242 offset:19456
	ds_read_b128 v[162:165], v242 offset:20480
	ds_read_b128 v[166:169], v242 offset:21504
	ds_read_b128 v[170:173], v242 offset:22528
	ds_read_b128 v[188:191], v242 offset:23552
	global_load_lds_dwordx4 v[212:213], off
	v_lshl_add_u64 v[214:215], s[16:17], 0, v[180:181]
	s_mov_b32 m0, s10
	s_nop 0
	global_load_lds_dwordx4 v[214:215], off
	s_barrier
	s_setprio 0
	s_waitcnt lgkmcnt(7)
	v_mfma_f32_16x16x32_bf16 v[94:97], v[130:133], v[146:149], 0
	v_mfma_f32_16x16x32_bf16 v[28:31], v[138:141], v[146:149], 0
	s_waitcnt lgkmcnt(5)
	v_mfma_f32_16x16x32_bf16 v[86:89], v[130:133], v[154:157], 0
	v_mfma_f32_16x16x32_bf16 v[20:23], v[138:141], v[154:157], 0
	s_waitcnt lgkmcnt(3)
	v_mfma_f32_16x16x32_bf16 v[78:81], v[130:133], v[162:165], 0
	v_mfma_f32_16x16x32_bf16 v[12:15], v[138:141], v[162:165], 0
	s_waitcnt lgkmcnt(1)
	v_mfma_f32_16x16x32_bf16 v[70:73], v[130:133], v[170:173], 0
	v_mfma_f32_16x16x32_bf16 v[4:7], v[138:141], v[170:173], 0
	v_mfma_f32_16x16x32_bf16 v[94:97], v[134:137], v[150:153], v[94:97]
	v_mfma_f32_16x16x32_bf16 v[28:31], v[142:145], v[150:153], v[28:31]
	v_mfma_f32_16x16x32_bf16 v[86:89], v[134:137], v[158:161], v[86:89]
	v_mfma_f32_16x16x32_bf16 v[20:23], v[142:145], v[158:161], v[20:23]
	v_mfma_f32_16x16x32_bf16 v[78:81], v[134:137], v[166:169], v[78:81]
	v_mfma_f32_16x16x32_bf16 v[12:15], v[142:145], v[166:169], v[12:15]
	s_waitcnt lgkmcnt(0)
	v_mfma_f32_16x16x32_bf16 v[70:73], v[134:137], v[188:191], v[70:73]
	v_mfma_f32_16x16x32_bf16 v[4:7], v[142:145], v[188:191], v[4:7]
	s_setprio 1
	s_barrier
; #define PG8_STAGE(bufoff, gbase, voff) do { _Pragma("unroll") for (int _i = 0; _i < 2; ++_i) \
;         __builtin_amdgcn_global_load_lds((const unsigned*)((const char*)(gbase) + (voff)[_i]), (PG8_LAS unsigned*)(lds + (bufoff) + ldsw + _i * 8192), 16, 0, 0); } while (0)
; #define PG8_LDA(dst, b, h) do { _Pragma("unroll") for (int m = 0; m < 4; ++m) _Pragma("unroll") for (int k = 0; k < 2; ++k) dst[m][k] = *(const PG8_LAS bf16x8*)(lds + PG8_SA(b, h) + aoff + m * 2048 + k * 1024); } while (0)
; #define PG8_LDB(dst, b, h) do { _Pragma("unroll") for (int n = 0; n < 2; ++n) _Pragma("unroll") for (int k = 0; k < 2; ++k) dst[n][k] = *(const PG8_LAS bf16x8*)(lds + PG8_SB(b, h) + boff + n * 2048 + k * 1024); } while (0)
; #define PG8_MMA(ai, bj, At, Bt) do { __builtin_amdgcn_s_setprio(1); _Pragma("unroll") for (int m = 0; m < 4; ++m) _Pragma("unroll") for (int n = 0; n < 2; ++n) _Pragma("unroll") for (int k = 0; k < 2; ++k) \
;         acc[ai][bj][m][n] = __builtin_amdgcn_mfma_f32_16x16x32_bf16(Bt[n][k], At[m][k], acc[ai][bj][m][n], 0, 0, 0); __builtin_amdgcn_s_setprio(0); } while (0)
; #define PG8_WAIT_V(n) asm volatile("s_waitcnt vmcnt(" #n ")" ::: "memory")
; #define PG8_WAIT_L(n) asm volatile("s_waitcnt lgkmcnt(" #n ")" ::: "memory")
; #define PG8_BAR __builtin_amdgcn_s_barrier()
; template <class Epi, class Sched>
; __device__ __forceinline__ void gemm_phase(PG8_LAS unsigned char* lds, const Gemm g, const Sched& S, const Epi& E) {
;     ...
;             PG8_LDB(B1, 0, 1); PG8_STAGE(PG8_SB(0, 0), b2, voffB);
;             PG8_BAR; PG8_WAIT_L(0); PG8_MMA(0, 1, At, B1); PG8_BAR;
;             PG8_LDA(At, 0, 1); PG8_STAGE(PG8_SA(0, 0), a2, voffA);
;             PG8_BAR; PG8_WAIT_L(0); PG8_MMA(1, 0, At, B0); PG8_BAR; PG8_SCHED;
;             PG8_STAGE(PG8_SB(0, 1), b2 + hstep, voffB);
;             PG8_WAIT_V(6); PG8_BAR; PG8_MMA(1, 1, At, B1); PG8_BAR;
;             PG8_LDB(B0, 1, 0); PG8_SCHED; PG8_LDA(At, 1, 0); PG8_STAGE(PG8_SA(0, 1), a2 + hstep, voffA);
;             PG8_WAIT_L(8); PG8_BAR; PG8_WAIT_L(0); PG8_MMA(0, 0, At, B0); PG8_BAR; PG8_SCHED;
;             PG8_LDB(B1, 1, 1); PG8_STAGE(PG8_SB(1, 0), b3, voffB);
;             PG8_BAR; PG8_WAIT_L(0); PG8_MMA(0, 1, At, B1); PG8_BAR;
;             PG8_LDA(At, 1, 1); PG8_STAGE(PG8_SA(1, 0), a3, voffA);
;             PG8_BAR; PG8_WAIT_L(0); PG8_MMA(1, 0, At, B0); PG8_BAR; PG8_SCHED;
	s_add_u32 s22, s12, 0x40000
	s_addc_u32 s23, s13, 0
	s_add_i32 s31, s31, s36
	v_lshl_add_u64 v[130:131], s[22:23], 0, v[178:179]
	s_mov_b32 m0, s31
	s_nop 0
	global_load_lds_dwordx4 v[130:131], off
	v_lshl_add_u64 v[130:131], s[22:23], 0, v[182:183]
	s_add_i32 m0, s31, 0x2000
	s_nop 0
	global_load_lds_dwordx4 v[130:131], off
	s_waitcnt vmcnt(6)
	s_barrier
	s_setprio 0
	v_mfma_f32_16x16x32_bf16 v[90:93], v[192:195], v[146:149], 0
	v_mfma_f32_16x16x32_bf16 v[24:27], v[200:203], v[146:149], 0
	v_mfma_f32_16x16x32_bf16 v[82:85], v[192:195], v[154:157], 0
	v_mfma_f32_16x16x32_bf16 v[16:19], v[200:203], v[154:157], 0
	v_mfma_f32_16x16x32_bf16 v[74:77], v[192:195], v[162:165], 0
	v_mfma_f32_16x16x32_bf16 v[8:11], v[200:203], v[162:165], 0
	v_mfma_f32_16x16x32_bf16 v[66:69], v[192:195], v[170:173], 0
	v_mfma_f32_16x16x32_bf16 v[0:3], v[200:203], v[170:173], 0
	v_mfma_f32_16x16x32_bf16 v[90:93], v[196:199], v[150:153], v[90:93]
	v_mfma_f32_16x16x32_bf16 v[24:27], v[204:207], v[150:153], v[24:27]
	v_mfma_f32_16x16x32_bf16 v[82:85], v[196:199], v[158:161], v[82:85]
	v_mfma_f32_16x16x32_bf16 v[16:19], v[204:207], v[158:161], v[16:19]
	v_mfma_f32_16x16x32_bf16 v[74:77], v[196:199], v[166:169], v[74:77]
	v_mfma_f32_16x16x32_bf16 v[8:11], v[204:207], v[166:169], v[8:11]
	v_mfma_f32_16x16x32_bf16 v[66:69], v[196:199], v[188:191], v[66:69]
	v_mfma_f32_16x16x32_bf16 v[0:3], v[204:207], v[188:191], v[0:3]
	s_setprio 1
	s_add_i32 s22, 0, 0x18000
	v_add_u32_e32 v48, s22, v250
	s_barrier
	ds_read_b128 v[130:133], v48
	ds_read_b128 v[134:137], v48 offset:1024
	ds_read_b128 v[138:141], v48 offset:2048
	ds_read_b128 v[142:145], v48 offset:3072
	s_add_u32 s16, s16, 0x40000
	s_addc_u32 s17, s17, 0
	s_mov_b32 m0, s11
	v_lshl_add_u64 v[192:193], s[16:17], 0, v[176:177]
	ds_read_b128 v[146:149], v242 offset:32768
	ds_read_b128 v[150:153], v242 offset:33792
	ds_read_b128 v[154:157], v242 offset:34816
	ds_read_b128 v[158:161], v242 offset:35840
	ds_read_b128 v[162:165], v242 offset:36864
	ds_read_b128 v[166:169], v242 offset:37888
	ds_read_b128 v[170:173], v242 offset:38912
	ds_read_b128 v[188:191], v242 offset:39936
	global_load_lds_dwordx4 v[192:193], off
	v_lshl_add_u64 v[192:193], s[16:17], 0, v[180:181]
	s_mov_b32 m0, s24
	s_nop 0
	global_load_lds_dwordx4 v[192:193], off
	s_waitcnt lgkmcnt(8)
	s_barrier
	s_setprio 0
	s_waitcnt lgkmcnt(7)
	v_mfma_f32_16x16x32_bf16 v[126:129], v[130:133], v[146:149], v[126:129]
	v_mfma_f32_16x16x32_bf16 v[62:65], v[138:141], v[146:149], v[62:65]
	s_waitcnt lgkmcnt(5)
	v_mfma_f32_16x16x32_bf16 v[118:121], v[130:133], v[154:157], v[118:121]
	v_mfma_f32_16x16x32_bf16 v[54:57], v[138:141], v[154:157], v[54:57]
	s_waitcnt lgkmcnt(3)
	v_mfma_f32_16x16x32_bf16 v[110:113], v[130:133], v[162:165], v[110:113]
	v_mfma_f32_16x16x32_bf16 v[44:47], v[138:141], v[162:165], v[44:47]
	s_waitcnt lgkmcnt(1)
	v_mfma_f32_16x16x32_bf16 v[102:105], v[130:133], v[170:173], v[102:105]
	v_mfma_f32_16x16x32_bf16 v[36:39], v[138:141], v[170:173], v[36:39]
	v_mfma_f32_16x16x32_bf16 v[126:129], v[134:137], v[150:153], v[126:129]
	v_mfma_f32_16x16x32_bf16 v[62:65], v[142:145], v[150:153], v[62:65]
	v_mfma_f32_16x16x32_bf16 v[118:121], v[134:137], v[158:161], v[118:121]
	v_mfma_f32_16x16x32_bf16 v[54:57], v[142:145], v[158:161], v[54:57]
	v_mfma_f32_16x16x32_bf16 v[110:113], v[134:137], v[166:169], v[110:113]
	v_mfma_f32_16x16x32_bf16 v[44:47], v[142:145], v[166:169], v[44:47]
	s_waitcnt lgkmcnt(0)
	v_mfma_f32_16x16x32_bf16 v[102:105], v[134:137], v[188:191], v[102:105]
	v_mfma_f32_16x16x32_bf16 v[36:39], v[142:145], v[188:191], v[36:39]
	s_setprio 1
	s_barrier
	s_add_i32 s16, 0, 0x1c000
	s_add_i32 s17, s22, s36
	v_add_u32_e32 v48, s16, v250
	v_lshl_add_u64 v[208:209], v[208:209], 0, s[0:1]
	s_mov_b32 m0, s17
	ds_read_b128 v[192:195], v48
	ds_read_b128 v[196:199], v48 offset:1024
	ds_read_b128 v[200:203], v48 offset:2048
	ds_read_b128 v[204:207], v48 offset:3072
	global_load_lds_dwordx4 v[208:209], off
	v_lshl_add_u64 v[208:209], v[210:211], 0, s[0:1]
	s_add_i32 m0, s17, 0x2000
	s_nop 0
	global_load_lds_dwordx4 v[208:209], off
	s_barrier
	s_setprio 0
	s_waitcnt lgkmcnt(3)
	v_mfma_f32_16x16x32_bf16 v[122:125], v[192:195], v[146:149], v[122:125]
	s_waitcnt lgkmcnt(1)
	v_mfma_f32_16x16x32_bf16 v[58:61], v[200:203], v[146:149], v[58:61]
	v_mfma_f32_16x16x32_bf16 v[114:117], v[192:195], v[154:157], v[114:117]
	v_mfma_f32_16x16x32_bf16 v[50:53], v[200:203], v[154:157], v[50:53]
	v_mfma_f32_16x16x32_bf16 v[106:109], v[192:195], v[162:165], v[106:109]
	v_mfma_f32_16x16x32_bf16 v[40:43], v[200:203], v[162:165], v[40:43]
	v_mfma_f32_16x16x32_bf16 v[98:101], v[192:195], v[170:173], v[98:101]
	v_mfma_f32_16x16x32_bf16 v[32:35], v[200:203], v[170:173], v[32:35]
	v_mfma_f32_16x16x32_bf16 v[122:125], v[196:199], v[150:153], v[122:125]
	s_waitcnt lgkmcnt(0)
	v_mfma_f32_16x16x32_bf16 v[58:61], v[204:207], v[150:153], v[58:61]
	v_mfma_f32_16x16x32_bf16 v[114:117], v[196:199], v[158:161], v[114:117]
	v_mfma_f32_16x16x32_bf16 v[50:53], v[204:207], v[158:161], v[50:53]
	v_mfma_f32_16x16x32_bf16 v[106:109], v[196:199], v[166:169], v[106:109]
	v_mfma_f32_16x16x32_bf16 v[40:43], v[204:207], v[166:169], v[40:43]
	v_mfma_f32_16x16x32_bf16 v[98:101], v[196:199], v[188:191], v[98:101]
	v_mfma_f32_16x16x32_bf16 v[32:35], v[204:207], v[188:191], v[32:35]
	s_setprio 1
	s_mov_b32 m0, s25
	v_lshl_add_u64 v[208:209], v[212:213], 0, s[0:1]
	s_barrier
; #define PG8_STAGE(bufoff, gbase, voff) do { _Pragma("unroll") for (int _i = 0; _i < 2; ++_i) \
;         __builtin_amdgcn_global_load_lds((const unsigned*)((const char*)(gbase) + (voff)[_i]), (PG8_LAS unsigned*)(lds + (bufoff) + ldsw + _i * 8192), 16, 0, 0); } while (0)
; #define PG8_LDA(dst, b, h) do { _Pragma("unroll") for (int m = 0; m < 4; ++m) _Pragma("unroll") for (int k = 0; k < 2; ++k) dst[m][k] = *(const PG8_LAS bf16x8*)(lds + PG8_SA(b, h) + aoff + m * 2048 + k * 1024); } while (0)
; #define PG8_WAIT_V(n) asm volatile("s_waitcnt vmcnt(" #n ")" ::: "memory")
; template <class Epi, class Sched>
; __device__ __forceinline__ void gemm_phase(PG8_LAS unsigned char* lds, const Gemm g, const Sched& S, const Epi& E) {
;     ...
;         for (int t = 0; t < nt; t += 2) {
;             const bool last = (t == nt - 2);
;             const char* a1 = cA + (size_t)(t + 1) * kstep;
;             const char* a2 = last ? nA : cA + (size_t)(t + 2) * kstep; const char* b2 = last ? nB : cB + (size_t)(t + 2) * kstep;
;             const char* a3 = a2 + kstep; const char* b3 = b2 + kstep;
;             if (last && has_next) S.a_ready(nxt);
;             PG8_LDB(B0, 0, 0); PG8_SCHED; PG8_LDA(At, 0, 0); PG8_STAGE(PG8_SA(1, 1), a1 + hstep, voffA);
;             PG8_WAIT_L(8); PG8_BAR; PG8_WAIT_L(0); PG8_MMA(0, 0, At, B0); PG8_BAR; PG8_SCHED;
;             PG8_LDB(B1, 0, 1); PG8_STAGE(PG8_SB(0, 0), b2, voffB);
;             PG8_BAR; PG8_WAIT_L(0); PG8_MMA(0, 1, At, B1); PG8_BAR;
;             PG8_LDA(At, 0, 1); PG8_STAGE(PG8_SA(0, 0), a2, voffA);
;             PG8_BAR; PG8_WAIT_L(0); PG8_MMA(1, 0, At, B0); PG8_BAR; PG8_SCHED;
;             PG8_STAGE(PG8_SB(0, 1), b2 + hstep, voffB);
;             PG8_WAIT_V(6); PG8_BAR; PG8_MMA(1, 1, At, B1); PG8_BAR;
;             PG8_LDB(B0, 1, 0); PG8_SCHED; PG8_LDA(At, 1, 0); PG8_STAGE(PG8_SA(0, 1), a2 + hstep, voffA);
;             PG8_WAIT_L(8); PG8_BAR; PG8_WAIT_L(0); PG8_MMA(0, 0, At, B0); PG8_BAR; PG8_SCHED;
;             PG8_LDB(B1, 1, 1); PG8_STAGE(PG8_SB(1, 0), b3, voffB);
;             PG8_BAR; PG8_WAIT_L(0); PG8_MMA(0, 1, At, B1); PG8_BAR;
;             PG8_LDA(At, 1, 1); PG8_STAGE(PG8_SA(1, 0), a3, voffA);
;             PG8_BAR; PG8_WAIT_L(0); PG8_MMA(1, 0, At, B0); PG8_BAR; PG8_SCHED;
;             PG8_STAGE(PG8_SB(1, 1), b3 + hstep, voffB);
;             PG8_WAIT_V(6); PG8_BAR; PG8_MMA(1, 1, At, B1); PG8_BAR;
	ds_read_b128 v[146:149], v242 offset:49152
	ds_read_b128 v[150:153], v242 offset:50176
	ds_read_b128 v[154:157], v242 offset:51200
	ds_read_b128 v[158:161], v242 offset:52224
	ds_read_b128 v[162:165], v242 offset:53248
	ds_read_b128 v[166:169], v242 offset:54272
	ds_read_b128 v[170:173], v242 offset:55296
	ds_read_b128 v[188:191], v242 offset:56320
	global_load_lds_dwordx4 v[208:209], off
	v_lshl_add_u64 v[208:209], v[214:215], 0, s[0:1]
	s_mov_b32 m0, s18
	s_nop 0
	global_load_lds_dwordx4 v[208:209], off
	s_barrier
	s_setprio 0
	s_waitcnt lgkmcnt(7)
	v_mfma_f32_16x16x32_bf16 v[94:97], v[130:133], v[146:149], v[94:97]
	v_mfma_f32_16x16x32_bf16 v[28:31], v[138:141], v[146:149], v[28:31]
	s_waitcnt lgkmcnt(5)
	v_mfma_f32_16x16x32_bf16 v[86:89], v[130:133], v[154:157], v[86:89]
	v_mfma_f32_16x16x32_bf16 v[20:23], v[138:141], v[154:157], v[20:23]
	s_waitcnt lgkmcnt(3)
	v_mfma_f32_16x16x32_bf16 v[78:81], v[130:133], v[162:165], v[78:81]
	v_mfma_f32_16x16x32_bf16 v[12:15], v[138:141], v[162:165], v[12:15]
	s_waitcnt lgkmcnt(1)
	v_mfma_f32_16x16x32_bf16 v[70:73], v[130:133], v[170:173], v[70:73]
	v_mfma_f32_16x16x32_bf16 v[4:7], v[138:141], v[170:173], v[4:7]
	v_mfma_f32_16x16x32_bf16 v[94:97], v[134:137], v[150:153], v[94:97]
	v_mfma_f32_16x16x32_bf16 v[28:31], v[142:145], v[150:153], v[28:31]
	v_mfma_f32_16x16x32_bf16 v[86:89], v[134:137], v[158:161], v[86:89]
	v_mfma_f32_16x16x32_bf16 v[20:23], v[142:145], v[158:161], v[20:23]
	v_mfma_f32_16x16x32_bf16 v[78:81], v[134:137], v[166:169], v[78:81]
	v_mfma_f32_16x16x32_bf16 v[12:15], v[142:145], v[166:169], v[12:15]
	s_waitcnt lgkmcnt(0)
	v_mfma_f32_16x16x32_bf16 v[70:73], v[134:137], v[188:191], v[70:73]
	v_mfma_f32_16x16x32_bf16 v[4:7], v[142:145], v[188:191], v[4:7]
	s_setprio 1
	s_barrier
	s_add_u32 s12, s12, 0x40080
	s_addc_u32 s13, s13, 0
	s_add_i32 s16, s16, s36
	v_lshl_add_u64 v[130:131], s[12:13], 0, v[178:179]
	s_mov_b32 m0, s16
	s_nop 0
	global_load_lds_dwordx4 v[130:131], off
	v_lshl_add_u64 v[130:131], s[12:13], 0, v[182:183]
	s_add_i32 m0, s16, 0x2000
	s_nop 0
	global_load_lds_dwordx4 v[130:131], off
	s_waitcnt vmcnt(6)
	s_barrier
	s_setprio 0
	v_mfma_f32_16x16x32_bf16 v[90:93], v[192:195], v[146:149], v[90:93]
	v_mfma_f32_16x16x32_bf16 v[24:27], v[200:203], v[146:149], v[24:27]
	v_mfma_f32_16x16x32_bf16 v[82:85], v[192:195], v[154:157], v[82:85]
	v_mfma_f32_16x16x32_bf16 v[16:19], v[200:203], v[154:157], v[16:19]
	v_mfma_f32_16x16x32_bf16 v[74:77], v[192:195], v[162:165], v[74:77]
	v_mfma_f32_16x16x32_bf16 v[8:11], v[200:203], v[162:165], v[8:11]
	v_mfma_f32_16x16x32_bf16 v[66:69], v[192:195], v[170:173], v[66:69]
	v_mfma_f32_16x16x32_bf16 v[0:3], v[200:203], v[170:173], v[0:3]
	v_mfma_f32_16x16x32_bf16 v[90:93], v[196:199], v[150:153], v[90:93]
	v_mfma_f32_16x16x32_bf16 v[24:27], v[204:207], v[150:153], v[24:27]
	v_mfma_f32_16x16x32_bf16 v[82:85], v[196:199], v[158:161], v[82:85]
	v_mfma_f32_16x16x32_bf16 v[16:19], v[204:207], v[158:161], v[16:19]
	v_mfma_f32_16x16x32_bf16 v[74:77], v[196:199], v[166:169], v[74:77]
	v_mfma_f32_16x16x32_bf16 v[8:11], v[204:207], v[166:169], v[8:11]
	v_mfma_f32_16x16x32_bf16 v[66:69], v[196:199], v[188:191], v[66:69]
	v_mfma_f32_16x16x32_bf16 v[0:3], v[204:207], v[188:191], v[0:3]
	s_setprio 1
	s_add_i32 s30, s30, 2
	s_add_u32 s6, s6, 0x100
	s_addc_u32 s7, s7, 0
	s_add_u32 s27, s27, 0x100
	s_addc_u32 s29, s29, 0
	s_cmp_gt_u32 s30, 13
	s_barrier
	s_cbranch_scc1 .Lkpeel_exit_388
.LBB0_388:
	s_add_u32 s12, s6, 0xfffc0080
	s_addc_u32 s13, s7, -1
	s_add_i32 s22, 0, 0x10000
	v_add_u32_e32 v48, s22, v250
	ds_read_b128 v[130:133], v48
	ds_read_b128 v[134:137], v48 offset:1024
	ds_read_b128 v[138:141], v48 offset:2048
	ds_read_b128 v[142:145], v48 offset:3072
	s_cmp_eq_u32 s30, 12
	s_cselect_b32 s17, s9, s13
	s_cselect_b32 s16, s8, s12
	s_cselect_b32 s13, s3, s29
	s_cselect_b32 s12, s26, s27
	v_lshl_add_u64 v[192:193], s[6:7], 0, v[184:185]
	s_add_i32 m0, s37, 0xc000
	ds_read_b128 v[146:149], v242
	ds_read_b128 v[150:153], v242 offset:1024
	ds_read_b128 v[154:157], v242 offset:2048
	ds_read_b128 v[158:161], v242 offset:3072
	ds_read_b128 v[162:165], v242 offset:4096
	ds_read_b128 v[166:169], v242 offset:5120
	ds_read_b128 v[170:173], v242 offset:6144
	ds_read_b128 v[188:191], v242 offset:7168
	global_load_lds_dwordx4 v[192:193], off
	v_lshl_add_u64 v[192:193], s[6:7], 0, v[186:187]
	s_add_i32 m0, s37, 0xe000
	s_nop 0
	global_load_lds_dwordx4 v[192:193], off
	s_waitcnt lgkmcnt(8)
	s_barrier
	s_setprio 0
	s_waitcnt lgkmcnt(7)
	v_mfma_f32_16x16x32_bf16 v[126:129], v[130:133], v[146:149], v[126:129]
	v_mfma_f32_16x16x32_bf16 v[62:65], v[138:141], v[146:149], v[62:65]
	s_waitcnt lgkmcnt(5)
	v_mfma_f32_16x16x32_bf16 v[118:121], v[130:133], v[154:157], v[118:121]
	v_mfma_f32_16x16x32_bf16 v[54:57], v[138:141], v[154:157], v[54:57]
	s_waitcnt lgkmcnt(3)
	v_mfma_f32_16x16x32_bf16 v[110:113], v[130:133], v[162:165], v[110:113]
	v_mfma_f32_16x16x32_bf16 v[44:47], v[138:141], v[162:165], v[44:47]
	s_waitcnt lgkmcnt(1)
	v_mfma_f32_16x16x32_bf16 v[102:105], v[130:133], v[170:173], v[102:105]
	v_mfma_f32_16x16x32_bf16 v[36:39], v[138:141], v[170:173], v[36:39]
	v_mfma_f32_16x16x32_bf16 v[126:129], v[134:137], v[150:153], v[126:129]
	v_mfma_f32_16x16x32_bf16 v[62:65], v[142:145], v[150:153], v[62:65]
	v_mfma_f32_16x16x32_bf16 v[118:121], v[134:137], v[158:161], v[118:121]
	v_mfma_f32_16x16x32_bf16 v[54:57], v[142:145], v[158:161], v[54:57]
	v_mfma_f32_16x16x32_bf16 v[110:113], v[134:137], v[166:169], v[110:113]
	v_mfma_f32_16x16x32_bf16 v[44:47], v[142:145], v[166:169], v[44:47]
	s_waitcnt lgkmcnt(0)
	v_mfma_f32_16x16x32_bf16 v[102:105], v[134:137], v[188:191], v[102:105]
	v_mfma_f32_16x16x32_bf16 v[36:39], v[142:145], v[188:191], v[36:39]
	s_setprio 1
	s_barrier
; #define PG8_STAGE(bufoff, gbase, voff) do { _Pragma("unroll") for (int _i = 0; _i < 2; ++_i) \
;         __builtin_amdgcn_global_load_lds((const unsigned*)((const char*)(gbase) + (voff)[_i]), (PG8_LAS unsigned*)(lds + (bufoff) + ldsw + _i * 8192), 16, 0, 0); } while (0)
; #define PG8_LDA(dst, b, h) do { _Pragma("unroll") for (int m = 0; m < 4; ++m) _Pragma("unroll") for (int k = 0; k < 2; ++k) dst[m][k] = *(const PG8_LAS bf16x8*)(lds + PG8_SA(b, h) + aoff + m * 2048 + k * 1024); } while (0)
; #define PG8_LDB(dst, b, h) do { _Pragma("unroll") for (int n = 0; n < 2; ++n) _Pragma("unroll") for (int k = 0; k < 2; ++k) dst[n][k] = *(const PG8_LAS bf16x8*)(lds + PG8_SB(b, h) + boff + n * 2048 + k * 1024); } while (0)
; #define PG8_MMA(ai, bj, At, Bt) do { __builtin_amdgcn_s_setprio(1); _Pragma("unroll") for (int m = 0; m < 4; ++m) _Pragma("unroll") for (int n = 0; n < 2; ++n) _Pragma("unroll") for (int k = 0; k < 2; ++k) \
;         acc[ai][bj][m][n] = __builtin_amdgcn_mfma_f32_16x16x32_bf16(Bt[n][k], At[m][k], acc[ai][bj][m][n], 0, 0, 0); __builtin_amdgcn_s_setprio(0); } while (0)
; #define PG8_WAIT_V(n) asm volatile("s_waitcnt vmcnt(" #n ")" ::: "memory")
; #define PG8_WAIT_L(n) asm volatile("s_waitcnt lgkmcnt(" #n ")" ::: "memory")
; #define PG8_BAR __builtin_amdgcn_s_barrier()
; #define PG8_SCHED __builtin_amdgcn_sched_barrier(0)
; template <class Epi, class Sched>
; __device__ __forceinline__ void gemm_phase(PG8_LAS unsigned char* lds, const Gemm g, const Sched& S, const Epi& E) {
;     ...
;             PG8_LDB(B1, 0, 1); PG8_STAGE(PG8_SB(0, 0), b2, voffB);
;             PG8_BAR; PG8_WAIT_L(0); PG8_MMA(0, 1, At, B1); PG8_BAR;
;             PG8_LDA(At, 0, 1); PG8_STAGE(PG8_SA(0, 0), a2, voffA);
;             PG8_BAR; PG8_WAIT_L(0); PG8_MMA(1, 0, At, B0); PG8_BAR; PG8_SCHED;
;             PG8_STAGE(PG8_SB(0, 1), b2 + hstep, voffB);
;             PG8_WAIT_V(6); PG8_BAR; PG8_MMA(1, 1, At, B1); PG8_BAR;
;             PG8_LDB(B0, 1, 0); PG8_SCHED; PG8_LDA(At, 1, 0); PG8_STAGE(PG8_SA(0, 1), a2 + hstep, voffA);
;             PG8_WAIT_L(8); PG8_BAR; PG8_WAIT_L(0); PG8_MMA(0, 0, At, B0); PG8_BAR; PG8_SCHED;
;             PG8_LDB(B1, 1, 1); PG8_STAGE(PG8_SB(1, 0), b3, voffB);
;             PG8_BAR; PG8_WAIT_L(0); PG8_MMA(0, 1, At, B1); PG8_BAR;
;             PG8_LDA(At, 1, 1); PG8_STAGE(PG8_SA(1, 0), a3, voffA);
	s_add_i32 s31, 0, 0x14000
	s_add_i32 s22, s22, s36
	v_add_u32_e32 v48, s31, v250
	v_lshl_add_u64 v[208:209], s[12:13], 0, v[178:179]
	s_mov_b32 m0, s22
	ds_read_b128 v[192:195], v48
	ds_read_b128 v[196:199], v48 offset:1024
	ds_read_b128 v[200:203], v48 offset:2048
	ds_read_b128 v[204:207], v48 offset:3072
	global_load_lds_dwordx4 v[208:209], off
	v_lshl_add_u64 v[210:211], s[12:13], 0, v[182:183]
	s_add_i32 m0, s22, 0x2000
	s_nop 0
	global_load_lds_dwordx4 v[210:211], off
	s_barrier
	s_setprio 0
	s_waitcnt lgkmcnt(3)
	v_mfma_f32_16x16x32_bf16 v[122:125], v[192:195], v[146:149], v[122:125]
	s_waitcnt lgkmcnt(1)
	v_mfma_f32_16x16x32_bf16 v[58:61], v[200:203], v[146:149], v[58:61]
	v_mfma_f32_16x16x32_bf16 v[114:117], v[192:195], v[154:157], v[114:117]
	v_mfma_f32_16x16x32_bf16 v[50:53], v[200:203], v[154:157], v[50:53]
	v_mfma_f32_16x16x32_bf16 v[106:109], v[192:195], v[162:165], v[106:109]
	v_mfma_f32_16x16x32_bf16 v[40:43], v[200:203], v[162:165], v[40:43]
	v_mfma_f32_16x16x32_bf16 v[98:101], v[192:195], v[170:173], v[98:101]
	v_mfma_f32_16x16x32_bf16 v[32:35], v[200:203], v[170:173], v[32:35]
	v_mfma_f32_16x16x32_bf16 v[122:125], v[196:199], v[150:153], v[122:125]
	s_waitcnt lgkmcnt(0)
	v_mfma_f32_16x16x32_bf16 v[58:61], v[204:207], v[150:153], v[58:61]
	v_mfma_f32_16x16x32_bf16 v[114:117], v[196:199], v[158:161], v[114:117]
	v_mfma_f32_16x16x32_bf16 v[50:53], v[204:207], v[158:161], v[50:53]
	v_mfma_f32_16x16x32_bf16 v[106:109], v[196:199], v[166:169], v[106:109]
	v_mfma_f32_16x16x32_bf16 v[40:43], v[204:207], v[166:169], v[40:43]
	v_mfma_f32_16x16x32_bf16 v[98:101], v[196:199], v[188:191], v[98:101]
	v_mfma_f32_16x16x32_bf16 v[32:35], v[204:207], v[188:191], v[32:35]
	s_setprio 1
	s_mov_b32 m0, s37
	v_lshl_add_u64 v[212:213], s[16:17], 0, v[176:177]
	s_barrier
	ds_read_b128 v[146:149], v242 offset:16384
	ds_read_b128 v[150:153], v242 offset:17408
	ds_read_b128 v[154:157], v242 offset:18432
	ds_read_b128 v[158:161], v242 offset:19456
	ds_read_b128 v[162:165], v242 offset:20480
	ds_read_b128 v[166:169], v242 offset:21504
	ds_read_b128 v[170:173], v242 offset:22528
	ds_read_b128 v[188:191], v242 offset:23552
	global_load_lds_dwordx4 v[212:213], off
	v_lshl_add_u64 v[214:215], s[16:17], 0, v[180:181]
	s_mov_b32 m0, s10
	s_nop 0
	global_load_lds_dwordx4 v[214:215], off
	s_barrier
	s_setprio 0
	s_waitcnt lgkmcnt(7)
	v_mfma_f32_16x16x32_bf16 v[94:97], v[130:133], v[146:149], v[94:97]
	v_mfma_f32_16x16x32_bf16 v[28:31], v[138:141], v[146:149], v[28:31]
	s_waitcnt lgkmcnt(5)
	v_mfma_f32_16x16x32_bf16 v[86:89], v[130:133], v[154:157], v[86:89]
	v_mfma_f32_16x16x32_bf16 v[20:23], v[138:141], v[154:157], v[20:23]
	s_waitcnt lgkmcnt(3)
	v_mfma_f32_16x16x32_bf16 v[78:81], v[130:133], v[162:165], v[78:81]
	v_mfma_f32_16x16x32_bf16 v[12:15], v[138:141], v[162:165], v[12:15]
	s_waitcnt lgkmcnt(1)
	v_mfma_f32_16x16x32_bf16 v[70:73], v[130:133], v[170:173], v[70:73]
	v_mfma_f32_16x16x32_bf16 v[4:7], v[138:141], v[170:173], v[4:7]
	v_mfma_f32_16x16x32_bf16 v[94:97], v[134:137], v[150:153], v[94:97]
	v_mfma_f32_16x16x32_bf16 v[28:31], v[142:145], v[150:153], v[28:31]
	v_mfma_f32_16x16x32_bf16 v[86:89], v[134:137], v[158:161], v[86:89]
	v_mfma_f32_16x16x32_bf16 v[20:23], v[142:145], v[158:161], v[20:23]
	v_mfma_f32_16x16x32_bf16 v[78:81], v[134:137], v[166:169], v[78:81]
	v_mfma_f32_16x16x32_bf16 v[12:15], v[142:145], v[166:169], v[12:15]
	s_waitcnt lgkmcnt(0)
	v_mfma_f32_16x16x32_bf16 v[70:73], v[134:137], v[188:191], v[70:73]
	v_mfma_f32_16x16x32_bf16 v[4:7], v[142:145], v[188:191], v[4:7]
	s_setprio 1
	s_barrier
	s_add_u32 s22, s12, 0x40000
	s_addc_u32 s23, s13, 0
	s_add_i32 s31, s31, s36
	v_lshl_add_u64 v[130:131], s[22:23], 0, v[178:179]
	s_mov_b32 m0, s31
	s_nop 0
	global_load_lds_dwordx4 v[130:131], off
	v_lshl_add_u64 v[130:131], s[22:23], 0, v[182:183]
	s_add_i32 m0, s31, 0x2000
	s_nop 0
	global_load_lds_dwordx4 v[130:131], off
	s_waitcnt vmcnt(6)
	s_barrier
	s_setprio 0
	v_mfma_f32_16x16x32_bf16 v[90:93], v[192:195], v[146:149], v[90:93]
	v_mfma_f32_16x16x32_bf16 v[24:27], v[200:203], v[146:149], v[24:27]
	v_mfma_f32_16x16x32_bf16 v[82:85], v[192:195], v[154:157], v[82:85]
	v_mfma_f32_16x16x32_bf16 v[16:19], v[200:203], v[154:157], v[16:19]
	v_mfma_f32_16x16x32_bf16 v[74:77], v[192:195], v[162:165], v[74:77]
	v_mfma_f32_16x16x32_bf16 v[8:11], v[200:203], v[162:165], v[8:11]
	v_mfma_f32_16x16x32_bf16 v[66:69], v[192:195], v[170:173], v[66:69]
	v_mfma_f32_16x16x32_bf16 v[0:3], v[200:203], v[170:173], v[0:3]
	v_mfma_f32_16x16x32_bf16 v[90:93], v[196:199], v[150:153], v[90:93]
	v_mfma_f32_16x16x32_bf16 v[24:27], v[204:207], v[150:153], v[24:27]
	v_mfma_f32_16x16x32_bf16 v[82:85], v[196:199], v[158:161], v[82:85]
	v_mfma_f32_16x16x32_bf16 v[16:19], v[204:207], v[158:161], v[16:19]
	v_mfma_f32_16x16x32_bf16 v[74:77], v[196:199], v[166:169], v[74:77]
	v_mfma_f32_16x16x32_bf16 v[8:11], v[204:207], v[166:169], v[8:11]
	v_mfma_f32_16x16x32_bf16 v[66:69], v[196:199], v[188:191], v[66:69]
	v_mfma_f32_16x16x32_bf16 v[0:3], v[204:207], v[188:191], v[0:3]
	s_setprio 1
	s_add_i32 s22, 0, 0x18000
	v_add_u32_e32 v48, s22, v250
	s_barrier
	ds_read_b128 v[130:133], v48
	ds_read_b128 v[134:137], v48 offset:1024
	ds_read_b128 v[138:141], v48 offset:2048
	ds_read_b128 v[142:145], v48 offset:3072
	s_add_u32 s16, s16, 0x40000
	s_addc_u32 s17, s17, 0
	s_mov_b32 m0, s11
	v_lshl_add_u64 v[192:193], s[16:17], 0, v[176:177]
	ds_read_b128 v[146:149], v242 offset:32768
	ds_read_b128 v[150:153], v242 offset:33792
	ds_read_b128 v[154:157], v242 offset:34816
	ds_read_b128 v[158:161], v242 offset:35840
	ds_read_b128 v[162:165], v242 offset:36864
	ds_read_b128 v[166:169], v242 offset:37888
	ds_read_b128 v[170:173], v242 offset:38912
	ds_read_b128 v[188:191], v242 offset:39936
	global_load_lds_dwordx4 v[192:193], off
	v_lshl_add_u64 v[192:193], s[16:17], 0, v[180:181]
	s_mov_b32 m0, s24
	s_nop 0
	global_load_lds_dwordx4 v[192:193], off
	s_waitcnt lgkmcnt(8)
	s_barrier
; #define PG8_STAGE(bufoff, gbase, voff) do { _Pragma("unroll") for (int _i = 0; _i < 2; ++_i) \
;         __builtin_amdgcn_global_load_lds((const unsigned*)((const char*)(gbase) + (voff)[_i]), (PG8_LAS unsigned*)(lds + (bufoff) + ldsw + _i * 8192), 16, 0, 0); } while (0)
; #define PG8_LDA(dst, b, h) do { _Pragma("unroll") for (int m = 0; m < 4; ++m) _Pragma("unroll") for (int k = 0; k < 2; ++k) dst[m][k] = *(const PG8_LAS bf16x8*)(lds + PG8_SA(b, h) + aoff + m * 2048 + k * 1024); } while (0)
; #define PG8_LDB(dst, b, h) do { _Pragma("unroll") for (int n = 0; n < 2; ++n) _Pragma("unroll") for (int k = 0; k < 2; ++k) dst[n][k] = *(const PG8_LAS bf16x8*)(lds + PG8_SB(b, h) + boff + n * 2048 + k * 1024); } while (0)
; #define PG8_MMA(ai, bj, At, Bt) do { __builtin_amdgcn_s_setprio(1); _Pragma("unroll") for (int m = 0; m < 4; ++m) _Pragma("unroll") for (int n = 0; n < 2; ++n) _Pragma("unroll") for (int k = 0; k < 2; ++k) \
;         acc[ai][bj][m][n] = __builtin_amdgcn_mfma_f32_16x16x32_bf16(Bt[n][k], At[m][k], acc[ai][bj][m][n], 0, 0, 0); __builtin_amdgcn_s_setprio(0); } while (0)
; #define PG8_WAIT_V(n) asm volatile("s_waitcnt vmcnt(" #n ")" ::: "memory")
; #define PG8_WAIT_L(n) asm volatile("s_waitcnt lgkmcnt(" #n ")" ::: "memory")
; #define PG8_BAR __builtin_amdgcn_s_barrier()
; #define PG8_SCHED __builtin_amdgcn_sched_barrier(0)
; template <class Epi, class Sched>
; __device__ __forceinline__ void gemm_phase(PG8_LAS unsigned char* lds, const Gemm g, const Sched& S, const Epi& E) {
;     ...
;             PG8_WAIT_L(8); PG8_BAR; PG8_WAIT_L(0); PG8_MMA(0, 0, At, B0); PG8_BAR; PG8_SCHED;
;             PG8_LDB(B1, 1, 1); PG8_STAGE(PG8_SB(1, 0), b3, voffB);
;             PG8_BAR; PG8_WAIT_L(0); PG8_MMA(0, 1, At, B1); PG8_BAR;
;             PG8_LDA(At, 1, 1); PG8_STAGE(PG8_SA(1, 0), a3, voffA);
;             PG8_BAR; PG8_WAIT_L(0); PG8_MMA(1, 0, At, B0); PG8_BAR; PG8_SCHED;
;             PG8_STAGE(PG8_SB(1, 1), b3 + hstep, voffB);
;             PG8_WAIT_V(6); PG8_BAR; PG8_MMA(1, 1, At, B1); PG8_BAR;
	s_setprio 0
	s_waitcnt lgkmcnt(7)
	v_mfma_f32_16x16x32_bf16 v[126:129], v[130:133], v[146:149], v[126:129]
	v_mfma_f32_16x16x32_bf16 v[62:65], v[138:141], v[146:149], v[62:65]
	s_waitcnt lgkmcnt(5)
	v_mfma_f32_16x16x32_bf16 v[118:121], v[130:133], v[154:157], v[118:121]
	v_mfma_f32_16x16x32_bf16 v[54:57], v[138:141], v[154:157], v[54:57]
	s_waitcnt lgkmcnt(3)
	v_mfma_f32_16x16x32_bf16 v[110:113], v[130:133], v[162:165], v[110:113]
	v_mfma_f32_16x16x32_bf16 v[44:47], v[138:141], v[162:165], v[44:47]
	s_waitcnt lgkmcnt(1)
	v_mfma_f32_16x16x32_bf16 v[102:105], v[130:133], v[170:173], v[102:105]
	v_mfma_f32_16x16x32_bf16 v[36:39], v[138:141], v[170:173], v[36:39]
	v_mfma_f32_16x16x32_bf16 v[126:129], v[134:137], v[150:153], v[126:129]
	v_mfma_f32_16x16x32_bf16 v[62:65], v[142:145], v[150:153], v[62:65]
	v_mfma_f32_16x16x32_bf16 v[118:121], v[134:137], v[158:161], v[118:121]
	v_mfma_f32_16x16x32_bf16 v[54:57], v[142:145], v[158:161], v[54:57]
	v_mfma_f32_16x16x32_bf16 v[110:113], v[134:137], v[166:169], v[110:113]
	v_mfma_f32_16x16x32_bf16 v[44:47], v[142:145], v[166:169], v[44:47]
	s_waitcnt lgkmcnt(0)
	v_mfma_f32_16x16x32_bf16 v[102:105], v[134:137], v[188:191], v[102:105]
	v_mfma_f32_16x16x32_bf16 v[36:39], v[142:145], v[188:191], v[36:39]
	s_setprio 1
	s_barrier
	s_add_i32 s16, 0, 0x1c000
	s_add_i32 s17, s22, s36
	v_add_u32_e32 v48, s16, v250
	v_lshl_add_u64 v[208:209], v[208:209], 0, s[0:1]
	s_mov_b32 m0, s17
	ds_read_b128 v[192:195], v48
	ds_read_b128 v[196:199], v48 offset:1024
	ds_read_b128 v[200:203], v48 offset:2048
	ds_read_b128 v[204:207], v48 offset:3072
	global_load_lds_dwordx4 v[208:209], off
	v_lshl_add_u64 v[208:209], v[210:211], 0, s[0:1]
	s_add_i32 m0, s17, 0x2000
	s_nop 0
	global_load_lds_dwordx4 v[208:209], off
	s_barrier
	s_setprio 0
	s_waitcnt lgkmcnt(3)
	v_mfma_f32_16x16x32_bf16 v[122:125], v[192:195], v[146:149], v[122:125]
	s_waitcnt lgkmcnt(1)
	v_mfma_f32_16x16x32_bf16 v[58:61], v[200:203], v[146:149], v[58:61]
	v_mfma_f32_16x16x32_bf16 v[114:117], v[192:195], v[154:157], v[114:117]
	v_mfma_f32_16x16x32_bf16 v[50:53], v[200:203], v[154:157], v[50:53]
	v_mfma_f32_16x16x32_bf16 v[106:109], v[192:195], v[162:165], v[106:109]
	v_mfma_f32_16x16x32_bf16 v[40:43], v[200:203], v[162:165], v[40:43]
	v_mfma_f32_16x16x32_bf16 v[98:101], v[192:195], v[170:173], v[98:101]
	v_mfma_f32_16x16x32_bf16 v[32:35], v[200:203], v[170:173], v[32:35]
	v_mfma_f32_16x16x32_bf16 v[122:125], v[196:199], v[150:153], v[122:125]
	s_waitcnt lgkmcnt(0)
	v_mfma_f32_16x16x32_bf16 v[58:61], v[204:207], v[150:153], v[58:61]
	v_mfma_f32_16x16x32_bf16 v[114:117], v[196:199], v[158:161], v[114:117]
	v_mfma_f32_16x16x32_bf16 v[50:53], v[204:207], v[158:161], v[50:53]
	v_mfma_f32_16x16x32_bf16 v[106:109], v[196:199], v[166:169], v[106:109]
	v_mfma_f32_16x16x32_bf16 v[40:43], v[204:207], v[166:169], v[40:43]
	v_mfma_f32_16x16x32_bf16 v[98:101], v[196:199], v[188:191], v[98:101]
	v_mfma_f32_16x16x32_bf16 v[32:35], v[204:207], v[188:191], v[32:35]
	s_setprio 1
	s_mov_b32 m0, s25
	v_lshl_add_u64 v[208:209], v[212:213], 0, s[0:1]
	s_barrier
	ds_read_b128 v[146:149], v242 offset:49152
	ds_read_b128 v[150:153], v242 offset:50176
	ds_read_b128 v[154:157], v242 offset:51200
	ds_read_b128 v[158:161], v242 offset:52224
	ds_read_b128 v[162:165], v242 offset:53248
	ds_read_b128 v[166:169], v242 offset:54272
	ds_read_b128 v[170:173], v242 offset:55296
	ds_read_b128 v[188:191], v242 offset:56320
	global_load_lds_dwordx4 v[208:209], off
	v_lshl_add_u64 v[208:209], v[214:215], 0, s[0:1]
	s_mov_b32 m0, s18
	s_nop 0
	global_load_lds_dwordx4 v[208:209], off
	s_barrier
	s_setprio 0
	s_waitcnt lgkmcnt(7)
	v_mfma_f32_16x16x32_bf16 v[94:97], v[130:133], v[146:149], v[94:97]
	v_mfma_f32_16x16x32_bf16 v[28:31], v[138:141], v[146:149], v[28:31]
	s_waitcnt lgkmcnt(5)
	v_mfma_f32_16x16x32_bf16 v[86:89], v[130:133], v[154:157], v[86:89]
	v_mfma_f32_16x16x32_bf16 v[20:23], v[138:141], v[154:157], v[20:23]
	s_waitcnt lgkmcnt(3)
	v_mfma_f32_16x16x32_bf16 v[78:81], v[130:133], v[162:165], v[78:81]
	v_mfma_f32_16x16x32_bf16 v[12:15], v[138:141], v[162:165], v[12:15]
	s_waitcnt lgkmcnt(1)
	v_mfma_f32_16x16x32_bf16 v[70:73], v[130:133], v[170:173], v[70:73]
	v_mfma_f32_16x16x32_bf16 v[4:7], v[138:141], v[170:173], v[4:7]
	v_mfma_f32_16x16x32_bf16 v[94:97], v[134:137], v[150:153], v[94:97]
	v_mfma_f32_16x16x32_bf16 v[28:31], v[142:145], v[150:153], v[28:31]
	v_mfma_f32_16x16x32_bf16 v[86:89], v[134:137], v[158:161], v[86:89]
	v_mfma_f32_16x16x32_bf16 v[20:23], v[142:145], v[158:161], v[20:23]
	v_mfma_f32_16x16x32_bf16 v[78:81], v[134:137], v[166:169], v[78:81]
	v_mfma_f32_16x16x32_bf16 v[12:15], v[142:145], v[166:169], v[12:15]
	s_waitcnt lgkmcnt(0)
	v_mfma_f32_16x16x32_bf16 v[70:73], v[134:137], v[188:191], v[70:73]
	v_mfma_f32_16x16x32_bf16 v[4:7], v[142:145], v[188:191], v[4:7]
	s_setprio 1
	s_barrier
	s_add_u32 s12, s12, 0x40080
	s_addc_u32 s13, s13, 0
	s_add_i32 s16, s16, s36
	v_lshl_add_u64 v[130:131], s[12:13], 0, v[178:179]
	s_mov_b32 m0, s16
	s_nop 0
	global_load_lds_dwordx4 v[130:131], off
	v_lshl_add_u64 v[130:131], s[12:13], 0, v[182:183]
	s_add_i32 m0, s16, 0x2000
	s_nop 0
	global_load_lds_dwordx4 v[130:131], off
	s_waitcnt vmcnt(6)
	s_barrier
	s_setprio 0
	v_mfma_f32_16x16x32_bf16 v[90:93], v[192:195], v[146:149], v[90:93]
	v_mfma_f32_16x16x32_bf16 v[24:27], v[200:203], v[146:149], v[24:27]
	v_mfma_f32_16x16x32_bf16 v[82:85], v[192:195], v[154:157], v[82:85]
	v_mfma_f32_16x16x32_bf16 v[16:19], v[200:203], v[154:157], v[16:19]
	v_mfma_f32_16x16x32_bf16 v[74:77], v[192:195], v[162:165], v[74:77]
	v_mfma_f32_16x16x32_bf16 v[8:11], v[200:203], v[162:165], v[8:11]
	v_mfma_f32_16x16x32_bf16 v[66:69], v[192:195], v[170:173], v[66:69]
	v_mfma_f32_16x16x32_bf16 v[0:3], v[200:203], v[170:173], v[0:3]
	v_mfma_f32_16x16x32_bf16 v[90:93], v[196:199], v[150:153], v[90:93]
	v_mfma_f32_16x16x32_bf16 v[24:27], v[204:207], v[150:153], v[24:27]
	v_mfma_f32_16x16x32_bf16 v[82:85], v[196:199], v[158:161], v[82:85]
	v_mfma_f32_16x16x32_bf16 v[16:19], v[204:207], v[158:161], v[16:19]
	v_mfma_f32_16x16x32_bf16 v[74:77], v[196:199], v[166:169], v[74:77]
	v_mfma_f32_16x16x32_bf16 v[8:11], v[204:207], v[166:169], v[8:11]
	v_mfma_f32_16x16x32_bf16 v[66:69], v[196:199], v[188:191], v[66:69]
	v_mfma_f32_16x16x32_bf16 v[0:3], v[204:207], v[188:191], v[0:3]
	s_setprio 1
	s_add_i32 s30, s30, 2
	s_add_u32 s6, s6, 0x100
	s_addc_u32 s7, s7, 0
	s_add_u32 s27, s27, 0x100
	s_addc_u32 s29, s29, 0
	s_cmp_gt_u32 s30, 13
	s_barrier
	s_cbranch_scc0 .LBB0_388
; #define LAS __attribute__((address_space(3)))
;     __device__ __forceinline__ void operator()(const f32x4 (&acc)[2][2][4][2], const pg8::Unit& u, int wr, int wc, int fr, int fq) const {
;         const int cl = 32 * wc + 8 * fq, cv = u.pn * 128 + cl;
; #pragma unroll
;         for (int ai = 0; ai < 2; ++ai) { const int s = 2 * ai + wr;
;             if (fr == 0) { LAS float* p = xb + (s * 2 + 0) * 256 + cl; *(LAS f32x4*)p = acc[ai][0][0][0]; *(LAS f32x4*)(p + 4) = acc[ai][0][0][1]; *(LAS f32x4*)(p + 128) = acc[ai][1][0][0]; *(LAS f32x4*)(p + 132) = acc[ai][1][0][1]; }
;             if (fr == 15) { LAS float* p = xb + (s * 2 + 1) * 256 + cl; *(LAS f32x4*)p = acc[ai][0][3][0]; *(LAS f32x4*)(p + 4) = acc[ai][0][3][1]; *(LAS f32x4*)(p + 128) = acc[ai][1][3][0]; *(LAS f32x4*)(p + 132) = acc[ai][1][3][1]; } }
.Lkpeel_exit_388:
	s_setprio 0
	v_cmp_lt_i32_e32 vcc, 14, v175
	s_mov_b64 s[12:13], 0
	s_and_saveexec_b64 s[6:7], vcc
	s_xor_b64 s[6:7], exec, s[6:7]
	s_mov_b64 s[12:13], exec
	s_or_saveexec_b64 s[6:7], s[6:7]
	v_readlane_b32 s3, v254, 59
	v_mov_b64_e32 v[132:133], v[38:39]
	v_mov_b64_e32 v[136:137], v[104:105]
	v_mov_b64_e32 v[140:141], v[100:101]
	v_mov_b64_e32 v[144:145], v[34:35]
	v_mov_b32_e32 v48, s3
	v_mov_b64_e32 v[130:131], v[36:37]
	v_mov_b64_e32 v[134:135], v[102:103]
	v_mov_b64_e32 v[138:139], v[98:99]
	v_mov_b64_e32 v[142:143], v[32:33]
	s_xor_b64 exec, exec, s[6:7]
	s_cbranch_execz .LBB0_393
	v_readlane_b32 s3, v254, 58
	s_andn2_b64 s[12:13], s[12:13], exec
	s_and_b64 s[16:17], s[40:41], exec
	v_mov_b64_e32 v[132:133], v[64:65]
	v_mov_b64_e32 v[136:137], v[128:129]
	v_mov_b64_e32 v[140:141], v[124:125]
	v_mov_b64_e32 v[144:145], v[60:61]
	v_mov_b32_e32 v48, s3
	s_or_b64 s[12:13], s[12:13], s[16:17]
	v_mov_b64_e32 v[130:131], v[62:63]
	v_mov_b64_e32 v[134:135], v[126:127]
	v_mov_b64_e32 v[138:139], v[122:123]
	v_mov_b64_e32 v[142:143], v[58:59]
